# stack D + GEMM epilogue row-sum butterflies via v_permlane16/32_swap instead of ds_bpermute (no LDS round trips)
# speedup vs baseline: 1.0078x; 1.0078x over previous
.LBB0_540:
	v_lshl_add_u32 v150, s28, 8, v152
	v_lshl_or_b32 v148, s8, 8, v154
	v_ashrrev_i32_e32 v151, 31, v150
	v_ashrrev_i32_e32 v149, 31, v148
	v_lshlrev_b64 v[160:161], 10, v[150:151]
	v_lshl_add_u64 v[168:169], v[160:161], 0, v[148:149]
	v_lshl_add_u64 v[170:171], v[168:169], 2, s[52:53]
	global_load_dwordx4 v[160:163], v[170:171], off
	global_load_dwordx4 v[164:167], v[170:171], off offset:16
	v_lshlrev_b64 v[168:169], 1, v[168:169]
	v_lshl_add_u64 v[172:173], s[12:13], 0, v[168:169]
	s_lshl_b32 s28, s8, 2
	v_or_b32_e32 v168, 0x100, v168
	s_ashr_i32 s29, s28, 31
	s_waitcnt vmcnt(0)
	v_pk_add_f32 v[126:127], v[126:127], v[162:163]
	v_pk_add_f32 v[174:175], v[124:125], v[160:161]
	v_pk_add_f32 v[166:167], v[122:123], v[166:167]
	v_pk_add_f32 v[164:165], v[120:121], v[164:165]
	v_cvt_pk_bf16_f32 v120, v174, v175
	v_cvt_pk_bf16_f32 v121, v126, v127
	v_cvt_pk_bf16_f32 v122, v164, v165
	v_cvt_pk_bf16_f32 v123, v166, v167
	global_store_dwordx4 v[172:173], v[120:123], off
	global_load_dwordx4 v[122:125], v[170:171], off offset:512
	s_nop 0
	global_load_dwordx4 v[160:163], v[170:171], off offset:528
	v_and_b32_e32 v121, 64, v159
	v_xor_b32_e32 v120, 16, v159
	v_add_u32_e32 v121, 64, v121
	v_xor_b32_e32 v170, 32, v159
	v_cmp_lt_i32_e32 vcc, v120, v121
	v_pk_mul_f32 v[126:127], v[126:127], v[126:127]
	v_pk_mul_f32 v[166:167], v[166:167], v[166:167]
	v_cndmask_b32_e32 v120, v159, v120, vcc
	v_cmp_lt_i32_e32 vcc, v170, v121
	v_lshlrev_b32_e32 v121, 2, v120
	v_pk_mul_f32 v[164:165], v[164:165], v[164:165]
	v_cndmask_b32_e32 v170, v159, v170, vcc
	v_lshlrev_b32_e32 v120, 2, v170
	v_pk_mul_f32 v[170:171], v[174:175], v[174:175]
	v_add_f32_e32 v166, v166, v167
	v_add_f32_e32 v164, v164, v165
	v_add_f32_e32 v126, v126, v127
	v_add_f32_e32 v127, v170, v171
	v_add_f32_e32 v164, v164, v166
	v_add_f32_e32 v126, v127, v126
	v_add_f32_e32 v164, v126, v164
	s_waitcnt vmcnt(1)
	v_pk_add_f32 v[118:119], v[118:119], v[124:125]
	v_pk_add_f32 v[116:117], v[116:117], v[122:123]
	s_waitcnt vmcnt(0)
	v_pk_add_f32 v[122:123], v[114:115], v[162:163]
	v_pk_add_f32 v[112:113], v[112:113], v[160:161]
	v_pk_mul_f32 v[114:115], v[118:119], v[118:119]
	v_pk_mul_f32 v[124:125], v[116:117], v[116:117]
	v_pk_mul_f32 v[126:127], v[122:123], v[122:123]
	v_pk_mul_f32 v[160:161], v[112:113], v[112:113]
	v_add_f32_e32 v126, v126, v127
	v_add_f32_e32 v127, v160, v161
	v_add_f32_e32 v114, v114, v115
	v_add_f32_e32 v115, v124, v125
	v_add_f32_e32 v124, v127, v126
	v_add_f32_e32 v114, v115, v114
	v_add_f32_e32 v114, v114, v124
	v_add_f32_e32 v124, v164, v114
	v_mov_b32_e32 v125, v124
	s_nop 1
	v_permlane16_swap_b32_e32 v124, v125
	v_cvt_pk_bf16_f32 v114, v116, v117
	v_cvt_pk_bf16_f32 v116, v112, v113
	v_cvt_pk_bf16_f32 v115, v118, v119
	v_cvt_pk_bf16_f32 v117, v122, v123
	s_waitcnt lgkmcnt(0)
	v_add_f32_e32 v112, v124, v125
	v_mov_b32_e32 v113, v112
	s_nop 1
	v_permlane32_swap_b32_e32 v112, v113
	v_lshl_add_u64 v[118:119], s[12:13], 0, v[168:169]
	global_store_dwordx4 v[118:119], v[114:117], off
	s_and_saveexec_b64 s[30:31], s[4:5]
	s_cbranch_execz .LBB0_542
	v_lshlrev_b64 v[114:115], 6, v[150:151]
	v_lshl_add_u64 v[114:115], s[14:15], 0, v[114:115]
	v_lshl_add_u64 v[114:115], s[28:29], 2, v[114:115]
	s_lshl_b32 s8, s46, 2
	v_lshl_add_u64 v[114:115], v[114:115], 0, s[8:9]
	s_waitcnt lgkmcnt(0)
	v_add_f32_e32 v112, v112, v113
	global_store_dword v[114:115], v112, off
.LBB0_542:
	s_or_b64 exec, exec, s[30:31]
	v_or_b32_e32 v112, 16, v150
	s_waitcnt lgkmcnt(0)
	v_ashrrev_i32_e32 v113, 31, v112
	v_lshlrev_b64 v[114:115], 10, v[112:113]
	v_lshl_add_u64 v[118:119], v[114:115], 0, v[148:149]
	v_lshl_add_u64 v[126:127], v[118:119], 2, s[52:53]
	global_load_dwordx4 v[114:117], v[126:127], off
	global_load_dwordx4 v[122:125], v[126:127], off offset:16
	v_lshlrev_b64 v[118:119], 1, v[118:119]
	v_lshl_add_u64 v[160:161], s[12:13], 0, v[118:119]
	v_or_b32_e32 v118, 0x100, v118
	s_waitcnt vmcnt(1)
	v_pk_add_f32 v[116:117], v[110:111], v[116:117]
	v_pk_add_f32 v[114:115], v[108:109], v[114:115]
	s_waitcnt vmcnt(0)
	v_pk_add_f32 v[124:125], v[106:107], v[124:125]
	v_pk_add_f32 v[122:123], v[104:105], v[122:123]
	v_cvt_pk_bf16_f32 v104, v114, v115
	v_cvt_pk_bf16_f32 v105, v116, v117
	v_cvt_pk_bf16_f32 v106, v122, v123
	v_cvt_pk_bf16_f32 v107, v124, v125
	global_store_dwordx4 v[160:161], v[104:107], off
	global_load_dwordx4 v[104:107], v[126:127], off offset:512
	s_nop 0
	global_load_dwordx4 v[108:111], v[126:127], off offset:528
	v_pk_mul_f32 v[116:117], v[116:117], v[116:117]
	v_pk_mul_f32 v[114:115], v[114:115], v[114:115]
	v_pk_mul_f32 v[124:125], v[124:125], v[124:125]
	v_pk_mul_f32 v[122:123], v[122:123], v[122:123]
	v_add_f32_e32 v124, v124, v125
	v_add_f32_e32 v122, v122, v123
	v_add_f32_e32 v116, v116, v117
	v_add_f32_e32 v114, v114, v115
	v_add_f32_e32 v115, v122, v124
	v_add_f32_e32 v114, v114, v116
	v_add_f32_e32 v114, v114, v115
	s_waitcnt vmcnt(1)
	v_pk_add_f32 v[102:103], v[102:103], v[106:107]
	v_pk_add_f32 v[100:101], v[100:101], v[104:105]
	s_waitcnt vmcnt(0)
	v_pk_add_f32 v[104:105], v[98:99], v[110:111]
	v_pk_add_f32 v[96:97], v[96:97], v[108:109]
	v_pk_mul_f32 v[98:99], v[102:103], v[102:103]
	v_pk_mul_f32 v[106:107], v[100:101], v[100:101]
	v_pk_mul_f32 v[108:109], v[104:105], v[104:105]
	v_pk_mul_f32 v[110:111], v[96:97], v[96:97]
	v_add_f32_e32 v108, v108, v109
	v_add_f32_e32 v109, v110, v111
	v_add_f32_e32 v98, v98, v99
	v_add_f32_e32 v99, v106, v107
	v_add_f32_e32 v106, v109, v108
	v_add_f32_e32 v98, v99, v98
	v_add_f32_e32 v98, v98, v106
	v_add_f32_e32 v106, v114, v98
	v_mov_b32_e32 v107, v106
	s_nop 1
	v_permlane16_swap_b32_e32 v106, v107
	v_cvt_pk_bf16_f32 v98, v100, v101
	v_cvt_pk_bf16_f32 v100, v96, v97
	v_cvt_pk_bf16_f32 v99, v102, v103
	v_cvt_pk_bf16_f32 v101, v104, v105
	s_waitcnt lgkmcnt(0)
	v_add_f32_e32 v96, v106, v107
	v_mov_b32_e32 v97, v96
	s_nop 1
	v_permlane32_swap_b32_e32 v96, v97
	v_lshl_add_u64 v[102:103], s[12:13], 0, v[118:119]
	global_store_dwordx4 v[102:103], v[98:101], off
	s_and_saveexec_b64 s[30:31], s[4:5]
	s_cbranch_execz .LBB0_544
	v_lshlrev_b64 v[98:99], 6, v[112:113]
	v_lshl_add_u64 v[98:99], s[14:15], 0, v[98:99]
	v_lshl_add_u64 v[98:99], s[28:29], 2, v[98:99]
	s_lshl_b32 s8, s46, 2
	v_lshl_add_u64 v[98:99], v[98:99], 0, s[8:9]
	s_waitcnt lgkmcnt(0)
	v_add_f32_e32 v96, v96, v97
	global_store_dword v[98:99], v96, off
.LBB0_544:
	s_or_b64 exec, exec, s[30:31]
	v_or_b32_e32 v96, 32, v150
	s_waitcnt lgkmcnt(0)
	v_ashrrev_i32_e32 v97, 31, v96
	v_lshlrev_b64 v[98:99], 10, v[96:97]
	v_lshl_add_u64 v[106:107], v[98:99], 0, v[148:149]
	v_lshl_add_u64 v[108:109], v[106:107], 2, s[52:53]
	global_load_dwordx4 v[98:101], v[108:109], off
	global_load_dwordx4 v[102:105], v[108:109], off offset:16
	v_lshlrev_b64 v[106:107], 1, v[106:107]
	v_lshl_add_u64 v[110:111], s[12:13], 0, v[106:107]
	v_or_b32_e32 v106, 0x100, v106
	s_waitcnt vmcnt(1)
	v_pk_add_f32 v[100:101], v[94:95], v[100:101]
	v_pk_add_f32 v[98:99], v[92:93], v[98:99]
	s_waitcnt vmcnt(0)
	v_pk_add_f32 v[104:105], v[90:91], v[104:105]
	v_pk_add_f32 v[102:103], v[88:89], v[102:103]
	v_cvt_pk_bf16_f32 v88, v98, v99
	v_cvt_pk_bf16_f32 v89, v100, v101
	v_cvt_pk_bf16_f32 v90, v102, v103
	v_cvt_pk_bf16_f32 v91, v104, v105
	global_store_dwordx4 v[110:111], v[88:91], off
	global_load_dwordx4 v[88:91], v[108:109], off offset:512
	s_nop 0
	global_load_dwordx4 v[92:95], v[108:109], off offset:528
	v_pk_mul_f32 v[100:101], v[100:101], v[100:101]
	v_pk_mul_f32 v[98:99], v[98:99], v[98:99]
	v_pk_mul_f32 v[104:105], v[104:105], v[104:105]
	v_pk_mul_f32 v[102:103], v[102:103], v[102:103]
	v_add_f32_e32 v104, v104, v105
	v_add_f32_e32 v102, v102, v103
	v_add_f32_e32 v100, v100, v101
	v_add_f32_e32 v98, v98, v99
	v_add_f32_e32 v99, v102, v104
	v_add_f32_e32 v98, v98, v100
	v_add_f32_e32 v98, v98, v99
	s_waitcnt vmcnt(1)
	v_pk_add_f32 v[86:87], v[86:87], v[90:91]
	v_pk_add_f32 v[84:85], v[84:85], v[88:89]
	s_waitcnt vmcnt(0)
	v_pk_add_f32 v[88:89], v[82:83], v[94:95]
	v_pk_add_f32 v[80:81], v[80:81], v[92:93]
	v_pk_mul_f32 v[82:83], v[86:87], v[86:87]
	v_pk_mul_f32 v[90:91], v[84:85], v[84:85]
	v_pk_mul_f32 v[92:93], v[88:89], v[88:89]
	v_pk_mul_f32 v[94:95], v[80:81], v[80:81]
	v_add_f32_e32 v92, v92, v93
	v_add_f32_e32 v93, v94, v95
	v_add_f32_e32 v82, v82, v83
	v_add_f32_e32 v83, v90, v91
	v_add_f32_e32 v90, v93, v92
	v_add_f32_e32 v82, v83, v82
	v_add_f32_e32 v82, v82, v90
	v_add_f32_e32 v90, v98, v82
	v_mov_b32_e32 v91, v90
	s_nop 1
	v_permlane16_swap_b32_e32 v90, v91
	v_cvt_pk_bf16_f32 v82, v84, v85
	v_cvt_pk_bf16_f32 v84, v80, v81
	v_cvt_pk_bf16_f32 v83, v86, v87
	v_cvt_pk_bf16_f32 v85, v88, v89
	s_waitcnt lgkmcnt(0)
	v_add_f32_e32 v80, v90, v91
	v_mov_b32_e32 v81, v80
	s_nop 1
	v_permlane32_swap_b32_e32 v80, v81
	v_lshl_add_u64 v[86:87], s[12:13], 0, v[106:107]
	global_store_dwordx4 v[86:87], v[82:85], off
	s_and_saveexec_b64 s[30:31], s[4:5]
	s_cbranch_execz .LBB0_546
	v_lshlrev_b64 v[82:83], 6, v[96:97]
	v_lshl_add_u64 v[82:83], s[14:15], 0, v[82:83]
	v_lshl_add_u64 v[82:83], s[28:29], 2, v[82:83]
	s_lshl_b32 s8, s46, 2
	v_lshl_add_u64 v[82:83], v[82:83], 0, s[8:9]
	s_waitcnt lgkmcnt(0)
	v_add_f32_e32 v80, v80, v81
	global_store_dword v[82:83], v80, off
.LBB0_546:
	s_or_b64 exec, exec, s[30:31]
	v_or_b32_e32 v80, 48, v150
	s_waitcnt lgkmcnt(0)
	v_ashrrev_i32_e32 v81, 31, v80
	v_lshlrev_b64 v[82:83], 10, v[80:81]
	v_lshl_add_u64 v[90:91], v[82:83], 0, v[148:149]
	v_lshl_add_u64 v[92:93], v[90:91], 2, s[52:53]
	global_load_dwordx4 v[82:85], v[92:93], off
	global_load_dwordx4 v[86:89], v[92:93], off offset:16
	v_lshlrev_b64 v[90:91], 1, v[90:91]
	v_lshl_add_u64 v[94:95], s[12:13], 0, v[90:91]
	v_or_b32_e32 v90, 0x100, v90
	s_waitcnt vmcnt(1)
	v_pk_add_f32 v[84:85], v[78:79], v[84:85]
	v_pk_add_f32 v[82:83], v[76:77], v[82:83]
	s_waitcnt vmcnt(0)
	v_pk_add_f32 v[88:89], v[74:75], v[88:89]
	v_pk_add_f32 v[86:87], v[72:73], v[86:87]
	v_cvt_pk_bf16_f32 v72, v82, v83
	v_cvt_pk_bf16_f32 v73, v84, v85
	v_cvt_pk_bf16_f32 v74, v86, v87
	v_cvt_pk_bf16_f32 v75, v88, v89
	global_store_dwordx4 v[94:95], v[72:75], off
	global_load_dwordx4 v[72:75], v[92:93], off offset:512
	s_nop 0
	global_load_dwordx4 v[76:79], v[92:93], off offset:528
	v_pk_mul_f32 v[84:85], v[84:85], v[84:85]
	v_pk_mul_f32 v[82:83], v[82:83], v[82:83]
	v_pk_mul_f32 v[88:89], v[88:89], v[88:89]
	v_pk_mul_f32 v[86:87], v[86:87], v[86:87]
	v_add_f32_e32 v88, v88, v89
	v_add_f32_e32 v86, v86, v87
	v_add_f32_e32 v84, v84, v85
	v_add_f32_e32 v82, v82, v83
	v_add_f32_e32 v83, v86, v88
	v_add_f32_e32 v82, v82, v84
	v_add_f32_e32 v82, v82, v83
	s_waitcnt vmcnt(1)
	v_pk_add_f32 v[70:71], v[70:71], v[74:75]
	v_pk_add_f32 v[68:69], v[68:69], v[72:73]
	s_waitcnt vmcnt(0)
	v_pk_add_f32 v[72:73], v[66:67], v[78:79]
	v_pk_add_f32 v[64:65], v[64:65], v[76:77]
	v_pk_mul_f32 v[66:67], v[70:71], v[70:71]
	v_pk_mul_f32 v[74:75], v[68:69], v[68:69]
	v_pk_mul_f32 v[76:77], v[72:73], v[72:73]
	v_pk_mul_f32 v[78:79], v[64:65], v[64:65]
	v_add_f32_e32 v76, v76, v77
	v_add_f32_e32 v77, v78, v79
	v_add_f32_e32 v66, v66, v67
	v_add_f32_e32 v67, v74, v75
	v_add_f32_e32 v74, v77, v76
	v_add_f32_e32 v66, v67, v66
	v_add_f32_e32 v66, v66, v74
	v_add_f32_e32 v74, v82, v66
	v_mov_b32_e32 v75, v74
	s_nop 1
	v_permlane16_swap_b32_e32 v74, v75
	v_cvt_pk_bf16_f32 v66, v68, v69
	v_cvt_pk_bf16_f32 v68, v64, v65
	v_cvt_pk_bf16_f32 v67, v70, v71
	v_cvt_pk_bf16_f32 v69, v72, v73
	s_waitcnt lgkmcnt(0)
	v_add_f32_e32 v64, v74, v75
	v_mov_b32_e32 v65, v64
	s_nop 1
	v_permlane32_swap_b32_e32 v64, v65
	v_lshl_add_u64 v[70:71], s[12:13], 0, v[90:91]
	global_store_dwordx4 v[70:71], v[66:69], off
	s_and_saveexec_b64 s[30:31], s[4:5]
	s_cbranch_execz .LBB0_548
	v_lshlrev_b64 v[66:67], 6, v[80:81]
	v_lshl_add_u64 v[66:67], s[14:15], 0, v[66:67]
	v_lshl_add_u64 v[66:67], s[28:29], 2, v[66:67]
	s_lshl_b32 s8, s46, 2
	v_lshl_add_u64 v[66:67], v[66:67], 0, s[8:9]
	s_waitcnt lgkmcnt(0)
	v_add_f32_e32 v64, v64, v65
	global_store_dword v[66:67], v64, off
.LBB0_548:
	s_or_b64 exec, exec, s[30:31]
	v_add_u32_e32 v64, 0x80, v150
	s_waitcnt lgkmcnt(0)
	v_ashrrev_i32_e32 v65, 31, v64
	v_lshlrev_b64 v[66:67], 10, v[64:65]
	v_lshl_add_u64 v[74:75], v[66:67], 0, v[148:149]
	v_lshl_add_u64 v[76:77], v[74:75], 2, s[52:53]
	global_load_dwordx4 v[66:69], v[76:77], off
	global_load_dwordx4 v[70:73], v[76:77], off offset:16
	v_lshlrev_b64 v[74:75], 1, v[74:75]
	v_lshl_add_u64 v[78:79], s[12:13], 0, v[74:75]
	v_or_b32_e32 v74, 0x100, v74
	s_waitcnt vmcnt(1)
	v_pk_add_f32 v[68:69], v[62:63], v[68:69]
	v_pk_add_f32 v[66:67], v[60:61], v[66:67]
	s_waitcnt vmcnt(0)
	v_pk_add_f32 v[72:73], v[58:59], v[72:73]
	v_pk_add_f32 v[70:71], v[56:57], v[70:71]
	v_cvt_pk_bf16_f32 v56, v66, v67
	v_cvt_pk_bf16_f32 v57, v68, v69
	v_cvt_pk_bf16_f32 v58, v70, v71
	v_cvt_pk_bf16_f32 v59, v72, v73
	global_store_dwordx4 v[78:79], v[56:59], off
	global_load_dwordx4 v[56:59], v[76:77], off offset:512
	s_nop 0
	global_load_dwordx4 v[60:63], v[76:77], off offset:528
	v_pk_mul_f32 v[68:69], v[68:69], v[68:69]
	v_pk_mul_f32 v[66:67], v[66:67], v[66:67]
	v_pk_mul_f32 v[72:73], v[72:73], v[72:73]
	v_pk_mul_f32 v[70:71], v[70:71], v[70:71]
	v_add_f32_e32 v72, v72, v73
	v_add_f32_e32 v70, v70, v71
	v_add_f32_e32 v68, v68, v69
	v_add_f32_e32 v66, v66, v67
	v_add_f32_e32 v67, v70, v72
	v_add_f32_e32 v66, v66, v68
	v_add_f32_e32 v66, v66, v67
	s_waitcnt vmcnt(1)
	v_pk_add_f32 v[54:55], v[54:55], v[58:59]
	v_pk_add_f32 v[52:53], v[52:53], v[56:57]
	s_waitcnt vmcnt(0)
	v_pk_add_f32 v[56:57], v[50:51], v[62:63]
	v_pk_add_f32 v[48:49], v[48:49], v[60:61]
	v_pk_mul_f32 v[50:51], v[54:55], v[54:55]
	v_pk_mul_f32 v[58:59], v[52:53], v[52:53]
	v_pk_mul_f32 v[60:61], v[56:57], v[56:57]
	v_pk_mul_f32 v[62:63], v[48:49], v[48:49]
	v_add_f32_e32 v60, v60, v61
	v_add_f32_e32 v61, v62, v63
	v_add_f32_e32 v50, v50, v51
	v_add_f32_e32 v51, v58, v59
	v_add_f32_e32 v58, v61, v60
	v_add_f32_e32 v50, v51, v50
	v_add_f32_e32 v50, v50, v58
	v_add_f32_e32 v58, v66, v50
	v_mov_b32_e32 v59, v58
	s_nop 1
	v_permlane16_swap_b32_e32 v58, v59
	v_cvt_pk_bf16_f32 v50, v52, v53
	v_cvt_pk_bf16_f32 v52, v48, v49
	v_cvt_pk_bf16_f32 v51, v54, v55
	v_cvt_pk_bf16_f32 v53, v56, v57
	s_waitcnt lgkmcnt(0)
	v_add_f32_e32 v48, v58, v59
	v_mov_b32_e32 v49, v48
	s_nop 1
	v_permlane32_swap_b32_e32 v48, v49
	v_lshl_add_u64 v[54:55], s[12:13], 0, v[74:75]
	global_store_dwordx4 v[54:55], v[50:53], off
	s_and_saveexec_b64 s[30:31], s[4:5]
	s_cbranch_execz .LBB0_550
	v_lshlrev_b64 v[50:51], 6, v[64:65]
	v_lshl_add_u64 v[50:51], s[14:15], 0, v[50:51]
	v_lshl_add_u64 v[50:51], s[28:29], 2, v[50:51]
	s_lshl_b32 s8, s46, 2
	v_lshl_add_u64 v[50:51], v[50:51], 0, s[8:9]
	s_waitcnt lgkmcnt(0)
	v_add_f32_e32 v48, v48, v49
	global_store_dword v[50:51], v48, off
.LBB0_550:
	s_or_b64 exec, exec, s[30:31]
	v_add_u32_e32 v48, 0x90, v150
	s_waitcnt lgkmcnt(0)
	v_ashrrev_i32_e32 v49, 31, v48
	v_lshlrev_b64 v[50:51], 10, v[48:49]
	v_lshl_add_u64 v[58:59], v[50:51], 0, v[148:149]
	v_lshl_add_u64 v[60:61], v[58:59], 2, s[52:53]
	global_load_dwordx4 v[50:53], v[60:61], off
	global_load_dwordx4 v[54:57], v[60:61], off offset:16
	v_lshlrev_b64 v[58:59], 1, v[58:59]
	v_lshl_add_u64 v[62:63], s[12:13], 0, v[58:59]
	v_or_b32_e32 v58, 0x100, v58
	s_waitcnt vmcnt(1)
	v_pk_add_f32 v[52:53], v[46:47], v[52:53]
	v_pk_add_f32 v[50:51], v[44:45], v[50:51]
	s_waitcnt vmcnt(0)
	v_pk_add_f32 v[56:57], v[42:43], v[56:57]
	v_pk_add_f32 v[54:55], v[40:41], v[54:55]
	v_cvt_pk_bf16_f32 v40, v50, v51
	v_cvt_pk_bf16_f32 v41, v52, v53
	v_cvt_pk_bf16_f32 v42, v54, v55
	v_cvt_pk_bf16_f32 v43, v56, v57
	global_store_dwordx4 v[62:63], v[40:43], off
	global_load_dwordx4 v[40:43], v[60:61], off offset:512
	s_nop 0
	global_load_dwordx4 v[44:47], v[60:61], off offset:528
	v_pk_mul_f32 v[52:53], v[52:53], v[52:53]
	v_pk_mul_f32 v[50:51], v[50:51], v[50:51]
	v_pk_mul_f32 v[56:57], v[56:57], v[56:57]
	v_pk_mul_f32 v[54:55], v[54:55], v[54:55]
	v_add_f32_e32 v56, v56, v57
	v_add_f32_e32 v54, v54, v55
	v_add_f32_e32 v52, v52, v53
	v_add_f32_e32 v50, v50, v51
	v_add_f32_e32 v51, v54, v56
	v_add_f32_e32 v50, v50, v52
	v_add_f32_e32 v50, v50, v51
	s_waitcnt vmcnt(1)
	v_pk_add_f32 v[38:39], v[38:39], v[42:43]
	v_pk_add_f32 v[36:37], v[36:37], v[40:41]
	s_waitcnt vmcnt(0)
	v_pk_add_f32 v[40:41], v[34:35], v[46:47]
	v_pk_add_f32 v[32:33], v[32:33], v[44:45]
	v_pk_mul_f32 v[34:35], v[38:39], v[38:39]
	v_pk_mul_f32 v[42:43], v[36:37], v[36:37]
	v_pk_mul_f32 v[44:45], v[40:41], v[40:41]
	v_pk_mul_f32 v[46:47], v[32:33], v[32:33]
	v_add_f32_e32 v44, v44, v45
	v_add_f32_e32 v45, v46, v47
	v_add_f32_e32 v34, v34, v35
	v_add_f32_e32 v35, v42, v43
	v_add_f32_e32 v42, v45, v44
	v_add_f32_e32 v34, v35, v34
	v_add_f32_e32 v34, v34, v42
	v_add_f32_e32 v42, v50, v34
	v_mov_b32_e32 v43, v42
	s_nop 1
	v_permlane16_swap_b32_e32 v42, v43
	v_cvt_pk_bf16_f32 v34, v36, v37
	v_cvt_pk_bf16_f32 v36, v32, v33
	v_cvt_pk_bf16_f32 v35, v38, v39
	v_cvt_pk_bf16_f32 v37, v40, v41
	s_waitcnt lgkmcnt(0)
	v_add_f32_e32 v32, v42, v43
	v_mov_b32_e32 v33, v32
	s_nop 1
	v_permlane32_swap_b32_e32 v32, v33
	v_lshl_add_u64 v[38:39], s[12:13], 0, v[58:59]
	global_store_dwordx4 v[38:39], v[34:37], off
	s_and_saveexec_b64 s[30:31], s[4:5]
	s_cbranch_execz .LBB0_552
	v_lshlrev_b64 v[34:35], 6, v[48:49]
	v_lshl_add_u64 v[34:35], s[14:15], 0, v[34:35]
	v_lshl_add_u64 v[34:35], s[28:29], 2, v[34:35]
	s_lshl_b32 s8, s46, 2
	v_lshl_add_u64 v[34:35], v[34:35], 0, s[8:9]
	s_waitcnt lgkmcnt(0)
	v_add_f32_e32 v32, v32, v33
	global_store_dword v[34:35], v32, off
.LBB0_552:
	s_or_b64 exec, exec, s[30:31]
	v_add_u32_e32 v32, 0xa0, v150
	s_waitcnt lgkmcnt(0)
	v_ashrrev_i32_e32 v33, 31, v32
	v_lshlrev_b64 v[34:35], 10, v[32:33]
	v_lshl_add_u64 v[42:43], v[34:35], 0, v[148:149]
	v_lshl_add_u64 v[44:45], v[42:43], 2, s[52:53]
	global_load_dwordx4 v[34:37], v[44:45], off
	global_load_dwordx4 v[38:41], v[44:45], off offset:16
	v_lshlrev_b64 v[42:43], 1, v[42:43]
	v_lshl_add_u64 v[46:47], s[12:13], 0, v[42:43]
	v_or_b32_e32 v42, 0x100, v42
	s_waitcnt vmcnt(1)
	v_pk_add_f32 v[36:37], v[30:31], v[36:37]
	v_pk_add_f32 v[34:35], v[28:29], v[34:35]
	s_waitcnt vmcnt(0)
	v_pk_add_f32 v[40:41], v[26:27], v[40:41]
	v_pk_add_f32 v[38:39], v[24:25], v[38:39]
	v_cvt_pk_bf16_f32 v24, v34, v35
	v_cvt_pk_bf16_f32 v25, v36, v37
	v_cvt_pk_bf16_f32 v26, v38, v39
	v_cvt_pk_bf16_f32 v27, v40, v41
	global_store_dwordx4 v[46:47], v[24:27], off
	global_load_dwordx4 v[24:27], v[44:45], off offset:512
	s_nop 0
	global_load_dwordx4 v[28:31], v[44:45], off offset:528
	v_pk_mul_f32 v[36:37], v[36:37], v[36:37]
	v_pk_mul_f32 v[34:35], v[34:35], v[34:35]
	v_pk_mul_f32 v[40:41], v[40:41], v[40:41]
	v_pk_mul_f32 v[38:39], v[38:39], v[38:39]
	v_add_f32_e32 v40, v40, v41
	v_add_f32_e32 v38, v38, v39
	v_add_f32_e32 v36, v36, v37
	v_add_f32_e32 v34, v34, v35
	v_add_f32_e32 v35, v38, v40
	v_add_f32_e32 v34, v34, v36
	v_add_f32_e32 v34, v34, v35
	s_waitcnt vmcnt(1)
	v_pk_add_f32 v[22:23], v[22:23], v[26:27]
	v_pk_add_f32 v[20:21], v[20:21], v[24:25]
	s_waitcnt vmcnt(0)
	v_pk_add_f32 v[24:25], v[18:19], v[30:31]
	v_pk_add_f32 v[16:17], v[16:17], v[28:29]
	v_pk_mul_f32 v[18:19], v[22:23], v[22:23]
	v_pk_mul_f32 v[26:27], v[20:21], v[20:21]
	v_pk_mul_f32 v[28:29], v[24:25], v[24:25]
	v_pk_mul_f32 v[30:31], v[16:17], v[16:17]
	v_add_f32_e32 v28, v28, v29
	v_add_f32_e32 v29, v30, v31
	v_add_f32_e32 v18, v18, v19
	v_add_f32_e32 v19, v26, v27
	v_add_f32_e32 v26, v29, v28
	v_add_f32_e32 v18, v19, v18
	v_add_f32_e32 v18, v18, v26
	v_add_f32_e32 v26, v34, v18
	v_mov_b32_e32 v27, v26
	s_nop 1
	v_permlane16_swap_b32_e32 v26, v27
	v_cvt_pk_bf16_f32 v18, v20, v21
	v_cvt_pk_bf16_f32 v20, v16, v17
	v_cvt_pk_bf16_f32 v19, v22, v23
	v_cvt_pk_bf16_f32 v21, v24, v25
	s_waitcnt lgkmcnt(0)
	v_add_f32_e32 v16, v26, v27
	v_mov_b32_e32 v17, v16
	s_nop 1
	v_permlane32_swap_b32_e32 v16, v17
	v_lshl_add_u64 v[22:23], s[12:13], 0, v[42:43]
	global_store_dwordx4 v[22:23], v[18:21], off
	s_and_saveexec_b64 s[30:31], s[4:5]
	s_cbranch_execz .LBB0_554
	v_lshlrev_b64 v[18:19], 6, v[32:33]
	v_lshl_add_u64 v[18:19], s[14:15], 0, v[18:19]
	v_lshl_add_u64 v[18:19], s[28:29], 2, v[18:19]
	s_lshl_b32 s8, s46, 2
	v_lshl_add_u64 v[18:19], v[18:19], 0, s[8:9]
	s_waitcnt lgkmcnt(0)
	v_add_f32_e32 v16, v16, v17
	global_store_dword v[18:19], v16, off
.LBB0_554:
	s_or_b64 exec, exec, s[30:31]
	v_add_u32_e32 v16, 0xb0, v150
	s_waitcnt lgkmcnt(0)
	v_ashrrev_i32_e32 v17, 31, v16
	v_lshlrev_b64 v[18:19], 10, v[16:17]
	v_lshl_add_u64 v[26:27], v[18:19], 0, v[148:149]
	v_lshl_add_u64 v[28:29], v[26:27], 2, s[52:53]
	global_load_dwordx4 v[18:21], v[28:29], off
	global_load_dwordx4 v[22:25], v[28:29], off offset:16
	v_lshlrev_b64 v[26:27], 1, v[26:27]
	v_lshl_add_u64 v[30:31], s[12:13], 0, v[26:27]
	v_or_b32_e32 v26, 0x100, v26
	s_waitcnt vmcnt(1)
	v_pk_add_f32 v[20:21], v[14:15], v[20:21]
	v_pk_add_f32 v[18:19], v[12:13], v[18:19]
	s_waitcnt vmcnt(0)
	v_pk_add_f32 v[24:25], v[10:11], v[24:25]
	v_pk_add_f32 v[22:23], v[8:9], v[22:23]
	v_cvt_pk_bf16_f32 v8, v18, v19
	v_cvt_pk_bf16_f32 v9, v20, v21
	v_cvt_pk_bf16_f32 v10, v22, v23
	v_cvt_pk_bf16_f32 v11, v24, v25
	global_store_dwordx4 v[30:31], v[8:11], off
	global_load_dwordx4 v[8:11], v[28:29], off offset:512
	s_nop 0
	global_load_dwordx4 v[12:15], v[28:29], off offset:528
	v_pk_mul_f32 v[20:21], v[20:21], v[20:21]
	v_pk_mul_f32 v[18:19], v[18:19], v[18:19]
	v_pk_mul_f32 v[24:25], v[24:25], v[24:25]
	v_pk_mul_f32 v[22:23], v[22:23], v[22:23]
	v_add_f32_e32 v24, v24, v25
	v_add_f32_e32 v22, v22, v23
	v_add_f32_e32 v20, v20, v21
	v_add_f32_e32 v18, v18, v19
	v_add_f32_e32 v19, v22, v24
	v_add_f32_e32 v18, v18, v20
	v_add_f32_e32 v18, v18, v19
	s_waitcnt vmcnt(1)
	v_pk_add_f32 v[6:7], v[6:7], v[10:11]
	v_pk_add_f32 v[4:5], v[4:5], v[8:9]
	s_waitcnt vmcnt(0)
	v_pk_add_f32 v[8:9], v[2:3], v[14:15]
	v_pk_add_f32 v[0:1], v[0:1], v[12:13]
	v_pk_mul_f32 v[2:3], v[6:7], v[6:7]
	v_pk_mul_f32 v[10:11], v[4:5], v[4:5]
	v_pk_mul_f32 v[12:13], v[8:9], v[8:9]
	v_pk_mul_f32 v[14:15], v[0:1], v[0:1]
	v_add_f32_e32 v12, v12, v13
	v_add_f32_e32 v13, v14, v15
	v_add_f32_e32 v2, v2, v3
	v_add_f32_e32 v3, v10, v11
	v_add_f32_e32 v10, v13, v12
	v_add_f32_e32 v2, v3, v2
	v_add_f32_e32 v2, v2, v10
	v_add_f32_e32 v10, v18, v2
	v_mov_b32_e32 v11, v10
	s_nop 1
	v_permlane16_swap_b32_e32 v10, v11
	v_cvt_pk_bf16_f32 v2, v4, v5
	v_cvt_pk_bf16_f32 v4, v0, v1
	v_cvt_pk_bf16_f32 v3, v6, v7
	v_cvt_pk_bf16_f32 v5, v8, v9
	s_waitcnt lgkmcnt(0)
	v_add_f32_e32 v0, v10, v11
	v_mov_b32_e32 v1, v0
	s_nop 1
	v_permlane32_swap_b32_e32 v0, v1
	v_lshl_add_u64 v[6:7], s[12:13], 0, v[26:27]
	global_store_dwordx4 v[6:7], v[2:5], off
	s_and_saveexec_b64 s[30:31], s[4:5]
	s_cbranch_execz .LBB0_556
	v_lshlrev_b64 v[2:3], 6, v[16:17]
	v_lshl_add_u64 v[2:3], s[14:15], 0, v[2:3]
	v_lshl_add_u64 v[2:3], s[28:29], 2, v[2:3]
	s_lshl_b32 s8, s46, 2
	v_lshl_add_u64 v[2:3], v[2:3], 0, s[8:9]
	s_waitcnt lgkmcnt(0)
	v_add_f32_e32 v0, v0, v1
	global_store_dword v[2:3], v0, off

.LBB0_627:
	v_lshl_add_u32 v152, s0, 8, v154
	v_ashrrev_i32_e32 v153, 31, v152
	v_lshlrev_b64 v[150:151], 6, v[152:153]
	v_lshl_add_u64 v[150:151], v[140:141], 0, v[150:151]
	global_load_dwordx4 v[164:167], v[150:151], off
	v_and_b32_e32 v163, 64, v161
	v_xor_b32_e32 v153, 16, v161
	v_pk_mul_f32 v[170:171], v[114:115], v[122:123]
	v_add_u32_e32 v122, 64, v163
	v_cmp_lt_i32_e32 vcc, v153, v122
	v_pk_mul_f32 v[172:173], v[112:113], v[120:121]
	v_xor_b32_e32 v174, 32, v161
	v_cndmask_b32_e32 v120, v161, v153, vcc
	v_lshlrev_b32_e32 v123, 2, v120
	v_cmp_lt_i32_e32 vcc, v174, v122
	v_pk_mul_f32 v[126:127], v[118:119], v[126:127]
	v_pk_mul_f32 v[124:125], v[116:117], v[124:125]
	v_cndmask_b32_e32 v122, v161, v174, vcc
	v_lshlrev_b32_e32 v122, 2, v122
	v_lshl_or_b32 v168, s1, 7, v156
	v_ashrrev_i32_e32 v169, 31, v168
	v_mov_b64_e32 v[150:151], s[10:11]
	v_pk_mul_f32 v[110:111], v[102:103], v[110:111]
	v_pk_mul_f32 v[108:109], v[100:101], v[108:109]
	v_pk_mul_f32 v[106:107], v[98:99], v[106:107]
	v_pk_mul_f32 v[104:105], v[96:97], v[104:105]
	v_pk_mul_f32 v[94:95], v[86:87], v[94:95]
	v_pk_mul_f32 v[92:93], v[84:85], v[92:93]
	v_pk_mul_f32 v[90:91], v[82:83], v[90:91]
	v_pk_mul_f32 v[88:89], v[80:81], v[88:89]
	v_pk_mul_f32 v[78:79], v[70:71], v[78:79]
	v_pk_mul_f32 v[76:77], v[68:69], v[76:77]
	v_pk_mul_f32 v[74:75], v[66:67], v[74:75]
	v_pk_mul_f32 v[72:73], v[64:65], v[72:73]
	v_pk_mul_f32 v[62:63], v[54:55], v[62:63]
	v_pk_mul_f32 v[60:61], v[52:53], v[60:61]
	v_pk_mul_f32 v[58:59], v[50:51], v[58:59]
	v_pk_mul_f32 v[56:57], v[48:49], v[56:57]
	v_pk_mul_f32 v[46:47], v[38:39], v[46:47]
	v_pk_mul_f32 v[44:45], v[36:37], v[44:45]
	v_pk_mul_f32 v[42:43], v[34:35], v[42:43]
	v_pk_mul_f32 v[40:41], v[32:33], v[40:41]
	v_pk_mul_f32 v[30:31], v[22:23], v[30:31]
	v_pk_mul_f32 v[28:29], v[20:21], v[28:29]
	v_pk_mul_f32 v[26:27], v[18:19], v[26:27]
	v_pk_mul_f32 v[24:25], v[16:17], v[24:25]
	v_pk_mul_f32 v[14:15], v[6:7], v[14:15]
	v_pk_mul_f32 v[12:13], v[4:5], v[12:13]
	v_pk_mul_f32 v[10:11], v[2:3], v[10:11]
	v_pk_mul_f32 v[8:9], v[0:1], v[8:9]
	s_waitcnt vmcnt(0)
	v_mov_b32_e32 v120, v165
	v_mov_b32_e32 v121, v166
	v_mov_b32_e32 v165, v167
	v_pk_add_f32 v[120:121], v[120:121], v[164:165]
	v_or_b32_e32 v166, 16, v152
	v_add_f32_e32 v120, v120, v121
	v_mov_b32_e32 v121, v120
	s_nop 1
	v_permlane16_swap_b32_e32 v120, v121
	v_ashrrev_i32_e32 v167, 31, v166
	v_mad_i64_i32 v[164:165], s[0:1], v152, s49, v[150:151]
	s_waitcnt lgkmcnt(0)
	v_add_f32_e32 v153, v120, v121
	v_mov_b32_e32 v163, v153
	s_nop 1
	v_permlane32_swap_b32_e32 v153, v163
	v_lshlrev_b64 v[120:121], 1, v[168:169]
	v_lshlrev_b64 v[168:169], 6, v[166:167]
	v_lshl_add_u64 v[164:165], v[164:165], 0, v[120:121]
	v_lshl_add_u64 v[168:169], v[140:141], 0, v[168:169]
	s_waitcnt lgkmcnt(0)
	v_add_f32_e32 v153, v153, v163
	v_fmamk_f32 v153, v153, 0x3a800000, v162
	v_mul_f32_e32 v163, 0x4b800000, v153
	v_cmp_gt_f32_e32 vcc, s52, v153
	s_nop 1
	v_cndmask_b32_e32 v153, v153, v163, vcc
	v_rsq_f32_e32 v153, v153
	s_nop 0
	v_mul_f32_e32 v163, 0x45800000, v153
	v_cndmask_b32_e32 v153, v153, v163, vcc
	v_mul_f32_e32 v163, 0xbfb8aa3b, v153
	v_mul_f32_e32 v116, v116, v163
	v_mul_f32_e32 v117, v117, v163
	v_mul_f32_e32 v118, v118, v163
	v_mul_f32_e32 v119, v119, v163
	v_mul_f32_e32 v112, v112, v163
	v_mul_f32_e32 v113, v113, v163
	v_mul_f32_e32 v114, v114, v163
	v_mul_f32_e32 v115, v115, v163
	v_exp_f32_e32 v116, v116
	v_exp_f32_e32 v117, v117
	v_exp_f32_e32 v118, v118
	v_exp_f32_e32 v119, v119
	v_exp_f32_e32 v112, v112
	v_exp_f32_e32 v113, v113
	v_exp_f32_e32 v114, v114
	v_exp_f32_e32 v115, v115
	v_mul_f32_e32 v174, v153, v153
	v_add_f32_e32 v116, 1.0, v116
	v_add_f32_e32 v117, 1.0, v117
	v_add_f32_e32 v118, 1.0, v118
	v_add_f32_e32 v119, 1.0, v119
	v_add_f32_e32 v153, 1.0, v112
	v_add_f32_e32 v163, 1.0, v113
	v_add_f32_e32 v167, 1.0, v114
	v_add_f32_e32 v175, 1.0, v115
	v_rcp_f32_e32 v112, v116
	v_rcp_f32_e32 v113, v117
	v_rcp_f32_e32 v114, v118
	v_rcp_f32_e32 v115, v119
	v_rcp_f32_e32 v116, v153
	v_rcp_f32_e32 v117, v163
	v_rcp_f32_e32 v118, v167
	v_rcp_f32_e32 v119, v175
	v_pk_mul_f32 v[112:113], v[174:175], v[112:113] op_sel_hi:[0,1]
	v_pk_mul_f32 v[114:115], v[174:175], v[114:115] op_sel_hi:[0,1]
	v_pk_mul_f32 v[116:117], v[174:175], v[116:117] op_sel_hi:[0,1]
	v_pk_mul_f32 v[118:119], v[174:175], v[118:119] op_sel_hi:[0,1]
	v_pk_mul_f32 v[112:113], v[124:125], v[112:113]
	v_pk_mul_f32 v[114:115], v[126:127], v[114:115]
	v_pk_mul_f32 v[116:117], v[172:173], v[116:117]
	v_pk_mul_f32 v[118:119], v[170:171], v[118:119]
	v_cvt_pk_bf16_f32 v112, v112, v113
	v_cvt_pk_bf16_f32 v113, v114, v115
	v_cvt_pk_bf16_f32 v114, v116, v117
	v_cvt_pk_bf16_f32 v115, v118, v119
	global_store_dwordx4 v[164:165], v[112:115], off
	global_load_dwordx4 v[112:115], v[168:169], off
	s_waitcnt vmcnt(0)
	v_mov_b32_e32 v116, v113
	v_mov_b32_e32 v117, v114
	v_mov_b32_e32 v113, v115
	v_pk_add_f32 v[112:113], v[116:117], v[112:113]
	v_mad_i64_i32 v[114:115], s[0:1], v166, s49, v[150:151]
	v_add_f32_e32 v112, v112, v113
	v_mov_b32_e32 v113, v112
	s_nop 1
	v_permlane16_swap_b32_e32 v112, v113
	v_lshl_add_u64 v[114:115], v[114:115], 0, v[120:121]
	s_waitcnt lgkmcnt(0)
	v_add_f32_e32 v116, v112, v113
	v_mov_b32_e32 v117, v116
	s_nop 1
	v_permlane32_swap_b32_e32 v116, v117
	v_or_b32_e32 v112, 32, v152
	v_ashrrev_i32_e32 v113, 31, v112
	s_waitcnt lgkmcnt(0)
	v_add_f32_e32 v116, v116, v117
	v_fmamk_f32 v116, v116, 0x3a800000, v162
	v_mul_f32_e32 v117, 0x4b800000, v116
	v_cmp_gt_f32_e32 vcc, s52, v116
	s_nop 1
	v_cndmask_b32_e32 v116, v116, v117, vcc
	v_rsq_f32_e32 v118, v116
	v_lshlrev_b64 v[116:117], 6, v[112:113]
	v_lshl_add_u64 v[116:117], v[140:141], 0, v[116:117]
	v_mul_f32_e32 v113, 0x45800000, v118
	v_cndmask_b32_e32 v113, v118, v113, vcc
	v_mul_f32_e32 v119, 0xbfb8aa3b, v113
	v_mul_f32_e32 v100, v100, v119
	v_mul_f32_e32 v101, v101, v119
	v_mul_f32_e32 v102, v102, v119
	v_mul_f32_e32 v103, v103, v119
	v_mul_f32_e32 v96, v96, v119
	v_mul_f32_e32 v97, v97, v119
	v_mul_f32_e32 v98, v98, v119
	v_mul_f32_e32 v99, v99, v119
	v_exp_f32_e32 v100, v100
	v_exp_f32_e32 v101, v101
	v_exp_f32_e32 v102, v102
	v_exp_f32_e32 v103, v103
	v_exp_f32_e32 v96, v96
	v_exp_f32_e32 v97, v97
	v_exp_f32_e32 v98, v98
	v_exp_f32_e32 v99, v99
	v_mul_f32_e32 v118, v113, v113
	v_add_f32_e32 v100, 1.0, v100
	v_add_f32_e32 v101, 1.0, v101
	v_add_f32_e32 v102, 1.0, v102
	v_add_f32_e32 v103, 1.0, v103
	v_add_f32_e32 v113, 1.0, v96
	v_add_f32_e32 v119, 1.0, v97
	v_add_f32_e32 v124, 1.0, v98
	v_add_f32_e32 v125, 1.0, v99
	v_rcp_f32_e32 v96, v100
	v_rcp_f32_e32 v97, v101
	v_rcp_f32_e32 v98, v102
	v_rcp_f32_e32 v99, v103
	v_rcp_f32_e32 v100, v113
	v_rcp_f32_e32 v101, v119
	v_rcp_f32_e32 v102, v124
	v_rcp_f32_e32 v103, v125
	v_pk_mul_f32 v[96:97], v[118:119], v[96:97] op_sel_hi:[0,1]
	v_pk_mul_f32 v[98:99], v[118:119], v[98:99] op_sel_hi:[0,1]
	v_pk_mul_f32 v[100:101], v[118:119], v[100:101] op_sel_hi:[0,1]
	v_pk_mul_f32 v[102:103], v[118:119], v[102:103] op_sel_hi:[0,1]
	v_pk_mul_f32 v[96:97], v[108:109], v[96:97]
	v_pk_mul_f32 v[98:99], v[110:111], v[98:99]
	v_pk_mul_f32 v[100:101], v[104:105], v[100:101]
	v_pk_mul_f32 v[102:103], v[106:107], v[102:103]
	v_cvt_pk_bf16_f32 v96, v96, v97
	v_cvt_pk_bf16_f32 v97, v98, v99
	v_cvt_pk_bf16_f32 v98, v100, v101
	v_cvt_pk_bf16_f32 v99, v102, v103
	global_store_dwordx4 v[114:115], v[96:99], off
	global_load_dwordx4 v[96:99], v[116:117], off
	s_waitcnt vmcnt(0)
	v_mov_b32_e32 v100, v97
	v_mov_b32_e32 v101, v98
	v_mov_b32_e32 v97, v99
	v_pk_add_f32 v[96:97], v[100:101], v[96:97]
	v_mad_i64_i32 v[98:99], s[0:1], v112, s49, v[150:151]
	v_add_f32_e32 v96, v96, v97
	v_mov_b32_e32 v97, v96
	s_nop 1
	v_permlane16_swap_b32_e32 v96, v97
	v_lshl_add_u64 v[98:99], v[98:99], 0, v[120:121]
	s_waitcnt lgkmcnt(0)
	v_add_f32_e32 v100, v96, v97
	v_mov_b32_e32 v101, v100
	s_nop 1
	v_permlane32_swap_b32_e32 v100, v101
	v_or_b32_e32 v96, 48, v152
	v_ashrrev_i32_e32 v97, 31, v96
	s_waitcnt lgkmcnt(0)
	v_add_f32_e32 v100, v100, v101
	v_fmamk_f32 v100, v100, 0x3a800000, v162
	v_mul_f32_e32 v101, 0x4b800000, v100
	v_cmp_gt_f32_e32 vcc, s52, v100
	s_nop 1
	v_cndmask_b32_e32 v100, v100, v101, vcc
	v_rsq_f32_e32 v102, v100
	v_lshlrev_b64 v[100:101], 6, v[96:97]
	v_lshl_add_u64 v[100:101], v[140:141], 0, v[100:101]
	v_mul_f32_e32 v97, 0x45800000, v102
	v_cndmask_b32_e32 v97, v102, v97, vcc
	v_mul_f32_e32 v103, 0xbfb8aa3b, v97
	v_mul_f32_e32 v84, v84, v103
	v_mul_f32_e32 v85, v85, v103
	v_mul_f32_e32 v86, v86, v103
	v_mul_f32_e32 v87, v87, v103
	v_mul_f32_e32 v80, v80, v103
	v_mul_f32_e32 v81, v81, v103
	v_mul_f32_e32 v82, v82, v103
	v_mul_f32_e32 v83, v83, v103
	v_exp_f32_e32 v84, v84
	v_exp_f32_e32 v85, v85
	v_exp_f32_e32 v86, v86
	v_exp_f32_e32 v87, v87
	v_exp_f32_e32 v80, v80
	v_exp_f32_e32 v81, v81
	v_exp_f32_e32 v82, v82
	v_exp_f32_e32 v83, v83
	v_mul_f32_e32 v102, v97, v97
	v_add_f32_e32 v84, 1.0, v84
	v_add_f32_e32 v85, 1.0, v85
	v_add_f32_e32 v86, 1.0, v86
	v_add_f32_e32 v87, 1.0, v87
	v_add_f32_e32 v97, 1.0, v80
	v_add_f32_e32 v103, 1.0, v81
	v_add_f32_e32 v104, 1.0, v82
	v_add_f32_e32 v105, 1.0, v83
	v_rcp_f32_e32 v80, v84
	v_rcp_f32_e32 v81, v85
	v_rcp_f32_e32 v82, v86
	v_rcp_f32_e32 v83, v87
	v_rcp_f32_e32 v84, v97
	v_rcp_f32_e32 v85, v103
	v_rcp_f32_e32 v86, v104
	v_rcp_f32_e32 v87, v105
	v_pk_mul_f32 v[80:81], v[102:103], v[80:81] op_sel_hi:[0,1]
	v_pk_mul_f32 v[82:83], v[102:103], v[82:83] op_sel_hi:[0,1]
	v_pk_mul_f32 v[84:85], v[102:103], v[84:85] op_sel_hi:[0,1]
	v_pk_mul_f32 v[86:87], v[102:103], v[86:87] op_sel_hi:[0,1]
	v_pk_mul_f32 v[80:81], v[92:93], v[80:81]
	v_pk_mul_f32 v[82:83], v[94:95], v[82:83]
	v_pk_mul_f32 v[84:85], v[88:89], v[84:85]
	v_pk_mul_f32 v[86:87], v[90:91], v[86:87]
	v_cvt_pk_bf16_f32 v80, v80, v81
	v_cvt_pk_bf16_f32 v81, v82, v83
	v_cvt_pk_bf16_f32 v82, v84, v85
	v_cvt_pk_bf16_f32 v83, v86, v87
	global_store_dwordx4 v[98:99], v[80:83], off
	global_load_dwordx4 v[80:83], v[100:101], off
	s_waitcnt vmcnt(0)
	v_mov_b32_e32 v84, v81
	v_mov_b32_e32 v85, v82
	v_mov_b32_e32 v81, v83
	v_pk_add_f32 v[80:81], v[84:85], v[80:81]
	v_mad_i64_i32 v[82:83], s[0:1], v96, s49, v[150:151]
	v_add_f32_e32 v80, v80, v81
	v_mov_b32_e32 v81, v80
	s_nop 1
	v_permlane16_swap_b32_e32 v80, v81
	v_lshl_add_u64 v[82:83], v[82:83], 0, v[120:121]
	s_waitcnt lgkmcnt(0)
	v_add_f32_e32 v84, v80, v81
	v_mov_b32_e32 v85, v84
	s_nop 1
	v_permlane32_swap_b32_e32 v84, v85
	v_add_u32_e32 v80, 0x80, v152
	v_ashrrev_i32_e32 v81, 31, v80
	s_waitcnt lgkmcnt(0)
	v_add_f32_e32 v84, v84, v85
	v_fmamk_f32 v84, v84, 0x3a800000, v162
	v_mul_f32_e32 v85, 0x4b800000, v84
	v_cmp_gt_f32_e32 vcc, s52, v84
	s_nop 1
	v_cndmask_b32_e32 v84, v84, v85, vcc
	v_rsq_f32_e32 v86, v84
	v_lshlrev_b64 v[84:85], 6, v[80:81]
	v_lshl_add_u64 v[84:85], v[140:141], 0, v[84:85]
	v_mul_f32_e32 v81, 0x45800000, v86
	v_cndmask_b32_e32 v81, v86, v81, vcc
	v_mul_f32_e32 v87, 0xbfb8aa3b, v81
	v_mul_f32_e32 v68, v68, v87
	v_mul_f32_e32 v69, v69, v87
	v_mul_f32_e32 v70, v70, v87
	v_mul_f32_e32 v71, v71, v87
	v_mul_f32_e32 v64, v64, v87
	v_mul_f32_e32 v65, v65, v87
	v_mul_f32_e32 v66, v66, v87
	v_mul_f32_e32 v67, v67, v87
	v_exp_f32_e32 v68, v68
	v_exp_f32_e32 v69, v69
	v_exp_f32_e32 v70, v70
	v_exp_f32_e32 v71, v71
	v_exp_f32_e32 v64, v64
	v_exp_f32_e32 v65, v65
	v_exp_f32_e32 v66, v66
	v_exp_f32_e32 v67, v67
	v_mul_f32_e32 v86, v81, v81
	v_add_f32_e32 v68, 1.0, v68
	v_add_f32_e32 v69, 1.0, v69
	v_add_f32_e32 v70, 1.0, v70
	v_add_f32_e32 v71, 1.0, v71
	v_add_f32_e32 v81, 1.0, v64
	v_add_f32_e32 v87, 1.0, v65
	v_add_f32_e32 v88, 1.0, v66
	v_add_f32_e32 v89, 1.0, v67
	v_rcp_f32_e32 v64, v68
	v_rcp_f32_e32 v65, v69
	v_rcp_f32_e32 v66, v70
	v_rcp_f32_e32 v67, v71
	v_rcp_f32_e32 v68, v81
	v_rcp_f32_e32 v69, v87
	v_rcp_f32_e32 v70, v88
	v_rcp_f32_e32 v71, v89
	v_pk_mul_f32 v[64:65], v[86:87], v[64:65] op_sel_hi:[0,1]
	v_pk_mul_f32 v[66:67], v[86:87], v[66:67] op_sel_hi:[0,1]
	v_pk_mul_f32 v[68:69], v[86:87], v[68:69] op_sel_hi:[0,1]
	v_pk_mul_f32 v[70:71], v[86:87], v[70:71] op_sel_hi:[0,1]
	v_pk_mul_f32 v[64:65], v[76:77], v[64:65]
	v_pk_mul_f32 v[66:67], v[78:79], v[66:67]
	v_pk_mul_f32 v[68:69], v[72:73], v[68:69]
	v_pk_mul_f32 v[70:71], v[74:75], v[70:71]
	v_cvt_pk_bf16_f32 v64, v64, v65
	v_cvt_pk_bf16_f32 v65, v66, v67
	v_cvt_pk_bf16_f32 v66, v68, v69
	v_cvt_pk_bf16_f32 v67, v70, v71
	global_store_dwordx4 v[82:83], v[64:67], off
	global_load_dwordx4 v[64:67], v[84:85], off
	s_waitcnt vmcnt(0)
	v_mov_b32_e32 v68, v65
	v_mov_b32_e32 v69, v66
	v_mov_b32_e32 v65, v67
	v_pk_add_f32 v[64:65], v[68:69], v[64:65]
	v_mad_i64_i32 v[66:67], s[0:1], v80, s49, v[150:151]
	v_add_f32_e32 v64, v64, v65
	v_mov_b32_e32 v65, v64
	s_nop 1
	v_permlane16_swap_b32_e32 v64, v65
	v_lshl_add_u64 v[66:67], v[66:67], 0, v[120:121]
	s_waitcnt lgkmcnt(0)
	v_add_f32_e32 v68, v64, v65
	v_mov_b32_e32 v69, v68
	s_nop 1
	v_permlane32_swap_b32_e32 v68, v69
	v_add_u32_e32 v64, 0x90, v152
	v_ashrrev_i32_e32 v65, 31, v64
	s_waitcnt lgkmcnt(0)
	v_add_f32_e32 v68, v68, v69
	v_fmamk_f32 v68, v68, 0x3a800000, v162
	v_mul_f32_e32 v69, 0x4b800000, v68
	v_cmp_gt_f32_e32 vcc, s52, v68
	s_nop 1
	v_cndmask_b32_e32 v68, v68, v69, vcc
	v_rsq_f32_e32 v70, v68
	v_lshlrev_b64 v[68:69], 6, v[64:65]
	v_lshl_add_u64 v[68:69], v[140:141], 0, v[68:69]
	v_mul_f32_e32 v65, 0x45800000, v70
	v_cndmask_b32_e32 v65, v70, v65, vcc
	v_mul_f32_e32 v71, 0xbfb8aa3b, v65
	v_mul_f32_e32 v52, v52, v71
	v_mul_f32_e32 v53, v53, v71
	v_mul_f32_e32 v54, v54, v71
	v_mul_f32_e32 v55, v55, v71
	v_mul_f32_e32 v48, v48, v71
	v_mul_f32_e32 v49, v49, v71
	v_mul_f32_e32 v50, v50, v71
	v_mul_f32_e32 v51, v51, v71
	v_exp_f32_e32 v52, v52
	v_exp_f32_e32 v53, v53
	v_exp_f32_e32 v54, v54
	v_exp_f32_e32 v55, v55
	v_exp_f32_e32 v48, v48
	v_exp_f32_e32 v49, v49
	v_exp_f32_e32 v50, v50
	v_exp_f32_e32 v51, v51
	v_mul_f32_e32 v70, v65, v65
	v_add_f32_e32 v52, 1.0, v52
	v_add_f32_e32 v53, 1.0, v53
	v_add_f32_e32 v54, 1.0, v54
	v_add_f32_e32 v55, 1.0, v55
	v_add_f32_e32 v65, 1.0, v48
	v_add_f32_e32 v71, 1.0, v49
	v_add_f32_e32 v72, 1.0, v50
	v_add_f32_e32 v73, 1.0, v51
	v_rcp_f32_e32 v48, v52
	v_rcp_f32_e32 v49, v53
	v_rcp_f32_e32 v50, v54
	v_rcp_f32_e32 v51, v55
	v_rcp_f32_e32 v52, v65
	v_rcp_f32_e32 v53, v71
	v_rcp_f32_e32 v54, v72
	v_rcp_f32_e32 v55, v73
	v_pk_mul_f32 v[48:49], v[70:71], v[48:49] op_sel_hi:[0,1]
	v_pk_mul_f32 v[50:51], v[70:71], v[50:51] op_sel_hi:[0,1]
	v_pk_mul_f32 v[52:53], v[70:71], v[52:53] op_sel_hi:[0,1]
	v_pk_mul_f32 v[54:55], v[70:71], v[54:55] op_sel_hi:[0,1]
	v_pk_mul_f32 v[48:49], v[60:61], v[48:49]
	v_pk_mul_f32 v[50:51], v[62:63], v[50:51]
	v_pk_mul_f32 v[52:53], v[56:57], v[52:53]
	v_pk_mul_f32 v[54:55], v[58:59], v[54:55]
	v_cvt_pk_bf16_f32 v48, v48, v49
	v_cvt_pk_bf16_f32 v49, v50, v51
	v_cvt_pk_bf16_f32 v50, v52, v53
	v_cvt_pk_bf16_f32 v51, v54, v55
	global_store_dwordx4 v[66:67], v[48:51], off
	global_load_dwordx4 v[48:51], v[68:69], off
	s_waitcnt vmcnt(0)
	v_mov_b32_e32 v52, v49
	v_mov_b32_e32 v53, v50
	v_mov_b32_e32 v49, v51
	v_pk_add_f32 v[48:49], v[52:53], v[48:49]
	v_mad_i64_i32 v[50:51], s[0:1], v64, s49, v[150:151]
	v_add_f32_e32 v48, v48, v49
	v_mov_b32_e32 v49, v48
	s_nop 1
	v_permlane16_swap_b32_e32 v48, v49
	v_lshl_add_u64 v[50:51], v[50:51], 0, v[120:121]
	s_waitcnt lgkmcnt(0)
	v_add_f32_e32 v52, v48, v49
	v_mov_b32_e32 v53, v52
	s_nop 1
	v_permlane32_swap_b32_e32 v52, v53
	v_add_u32_e32 v48, 0xa0, v152
	v_ashrrev_i32_e32 v49, 31, v48
	s_waitcnt lgkmcnt(0)
	v_add_f32_e32 v52, v52, v53
	v_fmamk_f32 v52, v52, 0x3a800000, v162
	v_mul_f32_e32 v53, 0x4b800000, v52
	v_cmp_gt_f32_e32 vcc, s52, v52
	s_nop 1
	v_cndmask_b32_e32 v52, v52, v53, vcc
	v_rsq_f32_e32 v54, v52
	v_lshlrev_b64 v[52:53], 6, v[48:49]
	v_lshl_add_u64 v[52:53], v[140:141], 0, v[52:53]
	v_mul_f32_e32 v49, 0x45800000, v54
	v_cndmask_b32_e32 v49, v54, v49, vcc
	v_mul_f32_e32 v55, 0xbfb8aa3b, v49
	v_mul_f32_e32 v36, v36, v55
	v_mul_f32_e32 v37, v37, v55
	v_mul_f32_e32 v38, v38, v55
	v_mul_f32_e32 v39, v39, v55
	v_mul_f32_e32 v32, v32, v55
	v_mul_f32_e32 v33, v33, v55
	v_mul_f32_e32 v34, v34, v55
	v_mul_f32_e32 v35, v35, v55
	v_exp_f32_e32 v36, v36
	v_exp_f32_e32 v37, v37
	v_exp_f32_e32 v38, v38
	v_exp_f32_e32 v39, v39
	v_exp_f32_e32 v32, v32
	v_exp_f32_e32 v33, v33
	v_exp_f32_e32 v34, v34
	v_exp_f32_e32 v35, v35
	v_mul_f32_e32 v54, v49, v49
	v_add_f32_e32 v36, 1.0, v36
	v_add_f32_e32 v37, 1.0, v37
	v_add_f32_e32 v38, 1.0, v38
	v_add_f32_e32 v39, 1.0, v39
	v_add_f32_e32 v49, 1.0, v32
	v_add_f32_e32 v55, 1.0, v33
	v_add_f32_e32 v56, 1.0, v34
	v_add_f32_e32 v57, 1.0, v35
	v_rcp_f32_e32 v32, v36
	v_rcp_f32_e32 v33, v37
	v_rcp_f32_e32 v34, v38
	v_rcp_f32_e32 v35, v39
	v_rcp_f32_e32 v36, v49
	v_rcp_f32_e32 v37, v55
	v_rcp_f32_e32 v38, v56
	v_rcp_f32_e32 v39, v57
	v_pk_mul_f32 v[32:33], v[54:55], v[32:33] op_sel_hi:[0,1]
	v_pk_mul_f32 v[34:35], v[54:55], v[34:35] op_sel_hi:[0,1]
	v_pk_mul_f32 v[36:37], v[54:55], v[36:37] op_sel_hi:[0,1]
	v_pk_mul_f32 v[38:39], v[54:55], v[38:39] op_sel_hi:[0,1]
	v_pk_mul_f32 v[32:33], v[44:45], v[32:33]
	v_pk_mul_f32 v[34:35], v[46:47], v[34:35]
	v_pk_mul_f32 v[36:37], v[40:41], v[36:37]
	v_pk_mul_f32 v[38:39], v[42:43], v[38:39]
	v_cvt_pk_bf16_f32 v32, v32, v33
	v_cvt_pk_bf16_f32 v33, v34, v35
	v_cvt_pk_bf16_f32 v34, v36, v37
	v_cvt_pk_bf16_f32 v35, v38, v39
	global_store_dwordx4 v[50:51], v[32:35], off
	global_load_dwordx4 v[32:35], v[52:53], off
	s_waitcnt vmcnt(0)
	v_mov_b32_e32 v36, v33
	v_mov_b32_e32 v37, v34
	v_mov_b32_e32 v33, v35
	v_pk_add_f32 v[32:33], v[36:37], v[32:33]
	v_mad_i64_i32 v[34:35], s[0:1], v48, s49, v[150:151]
	v_add_f32_e32 v32, v32, v33
	v_mov_b32_e32 v33, v32
	s_nop 1
	v_permlane16_swap_b32_e32 v32, v33
	v_lshl_add_u64 v[34:35], v[34:35], 0, v[120:121]
	s_waitcnt lgkmcnt(0)
	v_add_f32_e32 v36, v32, v33
	v_mov_b32_e32 v37, v36
	s_nop 1
	v_permlane32_swap_b32_e32 v36, v37
	v_add_u32_e32 v32, 0xb0, v152
	v_ashrrev_i32_e32 v33, 31, v32
	s_waitcnt lgkmcnt(0)
	v_add_f32_e32 v36, v36, v37
	v_fmamk_f32 v36, v36, 0x3a800000, v162
	v_mul_f32_e32 v37, 0x4b800000, v36
	v_cmp_gt_f32_e32 vcc, s52, v36
	s_nop 1
	v_cndmask_b32_e32 v36, v36, v37, vcc
	v_rsq_f32_e32 v38, v36
	v_lshlrev_b64 v[36:37], 6, v[32:33]
	v_lshl_add_u64 v[36:37], v[140:141], 0, v[36:37]
	v_mul_f32_e32 v33, 0x45800000, v38
	v_cndmask_b32_e32 v33, v38, v33, vcc
	v_mul_f32_e32 v39, 0xbfb8aa3b, v33
	v_mul_f32_e32 v20, v20, v39
	v_mul_f32_e32 v21, v21, v39
	v_mul_f32_e32 v22, v22, v39
	v_mul_f32_e32 v23, v23, v39
	v_mul_f32_e32 v16, v16, v39
	v_mul_f32_e32 v17, v17, v39
	v_mul_f32_e32 v18, v18, v39
	v_mul_f32_e32 v19, v19, v39
	v_exp_f32_e32 v20, v20
	v_exp_f32_e32 v21, v21
	v_exp_f32_e32 v22, v22
	v_exp_f32_e32 v23, v23
	v_exp_f32_e32 v16, v16
	v_exp_f32_e32 v17, v17
	v_exp_f32_e32 v18, v18
	v_exp_f32_e32 v19, v19
	v_mul_f32_e32 v38, v33, v33
	v_add_f32_e32 v20, 1.0, v20
	v_add_f32_e32 v21, 1.0, v21
	v_add_f32_e32 v22, 1.0, v22
	v_add_f32_e32 v23, 1.0, v23
	v_add_f32_e32 v33, 1.0, v16
	v_add_f32_e32 v39, 1.0, v17
	v_add_f32_e32 v40, 1.0, v18
	v_add_f32_e32 v41, 1.0, v19
	v_rcp_f32_e32 v16, v20
	v_rcp_f32_e32 v17, v21
	v_rcp_f32_e32 v18, v22
	v_rcp_f32_e32 v19, v23
	v_rcp_f32_e32 v20, v33
	v_rcp_f32_e32 v21, v39
	v_rcp_f32_e32 v22, v40
	v_rcp_f32_e32 v23, v41
	v_pk_mul_f32 v[16:17], v[38:39], v[16:17] op_sel_hi:[0,1]
	v_pk_mul_f32 v[18:19], v[38:39], v[18:19] op_sel_hi:[0,1]
	v_pk_mul_f32 v[20:21], v[38:39], v[20:21] op_sel_hi:[0,1]
	v_pk_mul_f32 v[22:23], v[38:39], v[22:23] op_sel_hi:[0,1]
	v_pk_mul_f32 v[16:17], v[28:29], v[16:17]
	v_pk_mul_f32 v[18:19], v[30:31], v[18:19]
	v_pk_mul_f32 v[20:21], v[24:25], v[20:21]
	v_pk_mul_f32 v[22:23], v[26:27], v[22:23]
	v_cvt_pk_bf16_f32 v16, v16, v17
	v_cvt_pk_bf16_f32 v17, v18, v19
	v_cvt_pk_bf16_f32 v18, v20, v21
	v_cvt_pk_bf16_f32 v19, v22, v23
	global_store_dwordx4 v[34:35], v[16:19], off
	global_load_dwordx4 v[16:19], v[36:37], off
	s_andn2_b64 vcc, exec, s[4:5]
	s_waitcnt vmcnt(0)
	v_mov_b32_e32 v20, v17
	v_mov_b32_e32 v21, v18
	v_mov_b32_e32 v17, v19
	v_pk_add_f32 v[16:17], v[20:21], v[16:17]
	s_nop 0
	v_add_f32_e32 v16, v16, v17
	v_mov_b32_e32 v17, v16
	s_nop 1
	v_permlane16_swap_b32_e32 v16, v17
	s_waitcnt lgkmcnt(0)
	v_add_f32_e32 v16, v16, v17
	v_mov_b32_e32 v17, v16
	s_nop 1
	v_permlane32_swap_b32_e32 v16, v17
	s_waitcnt lgkmcnt(0)
	v_add_f32_e32 v16, v16, v17
	v_fmamk_f32 v16, v16, 0x3a800000, v162
	v_mul_f32_e32 v17, 0x4b800000, v16
	v_cmp_gt_f32_e64 s[0:1], s52, v16
	s_nop 1
	v_cndmask_b32_e64 v16, v16, v17, s[0:1]
	v_rsq_f32_e32 v18, v16
	v_mad_i64_i32 v[16:17], s[24:25], v32, s49, v[150:151]
	v_lshl_add_u64 v[16:17], v[16:17], 0, v[120:121]
	v_mul_f32_e32 v19, 0x45800000, v18
	v_cndmask_b32_e64 v18, v18, v19, s[0:1]
	v_mul_f32_e32 v19, 0xbfb8aa3b, v18
	v_mul_f32_e32 v4, v4, v19
	v_mul_f32_e32 v5, v5, v19
	v_mul_f32_e32 v6, v6, v19
	v_mul_f32_e32 v7, v7, v19
	v_mul_f32_e32 v0, v0, v19
	v_mul_f32_e32 v1, v1, v19
	v_mul_f32_e32 v2, v2, v19
	v_mul_f32_e32 v3, v3, v19
	v_exp_f32_e32 v4, v4
	v_exp_f32_e32 v5, v5
	v_exp_f32_e32 v6, v6
	v_exp_f32_e32 v7, v7
	v_exp_f32_e32 v0, v0
	v_exp_f32_e32 v1, v1
	v_exp_f32_e32 v2, v2
	v_exp_f32_e32 v3, v3
	v_add_f32_e32 v4, 1.0, v4
	v_add_f32_e32 v5, 1.0, v5
	v_add_f32_e32 v6, 1.0, v6
	v_add_f32_e32 v7, 1.0, v7
	v_add_f32_e32 v19, 1.0, v0
	v_add_f32_e32 v20, 1.0, v1
	v_add_f32_e32 v21, 1.0, v2
	v_add_f32_e32 v22, 1.0, v3
	v_rcp_f32_e32 v0, v4
	v_rcp_f32_e32 v1, v5
	v_rcp_f32_e32 v2, v6
	v_rcp_f32_e32 v3, v7
	v_rcp_f32_e32 v4, v19
	v_rcp_f32_e32 v5, v20
	v_rcp_f32_e32 v6, v21
	v_rcp_f32_e32 v7, v22
	v_mul_f32_e32 v18, v18, v18
	v_pk_mul_f32 v[0:1], v[18:19], v[0:1] op_sel_hi:[0,1]
	v_pk_mul_f32 v[2:3], v[18:19], v[2:3] op_sel_hi:[0,1]
	v_pk_mul_f32 v[4:5], v[18:19], v[4:5] op_sel_hi:[0,1]
	v_pk_mul_f32 v[6:7], v[18:19], v[6:7] op_sel_hi:[0,1]
	v_pk_mul_f32 v[0:1], v[12:13], v[0:1]
	v_pk_mul_f32 v[2:3], v[14:15], v[2:3]
	v_pk_mul_f32 v[4:5], v[8:9], v[4:5]
	v_pk_mul_f32 v[6:7], v[10:11], v[6:7]
	v_cvt_pk_bf16_f32 v0, v0, v1
	v_cvt_pk_bf16_f32 v1, v2, v3
	v_cvt_pk_bf16_f32 v2, v4, v5
	v_cvt_pk_bf16_f32 v3, v6, v7
	s_mov_b64 s[0:1], -1
	global_store_dwordx4 v[16:17], v[0:3], off
	s_cbranch_vccnz .LBB0_620
	s_andn2_b64 vcc, exec, s[8:9]
	s_cbranch_vccnz .LBB0_619
	s_barrier
	s_branch .LBB0_619

.LBB0_712:
	v_lshl_add_u32 v150, s53, 8, v152
	v_ashrrev_i32_e32 v151, 31, v150
	v_lshl_or_b32 v148, s10, 8, v154
	v_lshlrev_b64 v[160:161], 11, v[150:151]
	v_ashrrev_i32_e32 v149, 31, v148
	v_lshl_add_u64 v[160:161], s[14:15], 0, v[160:161]
	v_lshl_add_u64 v[170:171], v[148:149], 1, v[160:161]
	global_load_dwordx4 v[162:165], v[170:171], off
	global_load_dwordx4 v[166:169], v[170:171], off offset:256
	v_and_b32_e32 v161, 64, v159
	v_xor_b32_e32 v160, 16, v159
	v_add_u32_e32 v161, 64, v161
	v_xor_b32_e32 v172, 32, v159
	v_cmp_lt_i32_e32 vcc, v160, v161
	s_lshl_b32 s24, s10, 2
	s_ashr_i32 s25, s24, 31
	v_cndmask_b32_e32 v160, v159, v160, vcc
	v_cmp_lt_i32_e32 vcc, v172, v161
	v_lshlrev_b32_e32 v161, 2, v160
	s_waitcnt vmcnt(0)
	v_and_b32_e32 v173, 0xffff0000, v162
	v_cndmask_b32_e32 v172, v159, v172, vcc
	v_lshlrev_b32_e32 v160, 2, v172
	v_lshlrev_b32_e32 v172, 16, v162
	v_lshlrev_b32_e32 v162, 16, v163
	v_and_b32_e32 v163, 0xffff0000, v163
	v_lshlrev_b32_e32 v174, 16, v164
	v_and_b32_e32 v175, 0xffff0000, v164
	v_lshlrev_b32_e32 v164, 16, v165
	v_and_b32_e32 v165, 0xffff0000, v165
	v_lshlrev_b32_e32 v176, 16, v166
	v_and_b32_e32 v177, 0xffff0000, v166
	v_lshlrev_b32_e32 v166, 16, v167
	v_and_b32_e32 v167, 0xffff0000, v167
	v_lshlrev_b32_e32 v178, 16, v168
	v_and_b32_e32 v179, 0xffff0000, v168
	v_lshlrev_b32_e32 v168, 16, v169
	v_and_b32_e32 v169, 0xffff0000, v169
	v_pk_add_f32 v[124:125], v[124:125], v[172:173]
	v_pk_add_f32 v[126:127], v[126:127], v[162:163]
	v_pk_add_f32 v[120:121], v[120:121], v[174:175]
	v_pk_add_f32 v[122:123], v[122:123], v[164:165]
	v_pk_add_f32 v[116:117], v[116:117], v[176:177]
	v_pk_add_f32 v[118:119], v[118:119], v[166:167]
	v_pk_add_f32 v[162:163], v[112:113], v[178:179]
	v_pk_add_f32 v[164:165], v[114:115], v[168:169]
	v_cvt_pk_bf16_f32 v112, v124, v125
	v_cvt_pk_bf16_f32 v113, v126, v127
	v_pk_mul_f32 v[114:115], v[124:125], v[124:125]
	v_pk_mul_f32 v[124:125], v[126:127], v[126:127]
	v_pk_mul_f32 v[126:127], v[120:121], v[120:121]
	v_pk_mul_f32 v[166:167], v[122:123], v[122:123]
	v_pk_mul_f32 v[168:169], v[116:117], v[116:117]
	v_pk_mul_f32 v[172:173], v[118:119], v[118:119]
	v_pk_mul_f32 v[174:175], v[162:163], v[162:163]
	v_pk_mul_f32 v[176:177], v[164:165], v[164:165]
	v_add_f32_e32 v174, v174, v175
	v_add_f32_e32 v176, v176, v177
	v_add_f32_e32 v172, v172, v173
	v_add_f32_e32 v168, v168, v169
	v_add_f32_e32 v166, v166, v167
	v_add_f32_e32 v126, v126, v127
	v_add_f32_e32 v124, v124, v125
	v_add_f32_e32 v114, v114, v115
	v_add_f32_e32 v115, v174, v176
	v_add_f32_e32 v125, v168, v172
	v_add_f32_e32 v126, v126, v166
	v_add_f32_e32 v114, v114, v124
	v_add_f32_e32 v115, v125, v115
	v_add_f32_e32 v114, v114, v126
	v_add_f32_e32 v124, v114, v115
	v_mov_b32_e32 v125, v124
	s_nop 1
	v_permlane16_swap_b32_e32 v124, v125
	v_cvt_pk_bf16_f32 v114, v120, v121
	v_cvt_pk_bf16_f32 v115, v122, v123
	global_store_dwordx4 v[170:171], v[112:115], off
	s_waitcnt lgkmcnt(0)
	s_nop 0
	v_add_f32_e32 v112, v124, v125
	v_mov_b32_e32 v113, v112
	s_nop 1
	v_permlane32_swap_b32_e32 v112, v113
	v_cvt_pk_bf16_f32 v114, v116, v117
	v_cvt_pk_bf16_f32 v115, v118, v119
	v_cvt_pk_bf16_f32 v116, v162, v163
	v_cvt_pk_bf16_f32 v117, v164, v165
	global_store_dwordx4 v[170:171], v[114:117], off offset:256
	s_and_saveexec_b64 s[26:27], s[4:5]
	s_cbranch_execz .LBB0_714
	v_lshlrev_b64 v[114:115], 6, v[150:151]
	v_lshl_add_u64 v[114:115], s[16:17], 0, v[114:115]
	v_lshl_add_u64 v[114:115], s[24:25], 2, v[114:115]
	s_lshl_b32 s10, s40, 2
	v_lshl_add_u64 v[114:115], v[114:115], 0, s[10:11]
	s_waitcnt lgkmcnt(0)
	v_add_f32_e32 v112, v112, v113
	global_store_dword v[114:115], v112, off
.LBB0_714:
	s_or_b64 exec, exec, s[26:27]
	v_or_b32_e32 v112, 16, v150
	s_waitcnt lgkmcnt(0)
	v_ashrrev_i32_e32 v113, 31, v112
	v_lshlrev_b64 v[114:115], 11, v[112:113]
	v_lshl_add_u64 v[114:115], s[14:15], 0, v[114:115]
	v_lshl_add_u64 v[122:123], v[148:149], 1, v[114:115]
	global_load_dwordx4 v[114:117], v[122:123], off
	global_load_dwordx4 v[118:121], v[122:123], off offset:256
	s_waitcnt vmcnt(1)
	v_lshlrev_b32_e32 v124, 16, v114
	v_and_b32_e32 v125, 0xffff0000, v114
	v_lshlrev_b32_e32 v114, 16, v115
	v_and_b32_e32 v115, 0xffff0000, v115
	v_lshlrev_b32_e32 v126, 16, v116
	v_and_b32_e32 v127, 0xffff0000, v116
	v_lshlrev_b32_e32 v116, 16, v117
	v_and_b32_e32 v117, 0xffff0000, v117
	s_waitcnt vmcnt(0)
	v_lshlrev_b32_e32 v162, 16, v118
	v_and_b32_e32 v163, 0xffff0000, v118
	v_lshlrev_b32_e32 v118, 16, v119
	v_and_b32_e32 v119, 0xffff0000, v119
	v_lshlrev_b32_e32 v164, 16, v120
	v_and_b32_e32 v165, 0xffff0000, v120
	v_lshlrev_b32_e32 v120, 16, v121
	v_and_b32_e32 v121, 0xffff0000, v121
	v_pk_add_f32 v[108:109], v[108:109], v[124:125]
	v_pk_add_f32 v[110:111], v[110:111], v[114:115]
	v_pk_add_f32 v[104:105], v[104:105], v[126:127]
	v_pk_add_f32 v[106:107], v[106:107], v[116:117]
	v_pk_add_f32 v[100:101], v[100:101], v[162:163]
	v_pk_add_f32 v[102:103], v[102:103], v[118:119]
	v_pk_add_f32 v[114:115], v[96:97], v[164:165]
	v_pk_add_f32 v[116:117], v[98:99], v[120:121]
	v_cvt_pk_bf16_f32 v96, v108, v109
	v_cvt_pk_bf16_f32 v97, v110, v111
	v_pk_mul_f32 v[98:99], v[108:109], v[108:109]
	v_pk_mul_f32 v[108:109], v[110:111], v[110:111]
	v_pk_mul_f32 v[110:111], v[104:105], v[104:105]
	v_pk_mul_f32 v[118:119], v[106:107], v[106:107]
	v_pk_mul_f32 v[120:121], v[100:101], v[100:101]
	v_pk_mul_f32 v[124:125], v[102:103], v[102:103]
	v_pk_mul_f32 v[126:127], v[114:115], v[114:115]
	v_pk_mul_f32 v[162:163], v[116:117], v[116:117]
	v_add_f32_e32 v126, v126, v127
	v_add_f32_e32 v151, v162, v163
	v_add_f32_e32 v124, v124, v125
	v_add_f32_e32 v120, v120, v121
	v_add_f32_e32 v118, v118, v119
	v_add_f32_e32 v110, v110, v111
	v_add_f32_e32 v108, v108, v109
	v_add_f32_e32 v98, v98, v99
	v_add_f32_e32 v99, v126, v151
	v_add_f32_e32 v109, v120, v124
	v_add_f32_e32 v110, v110, v118
	v_add_f32_e32 v98, v98, v108
	v_add_f32_e32 v99, v109, v99
	v_add_f32_e32 v98, v98, v110
	v_add_f32_e32 v108, v98, v99
	v_mov_b32_e32 v109, v108
	s_nop 1
	v_permlane16_swap_b32_e32 v108, v109
	v_cvt_pk_bf16_f32 v98, v104, v105
	v_cvt_pk_bf16_f32 v99, v106, v107
	global_store_dwordx4 v[122:123], v[96:99], off
	s_waitcnt lgkmcnt(0)
	s_nop 0
	v_add_f32_e32 v96, v108, v109
	v_mov_b32_e32 v97, v96
	s_nop 1
	v_permlane32_swap_b32_e32 v96, v97
	v_cvt_pk_bf16_f32 v98, v100, v101
	v_cvt_pk_bf16_f32 v99, v102, v103
	v_cvt_pk_bf16_f32 v100, v114, v115
	v_cvt_pk_bf16_f32 v101, v116, v117
	global_store_dwordx4 v[122:123], v[98:101], off offset:256
	s_and_saveexec_b64 s[26:27], s[4:5]
	s_cbranch_execz .LBB0_716
	v_lshlrev_b64 v[98:99], 6, v[112:113]
	v_lshl_add_u64 v[98:99], s[16:17], 0, v[98:99]
	v_lshl_add_u64 v[98:99], s[24:25], 2, v[98:99]
	s_lshl_b32 s10, s40, 2
	v_lshl_add_u64 v[98:99], v[98:99], 0, s[10:11]
	s_waitcnt lgkmcnt(0)
	v_add_f32_e32 v96, v96, v97
	global_store_dword v[98:99], v96, off
.LBB0_716:
	s_or_b64 exec, exec, s[26:27]
	v_or_b32_e32 v96, 32, v150
	s_waitcnt lgkmcnt(0)
	v_ashrrev_i32_e32 v97, 31, v96
	v_lshlrev_b64 v[98:99], 11, v[96:97]
	v_lshl_add_u64 v[98:99], s[14:15], 0, v[98:99]
	v_lshl_add_u64 v[106:107], v[148:149], 1, v[98:99]
	global_load_dwordx4 v[98:101], v[106:107], off
	global_load_dwordx4 v[102:105], v[106:107], off offset:256
	s_waitcnt vmcnt(1)
	v_lshlrev_b32_e32 v108, 16, v98
	v_and_b32_e32 v109, 0xffff0000, v98
	v_lshlrev_b32_e32 v98, 16, v99
	v_and_b32_e32 v99, 0xffff0000, v99
	v_lshlrev_b32_e32 v110, 16, v100
	v_and_b32_e32 v111, 0xffff0000, v100
	v_lshlrev_b32_e32 v100, 16, v101
	v_and_b32_e32 v101, 0xffff0000, v101
	s_waitcnt vmcnt(0)
	v_lshlrev_b32_e32 v112, 16, v102
	v_and_b32_e32 v113, 0xffff0000, v102
	v_lshlrev_b32_e32 v102, 16, v103
	v_and_b32_e32 v103, 0xffff0000, v103
	v_lshlrev_b32_e32 v114, 16, v104
	v_and_b32_e32 v115, 0xffff0000, v104
	v_lshlrev_b32_e32 v104, 16, v105
	v_and_b32_e32 v105, 0xffff0000, v105
	v_pk_add_f32 v[92:93], v[92:93], v[108:109]
	v_pk_add_f32 v[94:95], v[94:95], v[98:99]
	v_pk_add_f32 v[88:89], v[88:89], v[110:111]
	v_pk_add_f32 v[90:91], v[90:91], v[100:101]
	v_pk_add_f32 v[84:85], v[84:85], v[112:113]
	v_pk_add_f32 v[86:87], v[86:87], v[102:103]
	v_pk_add_f32 v[98:99], v[80:81], v[114:115]
	v_pk_add_f32 v[100:101], v[82:83], v[104:105]
	v_cvt_pk_bf16_f32 v80, v92, v93
	v_cvt_pk_bf16_f32 v81, v94, v95
	v_pk_mul_f32 v[82:83], v[92:93], v[92:93]
	v_pk_mul_f32 v[92:93], v[94:95], v[94:95]
	v_pk_mul_f32 v[94:95], v[88:89], v[88:89]
	v_pk_mul_f32 v[102:103], v[90:91], v[90:91]
	v_pk_mul_f32 v[104:105], v[84:85], v[84:85]
	v_pk_mul_f32 v[108:109], v[86:87], v[86:87]
	v_pk_mul_f32 v[110:111], v[98:99], v[98:99]
	v_pk_mul_f32 v[112:113], v[100:101], v[100:101]
	v_add_f32_e32 v110, v110, v111
	v_add_f32_e32 v112, v112, v113
	v_add_f32_e32 v108, v108, v109
	v_add_f32_e32 v104, v104, v105
	v_add_f32_e32 v102, v102, v103
	v_add_f32_e32 v94, v94, v95
	v_add_f32_e32 v92, v92, v93
	v_add_f32_e32 v82, v82, v83
	v_add_f32_e32 v83, v110, v112
	v_add_f32_e32 v93, v104, v108
	v_add_f32_e32 v94, v94, v102
	v_add_f32_e32 v82, v82, v92
	v_add_f32_e32 v83, v93, v83
	v_add_f32_e32 v82, v82, v94
	v_add_f32_e32 v92, v82, v83
	v_mov_b32_e32 v93, v92
	s_nop 1
	v_permlane16_swap_b32_e32 v92, v93
	v_cvt_pk_bf16_f32 v82, v88, v89
	v_cvt_pk_bf16_f32 v83, v90, v91
	global_store_dwordx4 v[106:107], v[80:83], off
	s_waitcnt lgkmcnt(0)
	s_nop 0
	v_add_f32_e32 v80, v92, v93
	v_mov_b32_e32 v81, v80
	s_nop 1
	v_permlane32_swap_b32_e32 v80, v81
	v_cvt_pk_bf16_f32 v82, v84, v85
	v_cvt_pk_bf16_f32 v83, v86, v87
	v_cvt_pk_bf16_f32 v84, v98, v99
	v_cvt_pk_bf16_f32 v85, v100, v101
	global_store_dwordx4 v[106:107], v[82:85], off offset:256
	s_and_saveexec_b64 s[26:27], s[4:5]
	s_cbranch_execz .LBB0_718
	v_lshlrev_b64 v[82:83], 6, v[96:97]
	v_lshl_add_u64 v[82:83], s[16:17], 0, v[82:83]
	v_lshl_add_u64 v[82:83], s[24:25], 2, v[82:83]
	s_lshl_b32 s10, s40, 2
	v_lshl_add_u64 v[82:83], v[82:83], 0, s[10:11]
	s_waitcnt lgkmcnt(0)
	v_add_f32_e32 v80, v80, v81
	global_store_dword v[82:83], v80, off
.LBB0_718:
	s_or_b64 exec, exec, s[26:27]
	v_or_b32_e32 v80, 48, v150
	s_waitcnt lgkmcnt(0)
	v_ashrrev_i32_e32 v81, 31, v80
	v_lshlrev_b64 v[82:83], 11, v[80:81]
	v_lshl_add_u64 v[82:83], s[14:15], 0, v[82:83]
	v_lshl_add_u64 v[90:91], v[148:149], 1, v[82:83]
	global_load_dwordx4 v[82:85], v[90:91], off
	global_load_dwordx4 v[86:89], v[90:91], off offset:256
	s_waitcnt vmcnt(1)
	v_lshlrev_b32_e32 v92, 16, v82
	v_and_b32_e32 v93, 0xffff0000, v82
	v_lshlrev_b32_e32 v82, 16, v83
	v_and_b32_e32 v83, 0xffff0000, v83
	v_lshlrev_b32_e32 v94, 16, v84
	v_and_b32_e32 v95, 0xffff0000, v84
	v_lshlrev_b32_e32 v84, 16, v85
	v_and_b32_e32 v85, 0xffff0000, v85
	s_waitcnt vmcnt(0)
	v_lshlrev_b32_e32 v96, 16, v86
	v_and_b32_e32 v97, 0xffff0000, v86
	v_lshlrev_b32_e32 v86, 16, v87
	v_and_b32_e32 v87, 0xffff0000, v87
	v_lshlrev_b32_e32 v98, 16, v88
	v_and_b32_e32 v99, 0xffff0000, v88
	v_lshlrev_b32_e32 v88, 16, v89
	v_and_b32_e32 v89, 0xffff0000, v89
	v_pk_add_f32 v[76:77], v[76:77], v[92:93]
	v_pk_add_f32 v[78:79], v[78:79], v[82:83]
	v_pk_add_f32 v[72:73], v[72:73], v[94:95]
	v_pk_add_f32 v[74:75], v[74:75], v[84:85]
	v_pk_add_f32 v[68:69], v[68:69], v[96:97]
	v_pk_add_f32 v[70:71], v[70:71], v[86:87]
	v_pk_add_f32 v[82:83], v[64:65], v[98:99]
	v_pk_add_f32 v[84:85], v[66:67], v[88:89]
	v_cvt_pk_bf16_f32 v64, v76, v77
	v_cvt_pk_bf16_f32 v65, v78, v79
	v_pk_mul_f32 v[66:67], v[76:77], v[76:77]
	v_pk_mul_f32 v[76:77], v[78:79], v[78:79]
	v_pk_mul_f32 v[78:79], v[72:73], v[72:73]
	v_pk_mul_f32 v[86:87], v[74:75], v[74:75]
	v_pk_mul_f32 v[88:89], v[68:69], v[68:69]
	v_pk_mul_f32 v[92:93], v[70:71], v[70:71]
	v_pk_mul_f32 v[94:95], v[82:83], v[82:83]
	v_pk_mul_f32 v[96:97], v[84:85], v[84:85]
	v_add_f32_e32 v94, v94, v95
	v_add_f32_e32 v96, v96, v97
	v_add_f32_e32 v92, v92, v93
	v_add_f32_e32 v88, v88, v89
	v_add_f32_e32 v86, v86, v87
	v_add_f32_e32 v78, v78, v79
	v_add_f32_e32 v76, v76, v77
	v_add_f32_e32 v66, v66, v67
	v_add_f32_e32 v67, v94, v96
	v_add_f32_e32 v77, v88, v92
	v_add_f32_e32 v78, v78, v86
	v_add_f32_e32 v66, v66, v76
	v_add_f32_e32 v67, v77, v67
	v_add_f32_e32 v66, v66, v78
	v_add_f32_e32 v76, v66, v67
	v_mov_b32_e32 v77, v76
	s_nop 1
	v_permlane16_swap_b32_e32 v76, v77
	v_cvt_pk_bf16_f32 v66, v72, v73
	v_cvt_pk_bf16_f32 v67, v74, v75
	global_store_dwordx4 v[90:91], v[64:67], off
	s_waitcnt lgkmcnt(0)
	s_nop 0
	v_add_f32_e32 v64, v76, v77
	v_mov_b32_e32 v65, v64
	s_nop 1
	v_permlane32_swap_b32_e32 v64, v65
	v_cvt_pk_bf16_f32 v66, v68, v69
	v_cvt_pk_bf16_f32 v67, v70, v71
	v_cvt_pk_bf16_f32 v68, v82, v83
	v_cvt_pk_bf16_f32 v69, v84, v85
	global_store_dwordx4 v[90:91], v[66:69], off offset:256
	s_and_saveexec_b64 s[26:27], s[4:5]
	s_cbranch_execz .LBB0_720
	v_lshlrev_b64 v[66:67], 6, v[80:81]
	v_lshl_add_u64 v[66:67], s[16:17], 0, v[66:67]
	v_lshl_add_u64 v[66:67], s[24:25], 2, v[66:67]
	s_lshl_b32 s10, s40, 2
	v_lshl_add_u64 v[66:67], v[66:67], 0, s[10:11]
	s_waitcnt lgkmcnt(0)
	v_add_f32_e32 v64, v64, v65
	global_store_dword v[66:67], v64, off
.LBB0_720:
	s_or_b64 exec, exec, s[26:27]
	v_add_u32_e32 v64, 0x80, v150
	s_waitcnt lgkmcnt(0)
	v_ashrrev_i32_e32 v65, 31, v64
	v_lshlrev_b64 v[66:67], 11, v[64:65]
	v_lshl_add_u64 v[66:67], s[14:15], 0, v[66:67]
	v_lshl_add_u64 v[74:75], v[148:149], 1, v[66:67]
	global_load_dwordx4 v[66:69], v[74:75], off
	global_load_dwordx4 v[70:73], v[74:75], off offset:256
	s_waitcnt vmcnt(1)
	v_lshlrev_b32_e32 v76, 16, v66
	v_and_b32_e32 v77, 0xffff0000, v66
	v_lshlrev_b32_e32 v66, 16, v67
	v_and_b32_e32 v67, 0xffff0000, v67
	v_lshlrev_b32_e32 v78, 16, v68
	v_and_b32_e32 v79, 0xffff0000, v68
	v_lshlrev_b32_e32 v68, 16, v69
	v_and_b32_e32 v69, 0xffff0000, v69
	s_waitcnt vmcnt(0)
	v_lshlrev_b32_e32 v80, 16, v70
	v_and_b32_e32 v81, 0xffff0000, v70
	v_lshlrev_b32_e32 v70, 16, v71
	v_and_b32_e32 v71, 0xffff0000, v71
	v_lshlrev_b32_e32 v82, 16, v72
	v_and_b32_e32 v83, 0xffff0000, v72
	v_lshlrev_b32_e32 v72, 16, v73
	v_and_b32_e32 v73, 0xffff0000, v73
	v_pk_add_f32 v[60:61], v[60:61], v[76:77]
	v_pk_add_f32 v[62:63], v[62:63], v[66:67]
	v_pk_add_f32 v[56:57], v[56:57], v[78:79]
	v_pk_add_f32 v[58:59], v[58:59], v[68:69]
	v_pk_add_f32 v[52:53], v[52:53], v[80:81]
	v_pk_add_f32 v[54:55], v[54:55], v[70:71]
	v_pk_add_f32 v[66:67], v[48:49], v[82:83]
	v_pk_add_f32 v[68:69], v[50:51], v[72:73]
	v_cvt_pk_bf16_f32 v48, v60, v61
	v_cvt_pk_bf16_f32 v49, v62, v63
	v_pk_mul_f32 v[50:51], v[60:61], v[60:61]
	v_pk_mul_f32 v[60:61], v[62:63], v[62:63]
	v_pk_mul_f32 v[62:63], v[56:57], v[56:57]
	v_pk_mul_f32 v[70:71], v[58:59], v[58:59]
	v_pk_mul_f32 v[72:73], v[52:53], v[52:53]
	v_pk_mul_f32 v[76:77], v[54:55], v[54:55]
	v_pk_mul_f32 v[78:79], v[66:67], v[66:67]
	v_pk_mul_f32 v[80:81], v[68:69], v[68:69]
	v_add_f32_e32 v78, v78, v79
	v_add_f32_e32 v80, v80, v81
	v_add_f32_e32 v76, v76, v77
	v_add_f32_e32 v72, v72, v73
	v_add_f32_e32 v70, v70, v71
	v_add_f32_e32 v62, v62, v63
	v_add_f32_e32 v60, v60, v61
	v_add_f32_e32 v50, v50, v51
	v_add_f32_e32 v51, v78, v80
	v_add_f32_e32 v61, v72, v76
	v_add_f32_e32 v62, v62, v70
	v_add_f32_e32 v50, v50, v60
	v_add_f32_e32 v51, v61, v51
	v_add_f32_e32 v50, v50, v62
	v_add_f32_e32 v60, v50, v51
	v_mov_b32_e32 v61, v60
	s_nop 1
	v_permlane16_swap_b32_e32 v60, v61
	v_cvt_pk_bf16_f32 v50, v56, v57
	v_cvt_pk_bf16_f32 v51, v58, v59
	global_store_dwordx4 v[74:75], v[48:51], off
	s_waitcnt lgkmcnt(0)
	s_nop 0
	v_add_f32_e32 v48, v60, v61
	v_mov_b32_e32 v49, v48
	s_nop 1
	v_permlane32_swap_b32_e32 v48, v49
	v_cvt_pk_bf16_f32 v50, v52, v53
	v_cvt_pk_bf16_f32 v51, v54, v55
	v_cvt_pk_bf16_f32 v52, v66, v67
	v_cvt_pk_bf16_f32 v53, v68, v69
	global_store_dwordx4 v[74:75], v[50:53], off offset:256
	s_and_saveexec_b64 s[26:27], s[4:5]
	s_cbranch_execz .LBB0_722
	v_lshlrev_b64 v[50:51], 6, v[64:65]
	v_lshl_add_u64 v[50:51], s[16:17], 0, v[50:51]
	v_lshl_add_u64 v[50:51], s[24:25], 2, v[50:51]
	s_lshl_b32 s10, s40, 2
	v_lshl_add_u64 v[50:51], v[50:51], 0, s[10:11]
	s_waitcnt lgkmcnt(0)
	v_add_f32_e32 v48, v48, v49
	global_store_dword v[50:51], v48, off
.LBB0_722:
	s_or_b64 exec, exec, s[26:27]
	v_add_u32_e32 v48, 0x90, v150
	s_waitcnt lgkmcnt(0)
	v_ashrrev_i32_e32 v49, 31, v48
	v_lshlrev_b64 v[50:51], 11, v[48:49]
	v_lshl_add_u64 v[50:51], s[14:15], 0, v[50:51]
	v_lshl_add_u64 v[58:59], v[148:149], 1, v[50:51]
	global_load_dwordx4 v[50:53], v[58:59], off
	global_load_dwordx4 v[54:57], v[58:59], off offset:256
	s_waitcnt vmcnt(1)
	v_lshlrev_b32_e32 v60, 16, v50
	v_and_b32_e32 v61, 0xffff0000, v50
	v_lshlrev_b32_e32 v50, 16, v51
	v_and_b32_e32 v51, 0xffff0000, v51
	v_lshlrev_b32_e32 v62, 16, v52
	v_and_b32_e32 v63, 0xffff0000, v52
	v_lshlrev_b32_e32 v52, 16, v53
	v_and_b32_e32 v53, 0xffff0000, v53
	s_waitcnt vmcnt(0)
	v_lshlrev_b32_e32 v64, 16, v54
	v_and_b32_e32 v65, 0xffff0000, v54
	v_lshlrev_b32_e32 v54, 16, v55
	v_and_b32_e32 v55, 0xffff0000, v55
	v_lshlrev_b32_e32 v66, 16, v56
	v_and_b32_e32 v67, 0xffff0000, v56
	v_lshlrev_b32_e32 v56, 16, v57
	v_and_b32_e32 v57, 0xffff0000, v57
	v_pk_add_f32 v[44:45], v[44:45], v[60:61]
	v_pk_add_f32 v[46:47], v[46:47], v[50:51]
	v_pk_add_f32 v[40:41], v[40:41], v[62:63]
	v_pk_add_f32 v[42:43], v[42:43], v[52:53]
	v_pk_add_f32 v[36:37], v[36:37], v[64:65]
	v_pk_add_f32 v[38:39], v[38:39], v[54:55]
	v_pk_add_f32 v[50:51], v[32:33], v[66:67]
	v_pk_add_f32 v[52:53], v[34:35], v[56:57]
	v_cvt_pk_bf16_f32 v32, v44, v45
	v_cvt_pk_bf16_f32 v33, v46, v47
	v_pk_mul_f32 v[34:35], v[44:45], v[44:45]
	v_pk_mul_f32 v[44:45], v[46:47], v[46:47]
	v_pk_mul_f32 v[46:47], v[40:41], v[40:41]
	v_pk_mul_f32 v[54:55], v[42:43], v[42:43]
	v_pk_mul_f32 v[56:57], v[36:37], v[36:37]
	v_pk_mul_f32 v[60:61], v[38:39], v[38:39]
	v_pk_mul_f32 v[62:63], v[50:51], v[50:51]
	v_pk_mul_f32 v[64:65], v[52:53], v[52:53]
	v_add_f32_e32 v62, v62, v63
	v_add_f32_e32 v64, v64, v65
	v_add_f32_e32 v60, v60, v61
	v_add_f32_e32 v56, v56, v57
	v_add_f32_e32 v54, v54, v55
	v_add_f32_e32 v46, v46, v47
	v_add_f32_e32 v44, v44, v45
	v_add_f32_e32 v34, v34, v35
	v_add_f32_e32 v35, v62, v64
	v_add_f32_e32 v45, v56, v60
	v_add_f32_e32 v46, v46, v54
	v_add_f32_e32 v34, v34, v44
	v_add_f32_e32 v35, v45, v35
	v_add_f32_e32 v34, v34, v46
	v_add_f32_e32 v44, v34, v35
	v_mov_b32_e32 v45, v44
	s_nop 1
	v_permlane16_swap_b32_e32 v44, v45
	v_cvt_pk_bf16_f32 v34, v40, v41
	v_cvt_pk_bf16_f32 v35, v42, v43
	global_store_dwordx4 v[58:59], v[32:35], off
	s_waitcnt lgkmcnt(0)
	s_nop 0
	v_add_f32_e32 v32, v44, v45
	v_mov_b32_e32 v33, v32
	s_nop 1
	v_permlane32_swap_b32_e32 v32, v33
	v_cvt_pk_bf16_f32 v34, v36, v37
	v_cvt_pk_bf16_f32 v35, v38, v39
	v_cvt_pk_bf16_f32 v36, v50, v51
	v_cvt_pk_bf16_f32 v37, v52, v53
	global_store_dwordx4 v[58:59], v[34:37], off offset:256
	s_and_saveexec_b64 s[26:27], s[4:5]
	s_cbranch_execz .LBB0_724
	v_lshlrev_b64 v[34:35], 6, v[48:49]
	v_lshl_add_u64 v[34:35], s[16:17], 0, v[34:35]
	v_lshl_add_u64 v[34:35], s[24:25], 2, v[34:35]
	s_lshl_b32 s10, s40, 2
	v_lshl_add_u64 v[34:35], v[34:35], 0, s[10:11]
	s_waitcnt lgkmcnt(0)
	v_add_f32_e32 v32, v32, v33
	global_store_dword v[34:35], v32, off
.LBB0_724:
	s_or_b64 exec, exec, s[26:27]
	v_add_u32_e32 v32, 0xa0, v150
	s_waitcnt lgkmcnt(0)
	v_ashrrev_i32_e32 v33, 31, v32
	v_lshlrev_b64 v[34:35], 11, v[32:33]
	v_lshl_add_u64 v[34:35], s[14:15], 0, v[34:35]
	v_lshl_add_u64 v[42:43], v[148:149], 1, v[34:35]
	global_load_dwordx4 v[34:37], v[42:43], off
	global_load_dwordx4 v[38:41], v[42:43], off offset:256
	s_waitcnt vmcnt(1)
	v_lshlrev_b32_e32 v44, 16, v34
	v_and_b32_e32 v45, 0xffff0000, v34
	v_lshlrev_b32_e32 v34, 16, v35
	v_and_b32_e32 v35, 0xffff0000, v35
	v_lshlrev_b32_e32 v46, 16, v36
	v_and_b32_e32 v47, 0xffff0000, v36
	v_lshlrev_b32_e32 v36, 16, v37
	v_and_b32_e32 v37, 0xffff0000, v37
	s_waitcnt vmcnt(0)
	v_lshlrev_b32_e32 v48, 16, v38
	v_and_b32_e32 v49, 0xffff0000, v38
	v_lshlrev_b32_e32 v38, 16, v39
	v_and_b32_e32 v39, 0xffff0000, v39
	v_lshlrev_b32_e32 v50, 16, v40
	v_and_b32_e32 v51, 0xffff0000, v40
	v_lshlrev_b32_e32 v40, 16, v41
	v_and_b32_e32 v41, 0xffff0000, v41
	v_pk_add_f32 v[28:29], v[28:29], v[44:45]
	v_pk_add_f32 v[30:31], v[30:31], v[34:35]
	v_pk_add_f32 v[24:25], v[24:25], v[46:47]
	v_pk_add_f32 v[26:27], v[26:27], v[36:37]
	v_pk_add_f32 v[20:21], v[20:21], v[48:49]
	v_pk_add_f32 v[22:23], v[22:23], v[38:39]
	v_pk_add_f32 v[34:35], v[16:17], v[50:51]
	v_pk_add_f32 v[36:37], v[18:19], v[40:41]
	v_cvt_pk_bf16_f32 v16, v28, v29
	v_cvt_pk_bf16_f32 v17, v30, v31
	v_pk_mul_f32 v[18:19], v[28:29], v[28:29]
	v_pk_mul_f32 v[28:29], v[30:31], v[30:31]
	v_pk_mul_f32 v[30:31], v[24:25], v[24:25]
	v_pk_mul_f32 v[38:39], v[26:27], v[26:27]
	v_pk_mul_f32 v[40:41], v[20:21], v[20:21]
	v_pk_mul_f32 v[44:45], v[22:23], v[22:23]
	v_pk_mul_f32 v[46:47], v[34:35], v[34:35]
	v_pk_mul_f32 v[48:49], v[36:37], v[36:37]
	v_add_f32_e32 v46, v46, v47
	v_add_f32_e32 v48, v48, v49
	v_add_f32_e32 v44, v44, v45
	v_add_f32_e32 v40, v40, v41
	v_add_f32_e32 v38, v38, v39
	v_add_f32_e32 v30, v30, v31
	v_add_f32_e32 v28, v28, v29
	v_add_f32_e32 v18, v18, v19
	v_add_f32_e32 v19, v46, v48
	v_add_f32_e32 v29, v40, v44
	v_add_f32_e32 v30, v30, v38
	v_add_f32_e32 v18, v18, v28
	v_add_f32_e32 v19, v29, v19
	v_add_f32_e32 v18, v18, v30
	v_add_f32_e32 v28, v18, v19
	v_mov_b32_e32 v29, v28
	s_nop 1
	v_permlane16_swap_b32_e32 v28, v29
	v_cvt_pk_bf16_f32 v18, v24, v25
	v_cvt_pk_bf16_f32 v19, v26, v27
	global_store_dwordx4 v[42:43], v[16:19], off
	s_waitcnt lgkmcnt(0)
	s_nop 0
	v_add_f32_e32 v16, v28, v29
	v_mov_b32_e32 v17, v16
	s_nop 1
	v_permlane32_swap_b32_e32 v16, v17
	v_cvt_pk_bf16_f32 v18, v20, v21
	v_cvt_pk_bf16_f32 v19, v22, v23
	v_cvt_pk_bf16_f32 v20, v34, v35
	v_cvt_pk_bf16_f32 v21, v36, v37
	global_store_dwordx4 v[42:43], v[18:21], off offset:256
	s_and_saveexec_b64 s[26:27], s[4:5]
	s_cbranch_execz .LBB0_726
	v_lshlrev_b64 v[18:19], 6, v[32:33]
	v_lshl_add_u64 v[18:19], s[16:17], 0, v[18:19]
	v_lshl_add_u64 v[18:19], s[24:25], 2, v[18:19]
	s_lshl_b32 s10, s40, 2
	v_lshl_add_u64 v[18:19], v[18:19], 0, s[10:11]
	s_waitcnt lgkmcnt(0)
	v_add_f32_e32 v16, v16, v17
	global_store_dword v[18:19], v16, off
.LBB0_726:
	s_or_b64 exec, exec, s[26:27]
	v_add_u32_e32 v16, 0xb0, v150
	s_waitcnt lgkmcnt(0)
	v_ashrrev_i32_e32 v17, 31, v16
	v_lshlrev_b64 v[18:19], 11, v[16:17]
	v_lshl_add_u64 v[18:19], s[14:15], 0, v[18:19]
	v_lshl_add_u64 v[26:27], v[148:149], 1, v[18:19]
	global_load_dwordx4 v[18:21], v[26:27], off
	global_load_dwordx4 v[22:25], v[26:27], off offset:256
	s_waitcnt vmcnt(1)
	v_lshlrev_b32_e32 v28, 16, v18
	v_and_b32_e32 v29, 0xffff0000, v18
	v_lshlrev_b32_e32 v18, 16, v19
	v_and_b32_e32 v19, 0xffff0000, v19
	v_lshlrev_b32_e32 v30, 16, v20
	v_and_b32_e32 v31, 0xffff0000, v20
	v_lshlrev_b32_e32 v20, 16, v21
	v_and_b32_e32 v21, 0xffff0000, v21
	s_waitcnt vmcnt(0)
	v_lshlrev_b32_e32 v32, 16, v22
	v_and_b32_e32 v33, 0xffff0000, v22
	v_lshlrev_b32_e32 v22, 16, v23
	v_and_b32_e32 v23, 0xffff0000, v23
	v_lshlrev_b32_e32 v34, 16, v24
	v_and_b32_e32 v35, 0xffff0000, v24
	v_lshlrev_b32_e32 v24, 16, v25
	v_and_b32_e32 v25, 0xffff0000, v25
	v_pk_add_f32 v[12:13], v[12:13], v[28:29]
	v_pk_add_f32 v[14:15], v[14:15], v[18:19]
	v_pk_add_f32 v[8:9], v[8:9], v[30:31]
	v_pk_add_f32 v[10:11], v[10:11], v[20:21]
	v_pk_add_f32 v[4:5], v[4:5], v[32:33]
	v_pk_add_f32 v[6:7], v[6:7], v[22:23]
	v_pk_add_f32 v[18:19], v[0:1], v[34:35]
	v_pk_add_f32 v[20:21], v[2:3], v[24:25]
	v_cvt_pk_bf16_f32 v0, v12, v13
	v_cvt_pk_bf16_f32 v1, v14, v15
	v_pk_mul_f32 v[2:3], v[12:13], v[12:13]
	v_pk_mul_f32 v[12:13], v[14:15], v[14:15]
	v_pk_mul_f32 v[14:15], v[8:9], v[8:9]
	v_pk_mul_f32 v[22:23], v[10:11], v[10:11]
	v_pk_mul_f32 v[24:25], v[4:5], v[4:5]
	v_pk_mul_f32 v[28:29], v[6:7], v[6:7]
	v_pk_mul_f32 v[30:31], v[18:19], v[18:19]
	v_pk_mul_f32 v[32:33], v[20:21], v[20:21]
	v_add_f32_e32 v30, v30, v31
	v_add_f32_e32 v32, v32, v33
	v_add_f32_e32 v28, v28, v29
	v_add_f32_e32 v24, v24, v25
	v_add_f32_e32 v22, v22, v23
	v_add_f32_e32 v14, v14, v15
	v_add_f32_e32 v12, v12, v13
	v_add_f32_e32 v2, v2, v3
	v_add_f32_e32 v3, v30, v32
	v_add_f32_e32 v13, v24, v28
	v_add_f32_e32 v14, v14, v22
	v_add_f32_e32 v2, v2, v12
	v_add_f32_e32 v3, v13, v3
	v_add_f32_e32 v2, v2, v14
	v_add_f32_e32 v12, v2, v3
	v_mov_b32_e32 v13, v12
	s_nop 1
	v_permlane16_swap_b32_e32 v12, v13
	v_cvt_pk_bf16_f32 v2, v8, v9
	v_cvt_pk_bf16_f32 v3, v10, v11
	global_store_dwordx4 v[26:27], v[0:3], off
	s_waitcnt lgkmcnt(0)
	s_nop 0
	v_add_f32_e32 v0, v12, v13
	v_mov_b32_e32 v1, v0
	s_nop 1
	v_permlane32_swap_b32_e32 v0, v1
	v_cvt_pk_bf16_f32 v2, v4, v5
	v_cvt_pk_bf16_f32 v3, v6, v7
	v_cvt_pk_bf16_f32 v4, v18, v19
	v_cvt_pk_bf16_f32 v5, v20, v21
	global_store_dwordx4 v[26:27], v[2:5], off offset:256
	s_and_saveexec_b64 s[26:27], s[4:5]
	s_cbranch_execz .LBB0_728
	v_lshlrev_b64 v[2:3], 6, v[16:17]
	v_lshl_add_u64 v[2:3], s[16:17], 0, v[2:3]
	v_lshl_add_u64 v[2:3], s[24:25], 2, v[2:3]
	s_lshl_b32 s10, s40, 2
	v_lshl_add_u64 v[2:3], v[2:3], 0, s[10:11]
	s_waitcnt lgkmcnt(0)
	v_add_f32_e32 v0, v0, v1
	global_store_dword v[2:3], v0, off

.LBB0_809:
	v_lshl_add_u32 v150, s6, 8, v159
	v_ashrrev_i32_e32 v151, 31, v150
	v_lshlrev_b64 v[152:153], 6, v[150:151]
	v_lshl_add_u64 v[152:153], v[140:141], 0, v[152:153]
	global_load_dwordx4 v[152:155], v[152:153], off
	v_and_b32_e32 v157, 64, v165
	v_xor_b32_e32 v156, 16, v165
	v_add_u32_e32 v168, 64, v157
	v_cmp_lt_i32_e32 vcc, v156, v168
	s_waitcnt vmcnt(0)
	v_mov_b32_e32 v157, v154
	v_cndmask_b32_e32 v156, v165, v156, vcc
	v_lshlrev_b32_e32 v167, 2, v156
	v_mov_b32_e32 v156, v153
	v_mov_b32_e32 v153, v155
	v_pk_add_f32 v[152:153], v[156:157], v[152:153]
	v_xor_b32_e32 v154, 32, v165
	v_add_f32_e32 v152, v152, v153
	v_mov_b32_e32 v153, v152
	s_nop 1
	v_permlane16_swap_b32_e32 v152, v153
	v_cmp_lt_i32_e32 vcc, v154, v168
	s_nop 1
	v_cndmask_b32_e32 v154, v165, v154, vcc
	v_lshlrev_b32_e32 v168, 2, v154
	s_waitcnt lgkmcnt(0)
	v_add_f32_e32 v154, v152, v153
	v_mov_b32_e32 v155, v154
	s_nop 1
	v_permlane32_swap_b32_e32 v154, v155
	v_lshl_or_b32 v152, s0, 8, v161
	v_ashrrev_i32_e32 v153, 31, v152
	s_waitcnt lgkmcnt(0)
	v_add_f32_e32 v154, v154, v155
	v_fmamk_f32 v154, v154, 0x3a800000, v166
	v_mul_f32_e32 v155, 0x4b800000, v154
	v_cmp_gt_f32_e32 vcc, s52, v154
	s_nop 1
	v_cndmask_b32_e32 v154, v154, v155, vcc
	v_rsq_f32_e32 v156, v154
	v_lshlrev_b64 v[154:155], 12, v[150:151]
	v_lshl_add_u64 v[154:155], s[12:13], 0, v[154:155]
	v_lshl_add_u64 v[154:155], v[152:153], 1, v[154:155]
	v_mul_f32_e32 v151, 0x45800000, v156
	v_cndmask_b32_e32 v156, v156, v151, vcc
	v_mov_b32_e32 v157, v156
	v_cmp_gt_i32_e32 vcc, s53, v152
	s_and_saveexec_b64 s[0:1], vcc
	s_cbranch_execz .LBB0_811
	v_mov_b32_e32 v170, v156
	v_mov_b32_e32 v171, v156
	v_pk_mul_f32 v[126:127], v[126:127], v[170:171]
	v_pk_mul_f32 v[124:125], v[124:125], v[156:157]
	v_pk_mul_f32 v[122:123], v[122:123], v[170:171]
	v_pk_mul_f32 v[120:121], v[120:121], v[156:157]
	v_cvt_pk_bf16_f32 v124, v124, v125
	v_cvt_pk_bf16_f32 v125, v126, v127
	v_cvt_pk_bf16_f32 v126, v120, v121
	v_cvt_pk_bf16_f32 v127, v122, v123
	global_store_dwordx4 v[154:155], v[124:127], off

.LBB0_813:
	s_or_b64 exec, exec, s[0:1]
	s_nop 0
	v_or_b32_e32 v116, 16, v150
	v_ashrrev_i32_e32 v117, 31, v116
	v_lshlrev_b64 v[112:113], 6, v[116:117]
	v_lshl_add_u64 v[112:113], v[140:141], 0, v[112:113]
	global_load_dwordx4 v[112:115], v[112:113], off
	s_waitcnt vmcnt(0)
	v_mov_b32_e32 v118, v113
	v_mov_b32_e32 v119, v114
	v_mov_b32_e32 v113, v115
	v_pk_add_f32 v[112:113], v[118:119], v[112:113]
	s_nop 0
	v_add_f32_e32 v112, v112, v113
	v_mov_b32_e32 v113, v112
	s_nop 1
	v_permlane16_swap_b32_e32 v112, v113
	s_waitcnt lgkmcnt(0)
	v_add_f32_e32 v112, v112, v113
	v_mov_b32_e32 v113, v112
	s_nop 1
	v_permlane32_swap_b32_e32 v112, v113
	s_waitcnt lgkmcnt(0)
	v_add_f32_e32 v112, v112, v113
	v_fmamk_f32 v112, v112, 0x3a800000, v166
	v_mul_f32_e32 v113, 0x4b800000, v112
	v_cmp_gt_f32_e64 s[0:1], s52, v112
	s_nop 1
	v_cndmask_b32_e64 v112, v112, v113, s[0:1]
	v_rsq_f32_e32 v114, v112
	v_lshlrev_b64 v[112:113], 12, v[116:117]
	v_lshl_add_u64 v[112:113], s[12:13], 0, v[112:113]
	v_lshl_add_u64 v[112:113], v[152:153], 1, v[112:113]
	v_mul_f32_e32 v115, 0x45800000, v114
	v_cndmask_b32_e64 v114, v114, v115, s[0:1]
	v_mov_b32_e32 v115, v114
	s_and_saveexec_b64 s[0:1], vcc
	s_cbranch_execz .LBB0_815
	v_mov_b32_e32 v116, v114
	v_mov_b32_e32 v117, v114
	v_pk_mul_f32 v[110:111], v[110:111], v[116:117]
	v_pk_mul_f32 v[108:109], v[108:109], v[114:115]
	v_pk_mul_f32 v[106:107], v[106:107], v[116:117]
	v_pk_mul_f32 v[104:105], v[104:105], v[114:115]
	v_cvt_pk_bf16_f32 v108, v108, v109
	v_cvt_pk_bf16_f32 v109, v110, v111
	v_cvt_pk_bf16_f32 v110, v104, v105
	v_cvt_pk_bf16_f32 v111, v106, v107
	global_store_dwordx4 v[112:113], v[108:111], off

.LBB0_817:
	s_or_b64 exec, exec, s[0:1]
	s_nop 0
	v_or_b32_e32 v100, 32, v150
	v_ashrrev_i32_e32 v101, 31, v100
	v_lshlrev_b64 v[96:97], 6, v[100:101]
	v_lshl_add_u64 v[96:97], v[140:141], 0, v[96:97]
	global_load_dwordx4 v[96:99], v[96:97], off
	s_waitcnt vmcnt(0)
	v_mov_b32_e32 v102, v97
	v_mov_b32_e32 v103, v98
	v_mov_b32_e32 v97, v99
	v_pk_add_f32 v[96:97], v[102:103], v[96:97]
	s_nop 0
	v_add_f32_e32 v96, v96, v97
	v_mov_b32_e32 v97, v96
	s_nop 1
	v_permlane16_swap_b32_e32 v96, v97
	s_waitcnt lgkmcnt(0)
	v_add_f32_e32 v96, v96, v97
	v_mov_b32_e32 v97, v96
	s_nop 1
	v_permlane32_swap_b32_e32 v96, v97
	s_waitcnt lgkmcnt(0)
	v_add_f32_e32 v96, v96, v97
	v_fmamk_f32 v96, v96, 0x3a800000, v166
	v_mul_f32_e32 v97, 0x4b800000, v96
	v_cmp_gt_f32_e64 s[0:1], s52, v96
	s_nop 1
	v_cndmask_b32_e64 v96, v96, v97, s[0:1]
	v_rsq_f32_e32 v98, v96
	v_lshlrev_b64 v[96:97], 12, v[100:101]
	v_lshl_add_u64 v[96:97], s[12:13], 0, v[96:97]
	v_lshl_add_u64 v[96:97], v[152:153], 1, v[96:97]
	v_mul_f32_e32 v99, 0x45800000, v98
	v_cndmask_b32_e64 v98, v98, v99, s[0:1]
	v_mov_b32_e32 v99, v98
	s_and_saveexec_b64 s[0:1], vcc
	s_cbranch_execz .LBB0_819
	v_mov_b32_e32 v100, v98
	v_mov_b32_e32 v101, v98
	v_pk_mul_f32 v[94:95], v[94:95], v[100:101]
	v_pk_mul_f32 v[92:93], v[92:93], v[98:99]
	v_pk_mul_f32 v[90:91], v[90:91], v[100:101]
	v_pk_mul_f32 v[88:89], v[88:89], v[98:99]
	v_cvt_pk_bf16_f32 v92, v92, v93
	v_cvt_pk_bf16_f32 v93, v94, v95
	v_cvt_pk_bf16_f32 v94, v88, v89
	v_cvt_pk_bf16_f32 v95, v90, v91
	global_store_dwordx4 v[96:97], v[92:95], off

.LBB0_821:
	s_or_b64 exec, exec, s[0:1]
	s_nop 0
	v_or_b32_e32 v84, 48, v150
	v_ashrrev_i32_e32 v85, 31, v84
	v_lshlrev_b64 v[80:81], 6, v[84:85]
	v_lshl_add_u64 v[80:81], v[140:141], 0, v[80:81]
	global_load_dwordx4 v[80:83], v[80:81], off
	s_waitcnt vmcnt(0)
	v_mov_b32_e32 v86, v81
	v_mov_b32_e32 v87, v82
	v_mov_b32_e32 v81, v83
	v_pk_add_f32 v[80:81], v[86:87], v[80:81]
	s_nop 0
	v_add_f32_e32 v80, v80, v81
	v_mov_b32_e32 v81, v80
	s_nop 1
	v_permlane16_swap_b32_e32 v80, v81
	s_waitcnt lgkmcnt(0)
	v_add_f32_e32 v80, v80, v81
	v_mov_b32_e32 v81, v80
	s_nop 1
	v_permlane32_swap_b32_e32 v80, v81
	s_waitcnt lgkmcnt(0)
	v_add_f32_e32 v80, v80, v81
	v_fmamk_f32 v80, v80, 0x3a800000, v166
	v_mul_f32_e32 v81, 0x4b800000, v80
	v_cmp_gt_f32_e64 s[0:1], s52, v80
	s_nop 1
	v_cndmask_b32_e64 v80, v80, v81, s[0:1]
	v_rsq_f32_e32 v82, v80
	v_lshlrev_b64 v[80:81], 12, v[84:85]
	v_lshl_add_u64 v[80:81], s[12:13], 0, v[80:81]
	v_lshl_add_u64 v[80:81], v[152:153], 1, v[80:81]
	v_mul_f32_e32 v83, 0x45800000, v82
	v_cndmask_b32_e64 v82, v82, v83, s[0:1]
	v_mov_b32_e32 v83, v82
	s_and_saveexec_b64 s[0:1], vcc
	s_cbranch_execz .LBB0_823
	v_mov_b32_e32 v84, v82
	v_mov_b32_e32 v85, v82
	v_pk_mul_f32 v[78:79], v[78:79], v[84:85]
	v_pk_mul_f32 v[76:77], v[76:77], v[82:83]
	v_pk_mul_f32 v[74:75], v[74:75], v[84:85]
	v_pk_mul_f32 v[72:73], v[72:73], v[82:83]
	v_cvt_pk_bf16_f32 v76, v76, v77
	v_cvt_pk_bf16_f32 v77, v78, v79
	v_cvt_pk_bf16_f32 v78, v72, v73
	v_cvt_pk_bf16_f32 v79, v74, v75
	global_store_dwordx4 v[80:81], v[76:79], off

.LBB0_825:
	s_or_b64 exec, exec, s[0:1]
	s_nop 0
	v_add_u32_e32 v68, 0x80, v150
	v_ashrrev_i32_e32 v69, 31, v68
	v_lshlrev_b64 v[64:65], 6, v[68:69]
	v_lshl_add_u64 v[64:65], v[140:141], 0, v[64:65]
	global_load_dwordx4 v[64:67], v[64:65], off
	s_waitcnt vmcnt(0)
	v_mov_b32_e32 v70, v65
	v_mov_b32_e32 v71, v66
	v_mov_b32_e32 v65, v67
	v_pk_add_f32 v[64:65], v[70:71], v[64:65]
	s_nop 0
	v_add_f32_e32 v64, v64, v65
	v_mov_b32_e32 v65, v64
	s_nop 1
	v_permlane16_swap_b32_e32 v64, v65
	s_waitcnt lgkmcnt(0)
	v_add_f32_e32 v64, v64, v65
	v_mov_b32_e32 v65, v64
	s_nop 1
	v_permlane32_swap_b32_e32 v64, v65
	s_waitcnt lgkmcnt(0)
	v_add_f32_e32 v64, v64, v65
	v_fmamk_f32 v64, v64, 0x3a800000, v166
	v_mul_f32_e32 v65, 0x4b800000, v64
	v_cmp_gt_f32_e64 s[0:1], s52, v64
	s_nop 1
	v_cndmask_b32_e64 v64, v64, v65, s[0:1]
	v_rsq_f32_e32 v66, v64
	v_lshlrev_b64 v[64:65], 12, v[68:69]
	v_lshl_add_u64 v[64:65], s[12:13], 0, v[64:65]
	v_lshl_add_u64 v[64:65], v[152:153], 1, v[64:65]
	v_mul_f32_e32 v67, 0x45800000, v66
	v_cndmask_b32_e64 v66, v66, v67, s[0:1]
	v_mov_b32_e32 v67, v66
	s_and_saveexec_b64 s[0:1], vcc
	s_cbranch_execz .LBB0_827
	v_mov_b32_e32 v68, v66
	v_mov_b32_e32 v69, v66
	v_pk_mul_f32 v[62:63], v[62:63], v[68:69]
	v_pk_mul_f32 v[60:61], v[60:61], v[66:67]
	v_pk_mul_f32 v[58:59], v[58:59], v[68:69]
	v_pk_mul_f32 v[56:57], v[56:57], v[66:67]
	v_cvt_pk_bf16_f32 v60, v60, v61
	v_cvt_pk_bf16_f32 v61, v62, v63
	v_cvt_pk_bf16_f32 v62, v56, v57
	v_cvt_pk_bf16_f32 v63, v58, v59
	global_store_dwordx4 v[64:65], v[60:63], off

.LBB0_829:
	s_or_b64 exec, exec, s[0:1]
	s_nop 0
	v_add_u32_e32 v52, 0x90, v150
	v_ashrrev_i32_e32 v53, 31, v52
	v_lshlrev_b64 v[48:49], 6, v[52:53]
	v_lshl_add_u64 v[48:49], v[140:141], 0, v[48:49]
	global_load_dwordx4 v[48:51], v[48:49], off
	s_waitcnt vmcnt(0)
	v_mov_b32_e32 v54, v49
	v_mov_b32_e32 v55, v50
	v_mov_b32_e32 v49, v51
	v_pk_add_f32 v[48:49], v[54:55], v[48:49]
	s_nop 0
	v_add_f32_e32 v48, v48, v49
	v_mov_b32_e32 v49, v48
	s_nop 1
	v_permlane16_swap_b32_e32 v48, v49
	s_waitcnt lgkmcnt(0)
	v_add_f32_e32 v48, v48, v49
	v_mov_b32_e32 v49, v48
	s_nop 1
	v_permlane32_swap_b32_e32 v48, v49
	s_waitcnt lgkmcnt(0)
	v_add_f32_e32 v48, v48, v49
	v_fmamk_f32 v48, v48, 0x3a800000, v166
	v_mul_f32_e32 v49, 0x4b800000, v48
	v_cmp_gt_f32_e64 s[0:1], s52, v48
	s_nop 1
	v_cndmask_b32_e64 v48, v48, v49, s[0:1]
	v_rsq_f32_e32 v50, v48
	v_lshlrev_b64 v[48:49], 12, v[52:53]
	v_lshl_add_u64 v[48:49], s[12:13], 0, v[48:49]
	v_lshl_add_u64 v[48:49], v[152:153], 1, v[48:49]
	v_mul_f32_e32 v51, 0x45800000, v50
	v_cndmask_b32_e64 v50, v50, v51, s[0:1]
	v_mov_b32_e32 v51, v50
	s_and_saveexec_b64 s[0:1], vcc
	s_cbranch_execz .LBB0_831
	v_mov_b32_e32 v52, v50
	v_mov_b32_e32 v53, v50
	v_pk_mul_f32 v[46:47], v[46:47], v[52:53]
	v_pk_mul_f32 v[44:45], v[44:45], v[50:51]
	v_pk_mul_f32 v[42:43], v[42:43], v[52:53]
	v_pk_mul_f32 v[40:41], v[40:41], v[50:51]
	v_cvt_pk_bf16_f32 v44, v44, v45
	v_cvt_pk_bf16_f32 v45, v46, v47
	v_cvt_pk_bf16_f32 v46, v40, v41
	v_cvt_pk_bf16_f32 v47, v42, v43
	global_store_dwordx4 v[48:49], v[44:47], off

.LBB0_833:
	s_or_b64 exec, exec, s[0:1]
	s_nop 0
	v_add_u32_e32 v36, 0xa0, v150
	v_ashrrev_i32_e32 v37, 31, v36
	v_lshlrev_b64 v[32:33], 6, v[36:37]
	v_lshl_add_u64 v[32:33], v[140:141], 0, v[32:33]
	global_load_dwordx4 v[32:35], v[32:33], off
	s_waitcnt vmcnt(0)
	v_mov_b32_e32 v38, v33
	v_mov_b32_e32 v39, v34
	v_mov_b32_e32 v33, v35
	v_pk_add_f32 v[32:33], v[38:39], v[32:33]
	s_nop 0
	v_add_f32_e32 v32, v32, v33
	v_mov_b32_e32 v33, v32
	s_nop 1
	v_permlane16_swap_b32_e32 v32, v33
	s_waitcnt lgkmcnt(0)
	v_add_f32_e32 v32, v32, v33
	v_mov_b32_e32 v33, v32
	s_nop 1
	v_permlane32_swap_b32_e32 v32, v33
	s_waitcnt lgkmcnt(0)
	v_add_f32_e32 v32, v32, v33
	v_fmamk_f32 v32, v32, 0x3a800000, v166
	v_mul_f32_e32 v33, 0x4b800000, v32
	v_cmp_gt_f32_e64 s[0:1], s52, v32
	s_nop 1
	v_cndmask_b32_e64 v32, v32, v33, s[0:1]
	v_rsq_f32_e32 v34, v32
	v_lshlrev_b64 v[32:33], 12, v[36:37]
	v_lshl_add_u64 v[32:33], s[12:13], 0, v[32:33]
	v_lshl_add_u64 v[32:33], v[152:153], 1, v[32:33]
	v_mul_f32_e32 v35, 0x45800000, v34
	v_cndmask_b32_e64 v34, v34, v35, s[0:1]
	v_mov_b32_e32 v35, v34
	s_and_saveexec_b64 s[0:1], vcc
	s_cbranch_execz .LBB0_835
	v_mov_b32_e32 v36, v34
	v_mov_b32_e32 v37, v34
	v_pk_mul_f32 v[30:31], v[30:31], v[36:37]
	v_pk_mul_f32 v[28:29], v[28:29], v[34:35]
	v_pk_mul_f32 v[26:27], v[26:27], v[36:37]
	v_pk_mul_f32 v[24:25], v[24:25], v[34:35]
	v_cvt_pk_bf16_f32 v28, v28, v29
	v_cvt_pk_bf16_f32 v29, v30, v31
	v_cvt_pk_bf16_f32 v30, v24, v25
	v_cvt_pk_bf16_f32 v31, v26, v27
	global_store_dwordx4 v[32:33], v[28:31], off

.LBB0_837:
	s_or_b64 exec, exec, s[0:1]
	s_nop 0
	v_add_u32_e32 v20, 0xb0, v150
	v_ashrrev_i32_e32 v21, 31, v20
	v_lshlrev_b64 v[16:17], 6, v[20:21]
	v_lshl_add_u64 v[16:17], v[140:141], 0, v[16:17]
	global_load_dwordx4 v[16:19], v[16:17], off
	s_waitcnt vmcnt(0)
	v_mov_b32_e32 v22, v17
	v_mov_b32_e32 v23, v18
	v_mov_b32_e32 v17, v19
	v_pk_add_f32 v[16:17], v[22:23], v[16:17]
	s_nop 0
	v_add_f32_e32 v16, v16, v17
	v_mov_b32_e32 v17, v16
	s_nop 1
	v_permlane16_swap_b32_e32 v16, v17
	s_waitcnt lgkmcnt(0)
	v_add_f32_e32 v16, v16, v17
	v_mov_b32_e32 v17, v16
	s_nop 1
	v_permlane32_swap_b32_e32 v16, v17
	s_waitcnt lgkmcnt(0)
	v_add_f32_e32 v16, v16, v17
	v_fmamk_f32 v16, v16, 0x3a800000, v166
	v_mul_f32_e32 v17, 0x4b800000, v16
	v_cmp_gt_f32_e64 s[0:1], s52, v16
	s_nop 1
	v_cndmask_b32_e64 v16, v16, v17, s[0:1]
	v_rsq_f32_e32 v18, v16
	v_lshlrev_b64 v[16:17], 12, v[20:21]
	v_lshl_add_u64 v[16:17], s[12:13], 0, v[16:17]
	v_lshl_add_u64 v[16:17], v[152:153], 1, v[16:17]
	v_mul_f32_e32 v19, 0x45800000, v18
	v_cndmask_b32_e64 v18, v18, v19, s[0:1]
	v_mov_b32_e32 v19, v18
	s_and_saveexec_b64 s[0:1], vcc
	s_cbranch_execnz .LBB0_840
	s_or_b64 exec, exec, s[0:1]
	s_and_saveexec_b64 s[0:1], s[6:7]
	s_cbranch_execnz .LBB0_841

.LBB0_1151:
	v_lshl_add_u32 v150, s28, 8, v131
	v_ashrrev_i32_e32 v151, 31, v150
	v_lshl_or_b32 v148, s8, 8, v153
	v_lshlrev_b64 v[158:159], 11, v[150:151]
	v_ashrrev_i32_e32 v149, 31, v148
	v_lshl_add_u64 v[158:159], s[12:13], 0, v[158:159]
	v_lshl_add_u64 v[168:169], v[148:149], 1, v[158:159]
	global_load_dwordx4 v[160:163], v[168:169], off
	global_load_dwordx4 v[164:167], v[168:169], off offset:256
	v_and_b32_e32 v159, 64, v157
	v_xor_b32_e32 v158, 16, v157
	v_add_u32_e32 v159, 64, v159
	v_xor_b32_e32 v170, 32, v157
	v_cmp_lt_i32_e32 vcc, v158, v159
	s_lshl_b32 s28, s8, 2
	s_ashr_i32 s29, s28, 31
	v_cndmask_b32_e32 v158, v157, v158, vcc
	v_cmp_lt_i32_e32 vcc, v170, v159
	v_lshlrev_b32_e32 v159, 2, v158
	s_waitcnt vmcnt(0)
	v_and_b32_e32 v171, 0xffff0000, v160
	v_cndmask_b32_e32 v170, v157, v170, vcc
	v_lshlrev_b32_e32 v158, 2, v170
	v_lshlrev_b32_e32 v170, 16, v160
	v_lshlrev_b32_e32 v160, 16, v161
	v_and_b32_e32 v161, 0xffff0000, v161
	v_lshlrev_b32_e32 v172, 16, v162
	v_and_b32_e32 v173, 0xffff0000, v162
	v_lshlrev_b32_e32 v162, 16, v163
	v_and_b32_e32 v163, 0xffff0000, v163
	v_lshlrev_b32_e32 v174, 16, v164
	v_and_b32_e32 v175, 0xffff0000, v164
	v_lshlrev_b32_e32 v164, 16, v165
	v_and_b32_e32 v165, 0xffff0000, v165
	v_lshlrev_b32_e32 v176, 16, v166
	v_and_b32_e32 v177, 0xffff0000, v166
	v_lshlrev_b32_e32 v166, 16, v167
	v_and_b32_e32 v167, 0xffff0000, v167
	v_pk_add_f32 v[124:125], v[124:125], v[170:171]
	v_pk_add_f32 v[126:127], v[126:127], v[160:161]
	v_pk_add_f32 v[120:121], v[120:121], v[172:173]
	v_pk_add_f32 v[122:123], v[122:123], v[162:163]
	v_pk_add_f32 v[116:117], v[116:117], v[174:175]
	v_pk_add_f32 v[118:119], v[118:119], v[164:165]
	v_pk_add_f32 v[160:161], v[112:113], v[176:177]
	v_pk_add_f32 v[162:163], v[114:115], v[166:167]
	v_cvt_pk_bf16_f32 v112, v124, v125
	v_cvt_pk_bf16_f32 v113, v126, v127
	v_pk_mul_f32 v[114:115], v[124:125], v[124:125]
	v_pk_mul_f32 v[124:125], v[126:127], v[126:127]
	v_pk_mul_f32 v[126:127], v[120:121], v[120:121]
	v_pk_mul_f32 v[164:165], v[122:123], v[122:123]
	v_pk_mul_f32 v[166:167], v[116:117], v[116:117]
	v_pk_mul_f32 v[170:171], v[118:119], v[118:119]
	v_pk_mul_f32 v[172:173], v[160:161], v[160:161]
	v_pk_mul_f32 v[174:175], v[162:163], v[162:163]
	v_add_f32_e32 v172, v172, v173
	v_add_f32_e32 v174, v174, v175
	v_add_f32_e32 v170, v170, v171
	v_add_f32_e32 v166, v166, v167
	v_add_f32_e32 v164, v164, v165
	v_add_f32_e32 v126, v126, v127
	v_add_f32_e32 v124, v124, v125
	v_add_f32_e32 v114, v114, v115
	v_add_f32_e32 v115, v172, v174
	v_add_f32_e32 v125, v166, v170
	v_add_f32_e32 v126, v126, v164
	v_add_f32_e32 v114, v114, v124
	v_add_f32_e32 v115, v125, v115
	v_add_f32_e32 v114, v114, v126
	v_add_f32_e32 v124, v114, v115
	v_mov_b32_e32 v125, v124
	s_nop 1
	v_permlane16_swap_b32_e32 v124, v125
	v_cvt_pk_bf16_f32 v114, v120, v121
	v_cvt_pk_bf16_f32 v115, v122, v123
	global_store_dwordx4 v[168:169], v[112:115], off
	s_waitcnt lgkmcnt(0)
	s_nop 0
	v_add_f32_e32 v112, v124, v125
	v_mov_b32_e32 v113, v112
	s_nop 1
	v_permlane32_swap_b32_e32 v112, v113
	v_cvt_pk_bf16_f32 v114, v116, v117
	v_cvt_pk_bf16_f32 v115, v118, v119
	v_cvt_pk_bf16_f32 v116, v160, v161
	v_cvt_pk_bf16_f32 v117, v162, v163
	global_store_dwordx4 v[168:169], v[114:117], off offset:256
	s_and_saveexec_b64 s[30:31], s[4:5]
	s_cbranch_execz .LBB0_1153
	v_lshlrev_b64 v[114:115], 6, v[150:151]
	v_lshl_add_u64 v[114:115], s[14:15], 0, v[114:115]
	v_lshl_add_u64 v[114:115], s[28:29], 2, v[114:115]
	s_lshl_b32 s8, s46, 2
	v_lshl_add_u64 v[114:115], v[114:115], 0, s[8:9]
	s_waitcnt lgkmcnt(0)
	v_add_f32_e32 v112, v112, v113
	global_store_dword v[114:115], v112, off
.LBB0_1153:
	s_or_b64 exec, exec, s[30:31]
	v_or_b32_e32 v112, 16, v150
	s_waitcnt lgkmcnt(0)
	v_ashrrev_i32_e32 v113, 31, v112
	v_lshlrev_b64 v[114:115], 11, v[112:113]
	v_lshl_add_u64 v[114:115], s[12:13], 0, v[114:115]
	v_lshl_add_u64 v[122:123], v[148:149], 1, v[114:115]
	global_load_dwordx4 v[114:117], v[122:123], off
	global_load_dwordx4 v[118:121], v[122:123], off offset:256
	s_waitcnt vmcnt(1)
	v_lshlrev_b32_e32 v124, 16, v114
	v_and_b32_e32 v125, 0xffff0000, v114
	v_lshlrev_b32_e32 v114, 16, v115
	v_and_b32_e32 v115, 0xffff0000, v115
	v_lshlrev_b32_e32 v126, 16, v116
	v_and_b32_e32 v127, 0xffff0000, v116
	v_lshlrev_b32_e32 v116, 16, v117
	v_and_b32_e32 v117, 0xffff0000, v117
	s_waitcnt vmcnt(0)
	v_lshlrev_b32_e32 v160, 16, v118
	v_and_b32_e32 v161, 0xffff0000, v118
	v_lshlrev_b32_e32 v118, 16, v119
	v_and_b32_e32 v119, 0xffff0000, v119
	v_lshlrev_b32_e32 v162, 16, v120
	v_and_b32_e32 v163, 0xffff0000, v120
	v_lshlrev_b32_e32 v120, 16, v121
	v_and_b32_e32 v121, 0xffff0000, v121
	v_pk_add_f32 v[108:109], v[108:109], v[124:125]
	v_pk_add_f32 v[110:111], v[110:111], v[114:115]
	v_pk_add_f32 v[104:105], v[104:105], v[126:127]
	v_pk_add_f32 v[106:107], v[106:107], v[116:117]
	v_pk_add_f32 v[100:101], v[100:101], v[160:161]
	v_pk_add_f32 v[102:103], v[102:103], v[118:119]
	v_pk_add_f32 v[114:115], v[96:97], v[162:163]
	v_pk_add_f32 v[116:117], v[98:99], v[120:121]
	v_cvt_pk_bf16_f32 v96, v108, v109
	v_cvt_pk_bf16_f32 v97, v110, v111
	v_pk_mul_f32 v[98:99], v[108:109], v[108:109]
	v_pk_mul_f32 v[108:109], v[110:111], v[110:111]
	v_pk_mul_f32 v[110:111], v[104:105], v[104:105]
	v_pk_mul_f32 v[118:119], v[106:107], v[106:107]
	v_pk_mul_f32 v[120:121], v[100:101], v[100:101]
	v_pk_mul_f32 v[124:125], v[102:103], v[102:103]
	v_pk_mul_f32 v[126:127], v[114:115], v[114:115]
	v_pk_mul_f32 v[160:161], v[116:117], v[116:117]
	v_add_f32_e32 v126, v126, v127
	v_add_f32_e32 v151, v160, v161
	v_add_f32_e32 v124, v124, v125
	v_add_f32_e32 v120, v120, v121
	v_add_f32_e32 v118, v118, v119
	v_add_f32_e32 v110, v110, v111
	v_add_f32_e32 v108, v108, v109
	v_add_f32_e32 v98, v98, v99
	v_add_f32_e32 v99, v126, v151
	v_add_f32_e32 v109, v120, v124
	v_add_f32_e32 v110, v110, v118
	v_add_f32_e32 v98, v98, v108
	v_add_f32_e32 v99, v109, v99
	v_add_f32_e32 v98, v98, v110
	v_add_f32_e32 v108, v98, v99
	v_mov_b32_e32 v109, v108
	s_nop 1
	v_permlane16_swap_b32_e32 v108, v109
	v_cvt_pk_bf16_f32 v98, v104, v105
	v_cvt_pk_bf16_f32 v99, v106, v107
	global_store_dwordx4 v[122:123], v[96:99], off
	s_waitcnt lgkmcnt(0)
	s_nop 0
	v_add_f32_e32 v96, v108, v109
	v_mov_b32_e32 v97, v96
	s_nop 1
	v_permlane32_swap_b32_e32 v96, v97
	v_cvt_pk_bf16_f32 v98, v100, v101
	v_cvt_pk_bf16_f32 v99, v102, v103
	v_cvt_pk_bf16_f32 v100, v114, v115
	v_cvt_pk_bf16_f32 v101, v116, v117
	global_store_dwordx4 v[122:123], v[98:101], off offset:256
	s_and_saveexec_b64 s[30:31], s[4:5]
	s_cbranch_execz .LBB0_1155
	v_lshlrev_b64 v[98:99], 6, v[112:113]
	v_lshl_add_u64 v[98:99], s[14:15], 0, v[98:99]
	v_lshl_add_u64 v[98:99], s[28:29], 2, v[98:99]
	s_lshl_b32 s8, s46, 2
	v_lshl_add_u64 v[98:99], v[98:99], 0, s[8:9]
	s_waitcnt lgkmcnt(0)
	v_add_f32_e32 v96, v96, v97
	global_store_dword v[98:99], v96, off
.LBB0_1155:
	s_or_b64 exec, exec, s[30:31]
	v_or_b32_e32 v96, 32, v150
	s_waitcnt lgkmcnt(0)
	v_ashrrev_i32_e32 v97, 31, v96
	v_lshlrev_b64 v[98:99], 11, v[96:97]
	v_lshl_add_u64 v[98:99], s[12:13], 0, v[98:99]
	v_lshl_add_u64 v[106:107], v[148:149], 1, v[98:99]
	global_load_dwordx4 v[98:101], v[106:107], off
	global_load_dwordx4 v[102:105], v[106:107], off offset:256
	s_waitcnt vmcnt(1)
	v_lshlrev_b32_e32 v108, 16, v98
	v_and_b32_e32 v109, 0xffff0000, v98
	v_lshlrev_b32_e32 v98, 16, v99
	v_and_b32_e32 v99, 0xffff0000, v99
	v_lshlrev_b32_e32 v110, 16, v100
	v_and_b32_e32 v111, 0xffff0000, v100
	v_lshlrev_b32_e32 v100, 16, v101
	v_and_b32_e32 v101, 0xffff0000, v101
	s_waitcnt vmcnt(0)
	v_lshlrev_b32_e32 v112, 16, v102
	v_and_b32_e32 v113, 0xffff0000, v102
	v_lshlrev_b32_e32 v102, 16, v103
	v_and_b32_e32 v103, 0xffff0000, v103
	v_lshlrev_b32_e32 v114, 16, v104
	v_and_b32_e32 v115, 0xffff0000, v104
	v_lshlrev_b32_e32 v104, 16, v105
	v_and_b32_e32 v105, 0xffff0000, v105
	v_pk_add_f32 v[92:93], v[92:93], v[108:109]
	v_pk_add_f32 v[94:95], v[94:95], v[98:99]
	v_pk_add_f32 v[88:89], v[88:89], v[110:111]
	v_pk_add_f32 v[90:91], v[90:91], v[100:101]
	v_pk_add_f32 v[84:85], v[84:85], v[112:113]
	v_pk_add_f32 v[86:87], v[86:87], v[102:103]
	v_pk_add_f32 v[98:99], v[80:81], v[114:115]
	v_pk_add_f32 v[100:101], v[82:83], v[104:105]
	v_cvt_pk_bf16_f32 v80, v92, v93
	v_cvt_pk_bf16_f32 v81, v94, v95
	v_pk_mul_f32 v[82:83], v[92:93], v[92:93]
	v_pk_mul_f32 v[92:93], v[94:95], v[94:95]
	v_pk_mul_f32 v[94:95], v[88:89], v[88:89]
	v_pk_mul_f32 v[102:103], v[90:91], v[90:91]
	v_pk_mul_f32 v[104:105], v[84:85], v[84:85]
	v_pk_mul_f32 v[108:109], v[86:87], v[86:87]
	v_pk_mul_f32 v[110:111], v[98:99], v[98:99]
	v_pk_mul_f32 v[112:113], v[100:101], v[100:101]
	v_add_f32_e32 v110, v110, v111
	v_add_f32_e32 v112, v112, v113
	v_add_f32_e32 v108, v108, v109
	v_add_f32_e32 v104, v104, v105
	v_add_f32_e32 v102, v102, v103
	v_add_f32_e32 v94, v94, v95
	v_add_f32_e32 v92, v92, v93
	v_add_f32_e32 v82, v82, v83
	v_add_f32_e32 v83, v110, v112
	v_add_f32_e32 v93, v104, v108
	v_add_f32_e32 v94, v94, v102
	v_add_f32_e32 v82, v82, v92
	v_add_f32_e32 v83, v93, v83
	v_add_f32_e32 v82, v82, v94
	v_add_f32_e32 v92, v82, v83
	v_mov_b32_e32 v93, v92
	s_nop 1
	v_permlane16_swap_b32_e32 v92, v93
	v_cvt_pk_bf16_f32 v82, v88, v89
	v_cvt_pk_bf16_f32 v83, v90, v91
	global_store_dwordx4 v[106:107], v[80:83], off
	s_waitcnt lgkmcnt(0)
	s_nop 0
	v_add_f32_e32 v80, v92, v93
	v_mov_b32_e32 v81, v80
	s_nop 1
	v_permlane32_swap_b32_e32 v80, v81
	v_cvt_pk_bf16_f32 v82, v84, v85
	v_cvt_pk_bf16_f32 v83, v86, v87
	v_cvt_pk_bf16_f32 v84, v98, v99
	v_cvt_pk_bf16_f32 v85, v100, v101
	global_store_dwordx4 v[106:107], v[82:85], off offset:256
	s_and_saveexec_b64 s[30:31], s[4:5]
	s_cbranch_execz .LBB0_1157
	v_lshlrev_b64 v[82:83], 6, v[96:97]
	v_lshl_add_u64 v[82:83], s[14:15], 0, v[82:83]
	v_lshl_add_u64 v[82:83], s[28:29], 2, v[82:83]
	s_lshl_b32 s8, s46, 2
	v_lshl_add_u64 v[82:83], v[82:83], 0, s[8:9]
	s_waitcnt lgkmcnt(0)
	v_add_f32_e32 v80, v80, v81
	global_store_dword v[82:83], v80, off
.LBB0_1157:
	s_or_b64 exec, exec, s[30:31]
	v_or_b32_e32 v80, 48, v150
	s_waitcnt lgkmcnt(0)
	v_ashrrev_i32_e32 v81, 31, v80
	v_lshlrev_b64 v[82:83], 11, v[80:81]
	v_lshl_add_u64 v[82:83], s[12:13], 0, v[82:83]
	v_lshl_add_u64 v[90:91], v[148:149], 1, v[82:83]
	global_load_dwordx4 v[82:85], v[90:91], off
	global_load_dwordx4 v[86:89], v[90:91], off offset:256
	s_waitcnt vmcnt(1)
	v_lshlrev_b32_e32 v92, 16, v82
	v_and_b32_e32 v93, 0xffff0000, v82
	v_lshlrev_b32_e32 v82, 16, v83
	v_and_b32_e32 v83, 0xffff0000, v83
	v_lshlrev_b32_e32 v94, 16, v84
	v_and_b32_e32 v95, 0xffff0000, v84
	v_lshlrev_b32_e32 v84, 16, v85
	v_and_b32_e32 v85, 0xffff0000, v85
	s_waitcnt vmcnt(0)
	v_lshlrev_b32_e32 v96, 16, v86
	v_and_b32_e32 v97, 0xffff0000, v86
	v_lshlrev_b32_e32 v86, 16, v87
	v_and_b32_e32 v87, 0xffff0000, v87
	v_lshlrev_b32_e32 v98, 16, v88
	v_and_b32_e32 v99, 0xffff0000, v88
	v_lshlrev_b32_e32 v88, 16, v89
	v_and_b32_e32 v89, 0xffff0000, v89
	v_pk_add_f32 v[76:77], v[76:77], v[92:93]
	v_pk_add_f32 v[78:79], v[78:79], v[82:83]
	v_pk_add_f32 v[72:73], v[72:73], v[94:95]
	v_pk_add_f32 v[74:75], v[74:75], v[84:85]
	v_pk_add_f32 v[68:69], v[68:69], v[96:97]
	v_pk_add_f32 v[70:71], v[70:71], v[86:87]
	v_pk_add_f32 v[82:83], v[64:65], v[98:99]
	v_pk_add_f32 v[84:85], v[66:67], v[88:89]
	v_cvt_pk_bf16_f32 v64, v76, v77
	v_cvt_pk_bf16_f32 v65, v78, v79
	v_pk_mul_f32 v[66:67], v[76:77], v[76:77]
	v_pk_mul_f32 v[76:77], v[78:79], v[78:79]
	v_pk_mul_f32 v[78:79], v[72:73], v[72:73]
	v_pk_mul_f32 v[86:87], v[74:75], v[74:75]
	v_pk_mul_f32 v[88:89], v[68:69], v[68:69]
	v_pk_mul_f32 v[92:93], v[70:71], v[70:71]
	v_pk_mul_f32 v[94:95], v[82:83], v[82:83]
	v_pk_mul_f32 v[96:97], v[84:85], v[84:85]
	v_add_f32_e32 v94, v94, v95
	v_add_f32_e32 v96, v96, v97
	v_add_f32_e32 v92, v92, v93
	v_add_f32_e32 v88, v88, v89
	v_add_f32_e32 v86, v86, v87
	v_add_f32_e32 v78, v78, v79
	v_add_f32_e32 v76, v76, v77
	v_add_f32_e32 v66, v66, v67
	v_add_f32_e32 v67, v94, v96
	v_add_f32_e32 v77, v88, v92
	v_add_f32_e32 v78, v78, v86
	v_add_f32_e32 v66, v66, v76
	v_add_f32_e32 v67, v77, v67
	v_add_f32_e32 v66, v66, v78
	v_add_f32_e32 v76, v66, v67
	v_mov_b32_e32 v77, v76
	s_nop 1
	v_permlane16_swap_b32_e32 v76, v77
	v_cvt_pk_bf16_f32 v66, v72, v73
	v_cvt_pk_bf16_f32 v67, v74, v75
	global_store_dwordx4 v[90:91], v[64:67], off
	s_waitcnt lgkmcnt(0)
	s_nop 0
	v_add_f32_e32 v64, v76, v77
	v_mov_b32_e32 v65, v64
	s_nop 1
	v_permlane32_swap_b32_e32 v64, v65
	v_cvt_pk_bf16_f32 v66, v68, v69
	v_cvt_pk_bf16_f32 v67, v70, v71
	v_cvt_pk_bf16_f32 v68, v82, v83
	v_cvt_pk_bf16_f32 v69, v84, v85
	global_store_dwordx4 v[90:91], v[66:69], off offset:256
	s_and_saveexec_b64 s[30:31], s[4:5]
	s_cbranch_execz .LBB0_1159
	v_lshlrev_b64 v[66:67], 6, v[80:81]
	v_lshl_add_u64 v[66:67], s[14:15], 0, v[66:67]
	v_lshl_add_u64 v[66:67], s[28:29], 2, v[66:67]
	s_lshl_b32 s8, s46, 2
	v_lshl_add_u64 v[66:67], v[66:67], 0, s[8:9]
	s_waitcnt lgkmcnt(0)
	v_add_f32_e32 v64, v64, v65
	global_store_dword v[66:67], v64, off
.LBB0_1159:
	s_or_b64 exec, exec, s[30:31]
	v_add_u32_e32 v64, 0x80, v150
	s_waitcnt lgkmcnt(0)
	v_ashrrev_i32_e32 v65, 31, v64
	v_lshlrev_b64 v[66:67], 11, v[64:65]
	v_lshl_add_u64 v[66:67], s[12:13], 0, v[66:67]
	v_lshl_add_u64 v[74:75], v[148:149], 1, v[66:67]
	global_load_dwordx4 v[66:69], v[74:75], off
	global_load_dwordx4 v[70:73], v[74:75], off offset:256
	s_waitcnt vmcnt(1)
	v_lshlrev_b32_e32 v76, 16, v66
	v_and_b32_e32 v77, 0xffff0000, v66
	v_lshlrev_b32_e32 v66, 16, v67
	v_and_b32_e32 v67, 0xffff0000, v67
	v_lshlrev_b32_e32 v78, 16, v68
	v_and_b32_e32 v79, 0xffff0000, v68
	v_lshlrev_b32_e32 v68, 16, v69
	v_and_b32_e32 v69, 0xffff0000, v69
	s_waitcnt vmcnt(0)
	v_lshlrev_b32_e32 v80, 16, v70
	v_and_b32_e32 v81, 0xffff0000, v70
	v_lshlrev_b32_e32 v70, 16, v71
	v_and_b32_e32 v71, 0xffff0000, v71
	v_lshlrev_b32_e32 v82, 16, v72
	v_and_b32_e32 v83, 0xffff0000, v72
	v_lshlrev_b32_e32 v72, 16, v73
	v_and_b32_e32 v73, 0xffff0000, v73
	v_pk_add_f32 v[60:61], v[60:61], v[76:77]
	v_pk_add_f32 v[62:63], v[62:63], v[66:67]
	v_pk_add_f32 v[56:57], v[56:57], v[78:79]
	v_pk_add_f32 v[58:59], v[58:59], v[68:69]
	v_pk_add_f32 v[52:53], v[52:53], v[80:81]
	v_pk_add_f32 v[54:55], v[54:55], v[70:71]
	v_pk_add_f32 v[66:67], v[48:49], v[82:83]
	v_pk_add_f32 v[68:69], v[50:51], v[72:73]
	v_cvt_pk_bf16_f32 v48, v60, v61
	v_cvt_pk_bf16_f32 v49, v62, v63
	v_pk_mul_f32 v[50:51], v[60:61], v[60:61]
	v_pk_mul_f32 v[60:61], v[62:63], v[62:63]
	v_pk_mul_f32 v[62:63], v[56:57], v[56:57]
	v_pk_mul_f32 v[70:71], v[58:59], v[58:59]
	v_pk_mul_f32 v[72:73], v[52:53], v[52:53]
	v_pk_mul_f32 v[76:77], v[54:55], v[54:55]
	v_pk_mul_f32 v[78:79], v[66:67], v[66:67]
	v_pk_mul_f32 v[80:81], v[68:69], v[68:69]
	v_add_f32_e32 v78, v78, v79
	v_add_f32_e32 v80, v80, v81
	v_add_f32_e32 v76, v76, v77
	v_add_f32_e32 v72, v72, v73
	v_add_f32_e32 v70, v70, v71
	v_add_f32_e32 v62, v62, v63
	v_add_f32_e32 v60, v60, v61
	v_add_f32_e32 v50, v50, v51
	v_add_f32_e32 v51, v78, v80
	v_add_f32_e32 v61, v72, v76
	v_add_f32_e32 v62, v62, v70
	v_add_f32_e32 v50, v50, v60
	v_add_f32_e32 v51, v61, v51
	v_add_f32_e32 v50, v50, v62
	v_add_f32_e32 v60, v50, v51
	v_mov_b32_e32 v61, v60
	s_nop 1
	v_permlane16_swap_b32_e32 v60, v61
	v_cvt_pk_bf16_f32 v50, v56, v57
	v_cvt_pk_bf16_f32 v51, v58, v59
	global_store_dwordx4 v[74:75], v[48:51], off
	s_waitcnt lgkmcnt(0)
	s_nop 0
	v_add_f32_e32 v48, v60, v61
	v_mov_b32_e32 v49, v48
	s_nop 1
	v_permlane32_swap_b32_e32 v48, v49
	v_cvt_pk_bf16_f32 v50, v52, v53
	v_cvt_pk_bf16_f32 v51, v54, v55
	v_cvt_pk_bf16_f32 v52, v66, v67
	v_cvt_pk_bf16_f32 v53, v68, v69
	global_store_dwordx4 v[74:75], v[50:53], off offset:256
	s_and_saveexec_b64 s[30:31], s[4:5]
	s_cbranch_execz .LBB0_1161
	v_lshlrev_b64 v[50:51], 6, v[64:65]
	v_lshl_add_u64 v[50:51], s[14:15], 0, v[50:51]
	v_lshl_add_u64 v[50:51], s[28:29], 2, v[50:51]
	s_lshl_b32 s8, s46, 2
	v_lshl_add_u64 v[50:51], v[50:51], 0, s[8:9]
	s_waitcnt lgkmcnt(0)
	v_add_f32_e32 v48, v48, v49
	global_store_dword v[50:51], v48, off
.LBB0_1161:
	s_or_b64 exec, exec, s[30:31]
	v_add_u32_e32 v48, 0x90, v150
	s_waitcnt lgkmcnt(0)
	v_ashrrev_i32_e32 v49, 31, v48
	v_lshlrev_b64 v[50:51], 11, v[48:49]
	v_lshl_add_u64 v[50:51], s[12:13], 0, v[50:51]
	v_lshl_add_u64 v[58:59], v[148:149], 1, v[50:51]
	global_load_dwordx4 v[50:53], v[58:59], off
	global_load_dwordx4 v[54:57], v[58:59], off offset:256
	s_waitcnt vmcnt(1)
	v_lshlrev_b32_e32 v60, 16, v50
	v_and_b32_e32 v61, 0xffff0000, v50
	v_lshlrev_b32_e32 v50, 16, v51
	v_and_b32_e32 v51, 0xffff0000, v51
	v_lshlrev_b32_e32 v62, 16, v52
	v_and_b32_e32 v63, 0xffff0000, v52
	v_lshlrev_b32_e32 v52, 16, v53
	v_and_b32_e32 v53, 0xffff0000, v53
	s_waitcnt vmcnt(0)
	v_lshlrev_b32_e32 v64, 16, v54
	v_and_b32_e32 v65, 0xffff0000, v54
	v_lshlrev_b32_e32 v54, 16, v55
	v_and_b32_e32 v55, 0xffff0000, v55
	v_lshlrev_b32_e32 v66, 16, v56
	v_and_b32_e32 v67, 0xffff0000, v56
	v_lshlrev_b32_e32 v56, 16, v57
	v_and_b32_e32 v57, 0xffff0000, v57
	v_pk_add_f32 v[44:45], v[44:45], v[60:61]
	v_pk_add_f32 v[46:47], v[46:47], v[50:51]
	v_pk_add_f32 v[40:41], v[40:41], v[62:63]
	v_pk_add_f32 v[42:43], v[42:43], v[52:53]
	v_pk_add_f32 v[36:37], v[36:37], v[64:65]
	v_pk_add_f32 v[38:39], v[38:39], v[54:55]
	v_pk_add_f32 v[50:51], v[32:33], v[66:67]
	v_pk_add_f32 v[52:53], v[34:35], v[56:57]
	v_cvt_pk_bf16_f32 v32, v44, v45
	v_cvt_pk_bf16_f32 v33, v46, v47
	v_pk_mul_f32 v[34:35], v[44:45], v[44:45]
	v_pk_mul_f32 v[44:45], v[46:47], v[46:47]
	v_pk_mul_f32 v[46:47], v[40:41], v[40:41]
	v_pk_mul_f32 v[54:55], v[42:43], v[42:43]
	v_pk_mul_f32 v[56:57], v[36:37], v[36:37]
	v_pk_mul_f32 v[60:61], v[38:39], v[38:39]
	v_pk_mul_f32 v[62:63], v[50:51], v[50:51]
	v_pk_mul_f32 v[64:65], v[52:53], v[52:53]
	v_add_f32_e32 v62, v62, v63
	v_add_f32_e32 v64, v64, v65
	v_add_f32_e32 v60, v60, v61
	v_add_f32_e32 v56, v56, v57
	v_add_f32_e32 v54, v54, v55
	v_add_f32_e32 v46, v46, v47
	v_add_f32_e32 v44, v44, v45
	v_add_f32_e32 v34, v34, v35
	v_add_f32_e32 v35, v62, v64
	v_add_f32_e32 v45, v56, v60
	v_add_f32_e32 v46, v46, v54
	v_add_f32_e32 v34, v34, v44
	v_add_f32_e32 v35, v45, v35
	v_add_f32_e32 v34, v34, v46
	v_add_f32_e32 v44, v34, v35
	v_mov_b32_e32 v45, v44
	s_nop 1
	v_permlane16_swap_b32_e32 v44, v45
	v_cvt_pk_bf16_f32 v34, v40, v41
	v_cvt_pk_bf16_f32 v35, v42, v43
	global_store_dwordx4 v[58:59], v[32:35], off
	s_waitcnt lgkmcnt(0)
	s_nop 0
	v_add_f32_e32 v32, v44, v45
	v_mov_b32_e32 v33, v32
	s_nop 1
	v_permlane32_swap_b32_e32 v32, v33
	v_cvt_pk_bf16_f32 v34, v36, v37
	v_cvt_pk_bf16_f32 v35, v38, v39
	v_cvt_pk_bf16_f32 v36, v50, v51
	v_cvt_pk_bf16_f32 v37, v52, v53
	global_store_dwordx4 v[58:59], v[34:37], off offset:256
	s_and_saveexec_b64 s[30:31], s[4:5]
	s_cbranch_execz .LBB0_1163
	v_lshlrev_b64 v[34:35], 6, v[48:49]
	v_lshl_add_u64 v[34:35], s[14:15], 0, v[34:35]
	v_lshl_add_u64 v[34:35], s[28:29], 2, v[34:35]
	s_lshl_b32 s8, s46, 2
	v_lshl_add_u64 v[34:35], v[34:35], 0, s[8:9]
	s_waitcnt lgkmcnt(0)
	v_add_f32_e32 v32, v32, v33
	global_store_dword v[34:35], v32, off
.LBB0_1163:
	s_or_b64 exec, exec, s[30:31]
	v_add_u32_e32 v32, 0xa0, v150
	s_waitcnt lgkmcnt(0)
	v_ashrrev_i32_e32 v33, 31, v32
	v_lshlrev_b64 v[34:35], 11, v[32:33]
	v_lshl_add_u64 v[34:35], s[12:13], 0, v[34:35]
	v_lshl_add_u64 v[42:43], v[148:149], 1, v[34:35]
	global_load_dwordx4 v[34:37], v[42:43], off
	global_load_dwordx4 v[38:41], v[42:43], off offset:256
	s_waitcnt vmcnt(1)
	v_lshlrev_b32_e32 v44, 16, v34
	v_and_b32_e32 v45, 0xffff0000, v34
	v_lshlrev_b32_e32 v34, 16, v35
	v_and_b32_e32 v35, 0xffff0000, v35
	v_lshlrev_b32_e32 v46, 16, v36
	v_and_b32_e32 v47, 0xffff0000, v36
	v_lshlrev_b32_e32 v36, 16, v37
	v_and_b32_e32 v37, 0xffff0000, v37
	s_waitcnt vmcnt(0)
	v_lshlrev_b32_e32 v48, 16, v38
	v_and_b32_e32 v49, 0xffff0000, v38
	v_lshlrev_b32_e32 v38, 16, v39
	v_and_b32_e32 v39, 0xffff0000, v39
	v_lshlrev_b32_e32 v50, 16, v40
	v_and_b32_e32 v51, 0xffff0000, v40
	v_lshlrev_b32_e32 v40, 16, v41
	v_and_b32_e32 v41, 0xffff0000, v41
	v_pk_add_f32 v[28:29], v[28:29], v[44:45]
	v_pk_add_f32 v[30:31], v[30:31], v[34:35]
	v_pk_add_f32 v[24:25], v[24:25], v[46:47]
	v_pk_add_f32 v[26:27], v[26:27], v[36:37]
	v_pk_add_f32 v[20:21], v[20:21], v[48:49]
	v_pk_add_f32 v[22:23], v[22:23], v[38:39]
	v_pk_add_f32 v[34:35], v[16:17], v[50:51]
	v_pk_add_f32 v[36:37], v[18:19], v[40:41]
	v_cvt_pk_bf16_f32 v16, v28, v29
	v_cvt_pk_bf16_f32 v17, v30, v31
	v_pk_mul_f32 v[18:19], v[28:29], v[28:29]
	v_pk_mul_f32 v[28:29], v[30:31], v[30:31]
	v_pk_mul_f32 v[30:31], v[24:25], v[24:25]
	v_pk_mul_f32 v[38:39], v[26:27], v[26:27]
	v_pk_mul_f32 v[40:41], v[20:21], v[20:21]
	v_pk_mul_f32 v[44:45], v[22:23], v[22:23]
	v_pk_mul_f32 v[46:47], v[34:35], v[34:35]
	v_pk_mul_f32 v[48:49], v[36:37], v[36:37]
	v_add_f32_e32 v46, v46, v47
	v_add_f32_e32 v48, v48, v49
	v_add_f32_e32 v44, v44, v45
	v_add_f32_e32 v40, v40, v41
	v_add_f32_e32 v38, v38, v39
	v_add_f32_e32 v30, v30, v31
	v_add_f32_e32 v28, v28, v29
	v_add_f32_e32 v18, v18, v19
	v_add_f32_e32 v19, v46, v48
	v_add_f32_e32 v29, v40, v44
	v_add_f32_e32 v30, v30, v38
	v_add_f32_e32 v18, v18, v28
	v_add_f32_e32 v19, v29, v19
	v_add_f32_e32 v18, v18, v30
	v_add_f32_e32 v28, v18, v19
	v_mov_b32_e32 v29, v28
	s_nop 1
	v_permlane16_swap_b32_e32 v28, v29
	v_cvt_pk_bf16_f32 v18, v24, v25
	v_cvt_pk_bf16_f32 v19, v26, v27
	global_store_dwordx4 v[42:43], v[16:19], off
	s_waitcnt lgkmcnt(0)
	s_nop 0
	v_add_f32_e32 v16, v28, v29
	v_mov_b32_e32 v17, v16
	s_nop 1
	v_permlane32_swap_b32_e32 v16, v17
	v_cvt_pk_bf16_f32 v18, v20, v21
	v_cvt_pk_bf16_f32 v19, v22, v23
	v_cvt_pk_bf16_f32 v20, v34, v35
	v_cvt_pk_bf16_f32 v21, v36, v37
	global_store_dwordx4 v[42:43], v[18:21], off offset:256
	s_and_saveexec_b64 s[30:31], s[4:5]
	s_cbranch_execz .LBB0_1165
	v_lshlrev_b64 v[18:19], 6, v[32:33]
	v_lshl_add_u64 v[18:19], s[14:15], 0, v[18:19]
	v_lshl_add_u64 v[18:19], s[28:29], 2, v[18:19]
	s_lshl_b32 s8, s46, 2
	v_lshl_add_u64 v[18:19], v[18:19], 0, s[8:9]
	s_waitcnt lgkmcnt(0)
	v_add_f32_e32 v16, v16, v17
	global_store_dword v[18:19], v16, off
.LBB0_1165:
	s_or_b64 exec, exec, s[30:31]
	v_add_u32_e32 v16, 0xb0, v150
	s_waitcnt lgkmcnt(0)
	v_ashrrev_i32_e32 v17, 31, v16
	v_lshlrev_b64 v[18:19], 11, v[16:17]
	v_lshl_add_u64 v[18:19], s[12:13], 0, v[18:19]
	v_lshl_add_u64 v[26:27], v[148:149], 1, v[18:19]
	global_load_dwordx4 v[18:21], v[26:27], off
	global_load_dwordx4 v[22:25], v[26:27], off offset:256
	s_waitcnt vmcnt(1)
	v_lshlrev_b32_e32 v28, 16, v18
	v_and_b32_e32 v29, 0xffff0000, v18
	v_lshlrev_b32_e32 v18, 16, v19
	v_and_b32_e32 v19, 0xffff0000, v19
	v_lshlrev_b32_e32 v30, 16, v20
	v_and_b32_e32 v31, 0xffff0000, v20
	v_lshlrev_b32_e32 v20, 16, v21
	v_and_b32_e32 v21, 0xffff0000, v21
	s_waitcnt vmcnt(0)
	v_lshlrev_b32_e32 v32, 16, v22
	v_and_b32_e32 v33, 0xffff0000, v22
	v_lshlrev_b32_e32 v22, 16, v23
	v_and_b32_e32 v23, 0xffff0000, v23
	v_lshlrev_b32_e32 v34, 16, v24
	v_and_b32_e32 v35, 0xffff0000, v24
	v_lshlrev_b32_e32 v24, 16, v25
	v_and_b32_e32 v25, 0xffff0000, v25
	v_pk_add_f32 v[12:13], v[12:13], v[28:29]
	v_pk_add_f32 v[14:15], v[14:15], v[18:19]
	v_pk_add_f32 v[8:9], v[8:9], v[30:31]
	v_pk_add_f32 v[10:11], v[10:11], v[20:21]
	v_pk_add_f32 v[4:5], v[4:5], v[32:33]
	v_pk_add_f32 v[6:7], v[6:7], v[22:23]
	v_pk_add_f32 v[18:19], v[0:1], v[34:35]
	v_pk_add_f32 v[20:21], v[2:3], v[24:25]
	v_cvt_pk_bf16_f32 v0, v12, v13
	v_cvt_pk_bf16_f32 v1, v14, v15
	v_pk_mul_f32 v[2:3], v[12:13], v[12:13]
	v_pk_mul_f32 v[12:13], v[14:15], v[14:15]
	v_pk_mul_f32 v[14:15], v[8:9], v[8:9]
	v_pk_mul_f32 v[22:23], v[10:11], v[10:11]
	v_pk_mul_f32 v[24:25], v[4:5], v[4:5]
	v_pk_mul_f32 v[28:29], v[6:7], v[6:7]
	v_pk_mul_f32 v[30:31], v[18:19], v[18:19]
	v_pk_mul_f32 v[32:33], v[20:21], v[20:21]
	v_add_f32_e32 v30, v30, v31
	v_add_f32_e32 v32, v32, v33
	v_add_f32_e32 v28, v28, v29
	v_add_f32_e32 v24, v24, v25
	v_add_f32_e32 v22, v22, v23
	v_add_f32_e32 v14, v14, v15
	v_add_f32_e32 v12, v12, v13
	v_add_f32_e32 v2, v2, v3
	v_add_f32_e32 v3, v30, v32
	v_add_f32_e32 v13, v24, v28
	v_add_f32_e32 v14, v14, v22
	v_add_f32_e32 v2, v2, v12
	v_add_f32_e32 v3, v13, v3
	v_add_f32_e32 v2, v2, v14
	v_add_f32_e32 v12, v2, v3
	v_mov_b32_e32 v13, v12
	s_nop 1
	v_permlane16_swap_b32_e32 v12, v13
	v_cvt_pk_bf16_f32 v2, v8, v9
	v_cvt_pk_bf16_f32 v3, v10, v11
	global_store_dwordx4 v[26:27], v[0:3], off
	s_waitcnt lgkmcnt(0)
	s_nop 0
	v_add_f32_e32 v0, v12, v13
	v_mov_b32_e32 v1, v0
	s_nop 1
	v_permlane32_swap_b32_e32 v0, v1
	v_cvt_pk_bf16_f32 v2, v4, v5
	v_cvt_pk_bf16_f32 v3, v6, v7
	v_cvt_pk_bf16_f32 v4, v18, v19
	v_cvt_pk_bf16_f32 v5, v20, v21
	global_store_dwordx4 v[26:27], v[2:5], off offset:256
	s_and_saveexec_b64 s[30:31], s[4:5]
	s_cbranch_execz .LBB0_1167
	v_lshlrev_b64 v[2:3], 6, v[16:17]
	v_lshl_add_u64 v[2:3], s[14:15], 0, v[2:3]
	v_lshl_add_u64 v[2:3], s[28:29], 2, v[2:3]
	s_lshl_b32 s8, s46, 2
	v_lshl_add_u64 v[2:3], v[2:3], 0, s[8:9]
	s_waitcnt lgkmcnt(0)
	v_add_f32_e32 v0, v0, v1
	global_store_dword v[2:3], v0, off

.LBB0_1238:
	v_lshl_add_u32 v152, s0, 8, v131
	v_ashrrev_i32_e32 v153, 31, v152
	v_lshlrev_b64 v[150:151], 6, v[152:153]
	v_lshl_add_u64 v[150:151], v[140:141], 0, v[150:151]
	global_load_dwordx4 v[162:165], v[150:151], off
	v_and_b32_e32 v161, 64, v159
	v_xor_b32_e32 v153, 16, v159
	v_pk_mul_f32 v[168:169], v[114:115], v[122:123]
	v_add_u32_e32 v122, 64, v161
	v_cmp_lt_i32_e32 vcc, v153, v122
	v_pk_mul_f32 v[170:171], v[112:113], v[120:121]
	v_xor_b32_e32 v172, 32, v159
	v_cndmask_b32_e32 v120, v159, v153, vcc
	v_lshlrev_b32_e32 v123, 2, v120
	v_cmp_lt_i32_e32 vcc, v172, v122
	v_pk_mul_f32 v[126:127], v[118:119], v[126:127]
	v_pk_mul_f32 v[124:125], v[116:117], v[124:125]
	v_cndmask_b32_e32 v122, v159, v172, vcc
	v_lshlrev_b32_e32 v122, 2, v122
	v_lshl_or_b32 v166, s1, 7, v155
	v_ashrrev_i32_e32 v167, 31, v166
	v_mov_b64_e32 v[150:151], s[10:11]
	v_pk_mul_f32 v[110:111], v[102:103], v[110:111]
	v_pk_mul_f32 v[108:109], v[100:101], v[108:109]
	v_pk_mul_f32 v[106:107], v[98:99], v[106:107]
	v_pk_mul_f32 v[104:105], v[96:97], v[104:105]
	v_pk_mul_f32 v[94:95], v[86:87], v[94:95]
	v_pk_mul_f32 v[92:93], v[84:85], v[92:93]
	v_pk_mul_f32 v[90:91], v[82:83], v[90:91]
	v_pk_mul_f32 v[88:89], v[80:81], v[88:89]
	v_pk_mul_f32 v[78:79], v[70:71], v[78:79]
	v_pk_mul_f32 v[76:77], v[68:69], v[76:77]
	v_pk_mul_f32 v[74:75], v[66:67], v[74:75]
	v_pk_mul_f32 v[72:73], v[64:65], v[72:73]
	v_pk_mul_f32 v[62:63], v[54:55], v[62:63]
	v_pk_mul_f32 v[60:61], v[52:53], v[60:61]
	v_pk_mul_f32 v[58:59], v[50:51], v[58:59]
	v_pk_mul_f32 v[56:57], v[48:49], v[56:57]
	v_pk_mul_f32 v[46:47], v[38:39], v[46:47]
	v_pk_mul_f32 v[44:45], v[36:37], v[44:45]
	v_pk_mul_f32 v[42:43], v[34:35], v[42:43]
	v_pk_mul_f32 v[40:41], v[32:33], v[40:41]
	v_pk_mul_f32 v[30:31], v[22:23], v[30:31]
	v_pk_mul_f32 v[28:29], v[20:21], v[28:29]
	v_pk_mul_f32 v[26:27], v[18:19], v[26:27]
	v_pk_mul_f32 v[24:25], v[16:17], v[24:25]
	v_pk_mul_f32 v[14:15], v[6:7], v[14:15]
	v_pk_mul_f32 v[12:13], v[4:5], v[12:13]
	v_pk_mul_f32 v[10:11], v[2:3], v[10:11]
	v_pk_mul_f32 v[8:9], v[0:1], v[8:9]
	s_waitcnt vmcnt(0)
	v_mov_b32_e32 v120, v163
	v_mov_b32_e32 v121, v164
	v_mov_b32_e32 v163, v165
	v_pk_add_f32 v[120:121], v[120:121], v[162:163]
	v_or_b32_e32 v164, 16, v152
	v_add_f32_e32 v120, v120, v121
	v_mov_b32_e32 v121, v120
	s_nop 1
	v_permlane16_swap_b32_e32 v120, v121
	v_ashrrev_i32_e32 v165, 31, v164
	v_mad_i64_i32 v[162:163], s[0:1], v152, s49, v[150:151]
	s_waitcnt lgkmcnt(0)
	v_add_f32_e32 v153, v120, v121
	v_mov_b32_e32 v161, v153
	s_nop 1
	v_permlane32_swap_b32_e32 v153, v161
	v_lshlrev_b64 v[120:121], 1, v[166:167]
	v_lshlrev_b64 v[166:167], 6, v[164:165]
	v_lshl_add_u64 v[162:163], v[162:163], 0, v[120:121]
	v_lshl_add_u64 v[166:167], v[140:141], 0, v[166:167]
	s_waitcnt lgkmcnt(0)
	v_add_f32_e32 v153, v153, v161
	v_fmamk_f32 v153, v153, 0x3a800000, v160
	v_mul_f32_e32 v161, 0x4b800000, v153
	v_cmp_gt_f32_e32 vcc, s52, v153
	s_nop 1
	v_cndmask_b32_e32 v153, v153, v161, vcc
	v_rsq_f32_e32 v153, v153
	s_nop 0
	v_mul_f32_e32 v161, 0x45800000, v153
	v_cndmask_b32_e32 v153, v153, v161, vcc
	v_mul_f32_e32 v161, 0xbfb8aa3b, v153
	v_mul_f32_e32 v116, v116, v161
	v_mul_f32_e32 v117, v117, v161
	v_mul_f32_e32 v118, v118, v161
	v_mul_f32_e32 v119, v119, v161
	v_mul_f32_e32 v112, v112, v161
	v_mul_f32_e32 v113, v113, v161
	v_mul_f32_e32 v114, v114, v161
	v_mul_f32_e32 v115, v115, v161
	v_exp_f32_e32 v116, v116
	v_exp_f32_e32 v117, v117
	v_exp_f32_e32 v118, v118
	v_exp_f32_e32 v119, v119
	v_exp_f32_e32 v112, v112
	v_exp_f32_e32 v113, v113
	v_exp_f32_e32 v114, v114
	v_exp_f32_e32 v115, v115
	v_mul_f32_e32 v172, v153, v153
	v_add_f32_e32 v116, 1.0, v116
	v_add_f32_e32 v117, 1.0, v117
	v_add_f32_e32 v118, 1.0, v118
	v_add_f32_e32 v119, 1.0, v119
	v_add_f32_e32 v153, 1.0, v112
	v_add_f32_e32 v161, 1.0, v113
	v_add_f32_e32 v165, 1.0, v114
	v_add_f32_e32 v173, 1.0, v115
	v_rcp_f32_e32 v112, v116
	v_rcp_f32_e32 v113, v117
	v_rcp_f32_e32 v114, v118
	v_rcp_f32_e32 v115, v119
	v_rcp_f32_e32 v116, v153
	v_rcp_f32_e32 v117, v161
	v_rcp_f32_e32 v118, v165
	v_rcp_f32_e32 v119, v173
	v_pk_mul_f32 v[112:113], v[172:173], v[112:113] op_sel_hi:[0,1]
	v_pk_mul_f32 v[114:115], v[172:173], v[114:115] op_sel_hi:[0,1]
	v_pk_mul_f32 v[116:117], v[172:173], v[116:117] op_sel_hi:[0,1]
	v_pk_mul_f32 v[118:119], v[172:173], v[118:119] op_sel_hi:[0,1]
	v_pk_mul_f32 v[112:113], v[124:125], v[112:113]
	v_pk_mul_f32 v[114:115], v[126:127], v[114:115]
	v_pk_mul_f32 v[116:117], v[170:171], v[116:117]
	v_pk_mul_f32 v[118:119], v[168:169], v[118:119]
	v_cvt_pk_bf16_f32 v112, v112, v113
	v_cvt_pk_bf16_f32 v113, v114, v115
	v_cvt_pk_bf16_f32 v114, v116, v117
	v_cvt_pk_bf16_f32 v115, v118, v119
	global_store_dwordx4 v[162:163], v[112:115], off
	global_load_dwordx4 v[112:115], v[166:167], off
	s_waitcnt vmcnt(0)
	v_mov_b32_e32 v116, v113
	v_mov_b32_e32 v117, v114
	v_mov_b32_e32 v113, v115
	v_pk_add_f32 v[112:113], v[116:117], v[112:113]
	v_mad_i64_i32 v[114:115], s[0:1], v164, s49, v[150:151]
	v_add_f32_e32 v112, v112, v113
	v_mov_b32_e32 v113, v112
	s_nop 1
	v_permlane16_swap_b32_e32 v112, v113
	v_lshl_add_u64 v[114:115], v[114:115], 0, v[120:121]
	s_waitcnt lgkmcnt(0)
	v_add_f32_e32 v116, v112, v113
	v_mov_b32_e32 v117, v116
	s_nop 1
	v_permlane32_swap_b32_e32 v116, v117
	v_or_b32_e32 v112, 32, v152
	v_ashrrev_i32_e32 v113, 31, v112
	s_waitcnt lgkmcnt(0)
	v_add_f32_e32 v116, v116, v117
	v_fmamk_f32 v116, v116, 0x3a800000, v160
	v_mul_f32_e32 v117, 0x4b800000, v116
	v_cmp_gt_f32_e32 vcc, s52, v116
	s_nop 1
	v_cndmask_b32_e32 v116, v116, v117, vcc
	v_rsq_f32_e32 v118, v116
	v_lshlrev_b64 v[116:117], 6, v[112:113]
	v_lshl_add_u64 v[116:117], v[140:141], 0, v[116:117]
	v_mul_f32_e32 v113, 0x45800000, v118
	v_cndmask_b32_e32 v113, v118, v113, vcc
	v_mul_f32_e32 v119, 0xbfb8aa3b, v113
	v_mul_f32_e32 v100, v100, v119
	v_mul_f32_e32 v101, v101, v119
	v_mul_f32_e32 v102, v102, v119
	v_mul_f32_e32 v103, v103, v119
	v_mul_f32_e32 v96, v96, v119
	v_mul_f32_e32 v97, v97, v119
	v_mul_f32_e32 v98, v98, v119
	v_mul_f32_e32 v99, v99, v119
	v_exp_f32_e32 v100, v100
	v_exp_f32_e32 v101, v101
	v_exp_f32_e32 v102, v102
	v_exp_f32_e32 v103, v103
	v_exp_f32_e32 v96, v96
	v_exp_f32_e32 v97, v97
	v_exp_f32_e32 v98, v98
	v_exp_f32_e32 v99, v99
	v_mul_f32_e32 v118, v113, v113
	v_add_f32_e32 v100, 1.0, v100
	v_add_f32_e32 v101, 1.0, v101
	v_add_f32_e32 v102, 1.0, v102
	v_add_f32_e32 v103, 1.0, v103
	v_add_f32_e32 v113, 1.0, v96
	v_add_f32_e32 v119, 1.0, v97
	v_add_f32_e32 v124, 1.0, v98
	v_add_f32_e32 v125, 1.0, v99
	v_rcp_f32_e32 v96, v100
	v_rcp_f32_e32 v97, v101
	v_rcp_f32_e32 v98, v102
	v_rcp_f32_e32 v99, v103
	v_rcp_f32_e32 v100, v113
	v_rcp_f32_e32 v101, v119
	v_rcp_f32_e32 v102, v124
	v_rcp_f32_e32 v103, v125
	v_pk_mul_f32 v[96:97], v[118:119], v[96:97] op_sel_hi:[0,1]
	v_pk_mul_f32 v[98:99], v[118:119], v[98:99] op_sel_hi:[0,1]
	v_pk_mul_f32 v[100:101], v[118:119], v[100:101] op_sel_hi:[0,1]
	v_pk_mul_f32 v[102:103], v[118:119], v[102:103] op_sel_hi:[0,1]
	v_pk_mul_f32 v[96:97], v[108:109], v[96:97]
	v_pk_mul_f32 v[98:99], v[110:111], v[98:99]
	v_pk_mul_f32 v[100:101], v[104:105], v[100:101]
	v_pk_mul_f32 v[102:103], v[106:107], v[102:103]
	v_cvt_pk_bf16_f32 v96, v96, v97
	v_cvt_pk_bf16_f32 v97, v98, v99
	v_cvt_pk_bf16_f32 v98, v100, v101
	v_cvt_pk_bf16_f32 v99, v102, v103
	global_store_dwordx4 v[114:115], v[96:99], off
	global_load_dwordx4 v[96:99], v[116:117], off
	s_waitcnt vmcnt(0)
	v_mov_b32_e32 v100, v97
	v_mov_b32_e32 v101, v98
	v_mov_b32_e32 v97, v99
	v_pk_add_f32 v[96:97], v[100:101], v[96:97]
	v_mad_i64_i32 v[98:99], s[0:1], v112, s49, v[150:151]
	v_add_f32_e32 v96, v96, v97
	v_mov_b32_e32 v97, v96
	s_nop 1
	v_permlane16_swap_b32_e32 v96, v97
	v_lshl_add_u64 v[98:99], v[98:99], 0, v[120:121]
	s_waitcnt lgkmcnt(0)
	v_add_f32_e32 v100, v96, v97
	v_mov_b32_e32 v101, v100
	s_nop 1
	v_permlane32_swap_b32_e32 v100, v101
	v_or_b32_e32 v96, 48, v152
	v_ashrrev_i32_e32 v97, 31, v96
	s_waitcnt lgkmcnt(0)
	v_add_f32_e32 v100, v100, v101
	v_fmamk_f32 v100, v100, 0x3a800000, v160
	v_mul_f32_e32 v101, 0x4b800000, v100
	v_cmp_gt_f32_e32 vcc, s52, v100
	s_nop 1
	v_cndmask_b32_e32 v100, v100, v101, vcc
	v_rsq_f32_e32 v102, v100
	v_lshlrev_b64 v[100:101], 6, v[96:97]
	v_lshl_add_u64 v[100:101], v[140:141], 0, v[100:101]
	v_mul_f32_e32 v97, 0x45800000, v102
	v_cndmask_b32_e32 v97, v102, v97, vcc
	v_mul_f32_e32 v103, 0xbfb8aa3b, v97
	v_mul_f32_e32 v84, v84, v103
	v_mul_f32_e32 v85, v85, v103
	v_mul_f32_e32 v86, v86, v103
	v_mul_f32_e32 v87, v87, v103
	v_mul_f32_e32 v80, v80, v103
	v_mul_f32_e32 v81, v81, v103
	v_mul_f32_e32 v82, v82, v103
	v_mul_f32_e32 v83, v83, v103
	v_exp_f32_e32 v84, v84
	v_exp_f32_e32 v85, v85
	v_exp_f32_e32 v86, v86
	v_exp_f32_e32 v87, v87
	v_exp_f32_e32 v80, v80
	v_exp_f32_e32 v81, v81
	v_exp_f32_e32 v82, v82
	v_exp_f32_e32 v83, v83
	v_mul_f32_e32 v102, v97, v97
	v_add_f32_e32 v84, 1.0, v84
	v_add_f32_e32 v85, 1.0, v85
	v_add_f32_e32 v86, 1.0, v86
	v_add_f32_e32 v87, 1.0, v87
	v_add_f32_e32 v97, 1.0, v80
	v_add_f32_e32 v103, 1.0, v81
	v_add_f32_e32 v104, 1.0, v82
	v_add_f32_e32 v105, 1.0, v83
	v_rcp_f32_e32 v80, v84
	v_rcp_f32_e32 v81, v85
	v_rcp_f32_e32 v82, v86
	v_rcp_f32_e32 v83, v87
	v_rcp_f32_e32 v84, v97
	v_rcp_f32_e32 v85, v103
	v_rcp_f32_e32 v86, v104
	v_rcp_f32_e32 v87, v105
	v_pk_mul_f32 v[80:81], v[102:103], v[80:81] op_sel_hi:[0,1]
	v_pk_mul_f32 v[82:83], v[102:103], v[82:83] op_sel_hi:[0,1]
	v_pk_mul_f32 v[84:85], v[102:103], v[84:85] op_sel_hi:[0,1]
	v_pk_mul_f32 v[86:87], v[102:103], v[86:87] op_sel_hi:[0,1]
	v_pk_mul_f32 v[80:81], v[92:93], v[80:81]
	v_pk_mul_f32 v[82:83], v[94:95], v[82:83]
	v_pk_mul_f32 v[84:85], v[88:89], v[84:85]
	v_pk_mul_f32 v[86:87], v[90:91], v[86:87]
	v_cvt_pk_bf16_f32 v80, v80, v81
	v_cvt_pk_bf16_f32 v81, v82, v83
	v_cvt_pk_bf16_f32 v82, v84, v85
	v_cvt_pk_bf16_f32 v83, v86, v87
	global_store_dwordx4 v[98:99], v[80:83], off
	global_load_dwordx4 v[80:83], v[100:101], off
	s_waitcnt vmcnt(0)
	v_mov_b32_e32 v84, v81
	v_mov_b32_e32 v85, v82
	v_mov_b32_e32 v81, v83
	v_pk_add_f32 v[80:81], v[84:85], v[80:81]
	v_mad_i64_i32 v[82:83], s[0:1], v96, s49, v[150:151]
	v_add_f32_e32 v80, v80, v81
	v_mov_b32_e32 v81, v80
	s_nop 1
	v_permlane16_swap_b32_e32 v80, v81
	v_lshl_add_u64 v[82:83], v[82:83], 0, v[120:121]
	s_waitcnt lgkmcnt(0)
	v_add_f32_e32 v84, v80, v81
	v_mov_b32_e32 v85, v84
	s_nop 1
	v_permlane32_swap_b32_e32 v84, v85
	v_add_u32_e32 v80, 0x80, v152
	v_ashrrev_i32_e32 v81, 31, v80
	s_waitcnt lgkmcnt(0)
	v_add_f32_e32 v84, v84, v85
	v_fmamk_f32 v84, v84, 0x3a800000, v160
	v_mul_f32_e32 v85, 0x4b800000, v84
	v_cmp_gt_f32_e32 vcc, s52, v84
	s_nop 1
	v_cndmask_b32_e32 v84, v84, v85, vcc
	v_rsq_f32_e32 v86, v84
	v_lshlrev_b64 v[84:85], 6, v[80:81]
	v_lshl_add_u64 v[84:85], v[140:141], 0, v[84:85]
	v_mul_f32_e32 v81, 0x45800000, v86
	v_cndmask_b32_e32 v81, v86, v81, vcc
	v_mul_f32_e32 v87, 0xbfb8aa3b, v81
	v_mul_f32_e32 v68, v68, v87
	v_mul_f32_e32 v69, v69, v87
	v_mul_f32_e32 v70, v70, v87
	v_mul_f32_e32 v71, v71, v87
	v_mul_f32_e32 v64, v64, v87
	v_mul_f32_e32 v65, v65, v87
	v_mul_f32_e32 v66, v66, v87
	v_mul_f32_e32 v67, v67, v87
	v_exp_f32_e32 v68, v68
	v_exp_f32_e32 v69, v69
	v_exp_f32_e32 v70, v70
	v_exp_f32_e32 v71, v71
	v_exp_f32_e32 v64, v64
	v_exp_f32_e32 v65, v65
	v_exp_f32_e32 v66, v66
	v_exp_f32_e32 v67, v67
	v_mul_f32_e32 v86, v81, v81
	v_add_f32_e32 v68, 1.0, v68
	v_add_f32_e32 v69, 1.0, v69
	v_add_f32_e32 v70, 1.0, v70
	v_add_f32_e32 v71, 1.0, v71
	v_add_f32_e32 v81, 1.0, v64
	v_add_f32_e32 v87, 1.0, v65
	v_add_f32_e32 v88, 1.0, v66
	v_add_f32_e32 v89, 1.0, v67
	v_rcp_f32_e32 v64, v68
	v_rcp_f32_e32 v65, v69
	v_rcp_f32_e32 v66, v70
	v_rcp_f32_e32 v67, v71
	v_rcp_f32_e32 v68, v81
	v_rcp_f32_e32 v69, v87
	v_rcp_f32_e32 v70, v88
	v_rcp_f32_e32 v71, v89
	v_pk_mul_f32 v[64:65], v[86:87], v[64:65] op_sel_hi:[0,1]
	v_pk_mul_f32 v[66:67], v[86:87], v[66:67] op_sel_hi:[0,1]
	v_pk_mul_f32 v[68:69], v[86:87], v[68:69] op_sel_hi:[0,1]
	v_pk_mul_f32 v[70:71], v[86:87], v[70:71] op_sel_hi:[0,1]
	v_pk_mul_f32 v[64:65], v[76:77], v[64:65]
	v_pk_mul_f32 v[66:67], v[78:79], v[66:67]
	v_pk_mul_f32 v[68:69], v[72:73], v[68:69]
	v_pk_mul_f32 v[70:71], v[74:75], v[70:71]
	v_cvt_pk_bf16_f32 v64, v64, v65
	v_cvt_pk_bf16_f32 v65, v66, v67
	v_cvt_pk_bf16_f32 v66, v68, v69
	v_cvt_pk_bf16_f32 v67, v70, v71
	global_store_dwordx4 v[82:83], v[64:67], off
	global_load_dwordx4 v[64:67], v[84:85], off
	s_waitcnt vmcnt(0)
	v_mov_b32_e32 v68, v65
	v_mov_b32_e32 v69, v66
	v_mov_b32_e32 v65, v67
	v_pk_add_f32 v[64:65], v[68:69], v[64:65]
	v_mad_i64_i32 v[66:67], s[0:1], v80, s49, v[150:151]
	v_add_f32_e32 v64, v64, v65
	v_mov_b32_e32 v65, v64
	s_nop 1
	v_permlane16_swap_b32_e32 v64, v65
	v_lshl_add_u64 v[66:67], v[66:67], 0, v[120:121]
	s_waitcnt lgkmcnt(0)
	v_add_f32_e32 v68, v64, v65
	v_mov_b32_e32 v69, v68
	s_nop 1
	v_permlane32_swap_b32_e32 v68, v69
	v_add_u32_e32 v64, 0x90, v152
	v_ashrrev_i32_e32 v65, 31, v64
	s_waitcnt lgkmcnt(0)
	v_add_f32_e32 v68, v68, v69
	v_fmamk_f32 v68, v68, 0x3a800000, v160
	v_mul_f32_e32 v69, 0x4b800000, v68
	v_cmp_gt_f32_e32 vcc, s52, v68
	s_nop 1
	v_cndmask_b32_e32 v68, v68, v69, vcc
	v_rsq_f32_e32 v70, v68
	v_lshlrev_b64 v[68:69], 6, v[64:65]
	v_lshl_add_u64 v[68:69], v[140:141], 0, v[68:69]
	v_mul_f32_e32 v65, 0x45800000, v70
	v_cndmask_b32_e32 v65, v70, v65, vcc
	v_mul_f32_e32 v71, 0xbfb8aa3b, v65
	v_mul_f32_e32 v52, v52, v71
	v_mul_f32_e32 v53, v53, v71
	v_mul_f32_e32 v54, v54, v71
	v_mul_f32_e32 v55, v55, v71
	v_mul_f32_e32 v48, v48, v71
	v_mul_f32_e32 v49, v49, v71
	v_mul_f32_e32 v50, v50, v71
	v_mul_f32_e32 v51, v51, v71
	v_exp_f32_e32 v52, v52
	v_exp_f32_e32 v53, v53
	v_exp_f32_e32 v54, v54
	v_exp_f32_e32 v55, v55
	v_exp_f32_e32 v48, v48
	v_exp_f32_e32 v49, v49
	v_exp_f32_e32 v50, v50
	v_exp_f32_e32 v51, v51
	v_mul_f32_e32 v70, v65, v65
	v_add_f32_e32 v52, 1.0, v52
	v_add_f32_e32 v53, 1.0, v53
	v_add_f32_e32 v54, 1.0, v54
	v_add_f32_e32 v55, 1.0, v55
	v_add_f32_e32 v65, 1.0, v48
	v_add_f32_e32 v71, 1.0, v49
	v_add_f32_e32 v72, 1.0, v50
	v_add_f32_e32 v73, 1.0, v51
	v_rcp_f32_e32 v48, v52
	v_rcp_f32_e32 v49, v53
	v_rcp_f32_e32 v50, v54
	v_rcp_f32_e32 v51, v55
	v_rcp_f32_e32 v52, v65
	v_rcp_f32_e32 v53, v71
	v_rcp_f32_e32 v54, v72
	v_rcp_f32_e32 v55, v73
	v_pk_mul_f32 v[48:49], v[70:71], v[48:49] op_sel_hi:[0,1]
	v_pk_mul_f32 v[50:51], v[70:71], v[50:51] op_sel_hi:[0,1]
	v_pk_mul_f32 v[52:53], v[70:71], v[52:53] op_sel_hi:[0,1]
	v_pk_mul_f32 v[54:55], v[70:71], v[54:55] op_sel_hi:[0,1]
	v_pk_mul_f32 v[48:49], v[60:61], v[48:49]
	v_pk_mul_f32 v[50:51], v[62:63], v[50:51]
	v_pk_mul_f32 v[52:53], v[56:57], v[52:53]
	v_pk_mul_f32 v[54:55], v[58:59], v[54:55]
	v_cvt_pk_bf16_f32 v48, v48, v49
	v_cvt_pk_bf16_f32 v49, v50, v51
	v_cvt_pk_bf16_f32 v50, v52, v53
	v_cvt_pk_bf16_f32 v51, v54, v55
	global_store_dwordx4 v[66:67], v[48:51], off
	global_load_dwordx4 v[48:51], v[68:69], off
	s_waitcnt vmcnt(0)
	v_mov_b32_e32 v52, v49
	v_mov_b32_e32 v53, v50
	v_mov_b32_e32 v49, v51
	v_pk_add_f32 v[48:49], v[52:53], v[48:49]
	v_mad_i64_i32 v[50:51], s[0:1], v64, s49, v[150:151]
	v_add_f32_e32 v48, v48, v49
	v_mov_b32_e32 v49, v48
	s_nop 1
	v_permlane16_swap_b32_e32 v48, v49
	v_lshl_add_u64 v[50:51], v[50:51], 0, v[120:121]
	s_waitcnt lgkmcnt(0)
	v_add_f32_e32 v52, v48, v49
	v_mov_b32_e32 v53, v52
	s_nop 1
	v_permlane32_swap_b32_e32 v52, v53
	v_add_u32_e32 v48, 0xa0, v152
	v_ashrrev_i32_e32 v49, 31, v48
	s_waitcnt lgkmcnt(0)
	v_add_f32_e32 v52, v52, v53
	v_fmamk_f32 v52, v52, 0x3a800000, v160
	v_mul_f32_e32 v53, 0x4b800000, v52
	v_cmp_gt_f32_e32 vcc, s52, v52
	s_nop 1
	v_cndmask_b32_e32 v52, v52, v53, vcc
	v_rsq_f32_e32 v54, v52
	v_lshlrev_b64 v[52:53], 6, v[48:49]
	v_lshl_add_u64 v[52:53], v[140:141], 0, v[52:53]
	v_mul_f32_e32 v49, 0x45800000, v54
	v_cndmask_b32_e32 v49, v54, v49, vcc
	v_mul_f32_e32 v55, 0xbfb8aa3b, v49
	v_mul_f32_e32 v36, v36, v55
	v_mul_f32_e32 v37, v37, v55
	v_mul_f32_e32 v38, v38, v55
	v_mul_f32_e32 v39, v39, v55
	v_mul_f32_e32 v32, v32, v55
	v_mul_f32_e32 v33, v33, v55
	v_mul_f32_e32 v34, v34, v55
	v_mul_f32_e32 v35, v35, v55
	v_exp_f32_e32 v36, v36
	v_exp_f32_e32 v37, v37
	v_exp_f32_e32 v38, v38
	v_exp_f32_e32 v39, v39
	v_exp_f32_e32 v32, v32
	v_exp_f32_e32 v33, v33
	v_exp_f32_e32 v34, v34
	v_exp_f32_e32 v35, v35
	v_mul_f32_e32 v54, v49, v49
	v_add_f32_e32 v36, 1.0, v36
	v_add_f32_e32 v37, 1.0, v37
	v_add_f32_e32 v38, 1.0, v38
	v_add_f32_e32 v39, 1.0, v39
	v_add_f32_e32 v49, 1.0, v32
	v_add_f32_e32 v55, 1.0, v33
	v_add_f32_e32 v56, 1.0, v34
	v_add_f32_e32 v57, 1.0, v35
	v_rcp_f32_e32 v32, v36
	v_rcp_f32_e32 v33, v37
	v_rcp_f32_e32 v34, v38
	v_rcp_f32_e32 v35, v39
	v_rcp_f32_e32 v36, v49
	v_rcp_f32_e32 v37, v55
	v_rcp_f32_e32 v38, v56
	v_rcp_f32_e32 v39, v57
	v_pk_mul_f32 v[32:33], v[54:55], v[32:33] op_sel_hi:[0,1]
	v_pk_mul_f32 v[34:35], v[54:55], v[34:35] op_sel_hi:[0,1]
	v_pk_mul_f32 v[36:37], v[54:55], v[36:37] op_sel_hi:[0,1]
	v_pk_mul_f32 v[38:39], v[54:55], v[38:39] op_sel_hi:[0,1]
	v_pk_mul_f32 v[32:33], v[44:45], v[32:33]
	v_pk_mul_f32 v[34:35], v[46:47], v[34:35]
	v_pk_mul_f32 v[36:37], v[40:41], v[36:37]
	v_pk_mul_f32 v[38:39], v[42:43], v[38:39]
	v_cvt_pk_bf16_f32 v32, v32, v33
	v_cvt_pk_bf16_f32 v33, v34, v35
	v_cvt_pk_bf16_f32 v34, v36, v37
	v_cvt_pk_bf16_f32 v35, v38, v39
	global_store_dwordx4 v[50:51], v[32:35], off
	global_load_dwordx4 v[32:35], v[52:53], off
	s_waitcnt vmcnt(0)
	v_mov_b32_e32 v36, v33
	v_mov_b32_e32 v37, v34
	v_mov_b32_e32 v33, v35
	v_pk_add_f32 v[32:33], v[36:37], v[32:33]
	v_mad_i64_i32 v[34:35], s[0:1], v48, s49, v[150:151]
	v_add_f32_e32 v32, v32, v33
	v_mov_b32_e32 v33, v32
	s_nop 1
	v_permlane16_swap_b32_e32 v32, v33
	v_lshl_add_u64 v[34:35], v[34:35], 0, v[120:121]
	s_waitcnt lgkmcnt(0)
	v_add_f32_e32 v36, v32, v33
	v_mov_b32_e32 v37, v36
	s_nop 1
	v_permlane32_swap_b32_e32 v36, v37
	v_add_u32_e32 v32, 0xb0, v152
	v_ashrrev_i32_e32 v33, 31, v32
	s_waitcnt lgkmcnt(0)
	v_add_f32_e32 v36, v36, v37
	v_fmamk_f32 v36, v36, 0x3a800000, v160
	v_mul_f32_e32 v37, 0x4b800000, v36
	v_cmp_gt_f32_e32 vcc, s52, v36
	s_nop 1
	v_cndmask_b32_e32 v36, v36, v37, vcc
	v_rsq_f32_e32 v38, v36
	v_lshlrev_b64 v[36:37], 6, v[32:33]
	v_lshl_add_u64 v[36:37], v[140:141], 0, v[36:37]
	v_mul_f32_e32 v33, 0x45800000, v38
	v_cndmask_b32_e32 v33, v38, v33, vcc
	v_mul_f32_e32 v39, 0xbfb8aa3b, v33
	v_mul_f32_e32 v20, v20, v39
	v_mul_f32_e32 v21, v21, v39
	v_mul_f32_e32 v22, v22, v39
	v_mul_f32_e32 v23, v23, v39
	v_mul_f32_e32 v16, v16, v39
	v_mul_f32_e32 v17, v17, v39
	v_mul_f32_e32 v18, v18, v39
	v_mul_f32_e32 v19, v19, v39
	v_exp_f32_e32 v20, v20
	v_exp_f32_e32 v21, v21
	v_exp_f32_e32 v22, v22
	v_exp_f32_e32 v23, v23
	v_exp_f32_e32 v16, v16
	v_exp_f32_e32 v17, v17
	v_exp_f32_e32 v18, v18
	v_exp_f32_e32 v19, v19
	v_mul_f32_e32 v38, v33, v33
	v_add_f32_e32 v20, 1.0, v20
	v_add_f32_e32 v21, 1.0, v21
	v_add_f32_e32 v22, 1.0, v22
	v_add_f32_e32 v23, 1.0, v23
	v_add_f32_e32 v33, 1.0, v16
	v_add_f32_e32 v39, 1.0, v17
	v_add_f32_e32 v40, 1.0, v18
	v_add_f32_e32 v41, 1.0, v19
	v_rcp_f32_e32 v16, v20
	v_rcp_f32_e32 v17, v21
	v_rcp_f32_e32 v18, v22
	v_rcp_f32_e32 v19, v23
	v_rcp_f32_e32 v20, v33
	v_rcp_f32_e32 v21, v39
	v_rcp_f32_e32 v22, v40
	v_rcp_f32_e32 v23, v41
	v_pk_mul_f32 v[16:17], v[38:39], v[16:17] op_sel_hi:[0,1]
	v_pk_mul_f32 v[18:19], v[38:39], v[18:19] op_sel_hi:[0,1]
	v_pk_mul_f32 v[20:21], v[38:39], v[20:21] op_sel_hi:[0,1]
	v_pk_mul_f32 v[22:23], v[38:39], v[22:23] op_sel_hi:[0,1]
	v_pk_mul_f32 v[16:17], v[28:29], v[16:17]
	v_pk_mul_f32 v[18:19], v[30:31], v[18:19]
	v_pk_mul_f32 v[20:21], v[24:25], v[20:21]
	v_pk_mul_f32 v[22:23], v[26:27], v[22:23]
	v_cvt_pk_bf16_f32 v16, v16, v17
	v_cvt_pk_bf16_f32 v17, v18, v19
	v_cvt_pk_bf16_f32 v18, v20, v21
	v_cvt_pk_bf16_f32 v19, v22, v23
	global_store_dwordx4 v[34:35], v[16:19], off
	global_load_dwordx4 v[16:19], v[36:37], off
	s_andn2_b64 vcc, exec, s[4:5]
	s_waitcnt vmcnt(0)
	v_mov_b32_e32 v20, v17
	v_mov_b32_e32 v21, v18
	v_mov_b32_e32 v17, v19
	v_pk_add_f32 v[16:17], v[20:21], v[16:17]
	s_nop 0
	v_add_f32_e32 v16, v16, v17
	v_mov_b32_e32 v17, v16
	s_nop 1
	v_permlane16_swap_b32_e32 v16, v17
	s_waitcnt lgkmcnt(0)
	v_add_f32_e32 v16, v16, v17
	v_mov_b32_e32 v17, v16
	s_nop 1
	v_permlane32_swap_b32_e32 v16, v17
	s_waitcnt lgkmcnt(0)
	v_add_f32_e32 v16, v16, v17
	v_fmamk_f32 v16, v16, 0x3a800000, v160
	v_mul_f32_e32 v17, 0x4b800000, v16
	v_cmp_gt_f32_e64 s[0:1], s52, v16
	s_nop 1
	v_cndmask_b32_e64 v16, v16, v17, s[0:1]
	v_rsq_f32_e32 v18, v16
	v_mad_i64_i32 v[16:17], s[24:25], v32, s49, v[150:151]
	v_lshl_add_u64 v[16:17], v[16:17], 0, v[120:121]
	v_mul_f32_e32 v19, 0x45800000, v18
	v_cndmask_b32_e64 v18, v18, v19, s[0:1]
	v_mul_f32_e32 v19, 0xbfb8aa3b, v18
	v_mul_f32_e32 v4, v4, v19
	v_mul_f32_e32 v5, v5, v19
	v_mul_f32_e32 v6, v6, v19
	v_mul_f32_e32 v7, v7, v19
	v_mul_f32_e32 v0, v0, v19
	v_mul_f32_e32 v1, v1, v19
	v_mul_f32_e32 v2, v2, v19
	v_mul_f32_e32 v3, v3, v19
	v_exp_f32_e32 v4, v4
	v_exp_f32_e32 v5, v5
	v_exp_f32_e32 v6, v6
	v_exp_f32_e32 v7, v7
	v_exp_f32_e32 v0, v0
	v_exp_f32_e32 v1, v1
	v_exp_f32_e32 v2, v2
	v_exp_f32_e32 v3, v3
	v_add_f32_e32 v4, 1.0, v4
	v_add_f32_e32 v5, 1.0, v5
	v_add_f32_e32 v6, 1.0, v6
	v_add_f32_e32 v7, 1.0, v7
	v_add_f32_e32 v19, 1.0, v0
	v_add_f32_e32 v20, 1.0, v1
	v_add_f32_e32 v21, 1.0, v2
	v_add_f32_e32 v22, 1.0, v3
	v_rcp_f32_e32 v0, v4
	v_rcp_f32_e32 v1, v5
	v_rcp_f32_e32 v2, v6
	v_rcp_f32_e32 v3, v7
	v_rcp_f32_e32 v4, v19
	v_rcp_f32_e32 v5, v20
	v_rcp_f32_e32 v6, v21
	v_rcp_f32_e32 v7, v22
	v_mul_f32_e32 v18, v18, v18
	v_pk_mul_f32 v[0:1], v[18:19], v[0:1] op_sel_hi:[0,1]
	v_pk_mul_f32 v[2:3], v[18:19], v[2:3] op_sel_hi:[0,1]
	v_pk_mul_f32 v[4:5], v[18:19], v[4:5] op_sel_hi:[0,1]
	v_pk_mul_f32 v[6:7], v[18:19], v[6:7] op_sel_hi:[0,1]
	v_pk_mul_f32 v[0:1], v[12:13], v[0:1]
	v_pk_mul_f32 v[2:3], v[14:15], v[2:3]
	v_pk_mul_f32 v[4:5], v[8:9], v[4:5]
	v_pk_mul_f32 v[6:7], v[10:11], v[6:7]
	v_cvt_pk_bf16_f32 v0, v0, v1
	v_cvt_pk_bf16_f32 v1, v2, v3
	v_cvt_pk_bf16_f32 v2, v4, v5
	v_cvt_pk_bf16_f32 v3, v6, v7
	s_mov_b64 s[0:1], -1
	global_store_dwordx4 v[16:17], v[0:3], off
	s_cbranch_vccnz .LBB0_1231
	s_andn2_b64 vcc, exec, s[8:9]
	s_cbranch_vccnz .LBB0_1230
	s_barrier
	s_branch .LBB0_1230

.LBB0_1323:
	v_lshl_add_u32 v150, s53, 8, v131
	v_ashrrev_i32_e32 v151, 31, v150
	v_lshl_or_b32 v148, s10, 8, v152
	v_lshlrev_b64 v[158:159], 11, v[150:151]
	v_ashrrev_i32_e32 v149, 31, v148
	v_lshl_add_u64 v[158:159], s[14:15], 0, v[158:159]
	v_lshl_add_u64 v[168:169], v[148:149], 1, v[158:159]
	global_load_dwordx4 v[160:163], v[168:169], off
	global_load_dwordx4 v[164:167], v[168:169], off offset:256
	v_and_b32_e32 v158, 64, v156
	v_xor_b32_e32 v157, 16, v156
	v_add_u32_e32 v158, 64, v158
	v_xor_b32_e32 v159, 32, v156
	v_cmp_lt_i32_e32 vcc, v157, v158
	s_lshl_b32 s24, s10, 2
	s_ashr_i32 s25, s24, 31
	v_cndmask_b32_e32 v157, v156, v157, vcc
	v_cmp_lt_i32_e32 vcc, v159, v158
	v_lshlrev_b32_e32 v158, 2, v157
	s_waitcnt vmcnt(0)
	v_lshlrev_b32_e32 v170, 16, v160
	v_and_b32_e32 v171, 0xffff0000, v160
	v_lshlrev_b32_e32 v160, 16, v161
	v_and_b32_e32 v161, 0xffff0000, v161
	v_lshlrev_b32_e32 v172, 16, v162
	v_and_b32_e32 v173, 0xffff0000, v162
	v_lshlrev_b32_e32 v162, 16, v163
	v_and_b32_e32 v163, 0xffff0000, v163
	v_lshlrev_b32_e32 v174, 16, v164
	v_and_b32_e32 v175, 0xffff0000, v164
	v_lshlrev_b32_e32 v164, 16, v165
	v_and_b32_e32 v165, 0xffff0000, v165
	v_lshlrev_b32_e32 v176, 16, v166
	v_and_b32_e32 v177, 0xffff0000, v166
	v_lshlrev_b32_e32 v166, 16, v167
	v_and_b32_e32 v167, 0xffff0000, v167
	v_pk_add_f32 v[124:125], v[124:125], v[170:171]
	v_pk_add_f32 v[126:127], v[126:127], v[160:161]
	v_pk_add_f32 v[120:121], v[120:121], v[172:173]
	v_pk_add_f32 v[122:123], v[122:123], v[162:163]
	v_pk_add_f32 v[116:117], v[116:117], v[174:175]
	v_pk_add_f32 v[118:119], v[118:119], v[164:165]
	v_pk_add_f32 v[160:161], v[112:113], v[176:177]
	v_pk_add_f32 v[162:163], v[114:115], v[166:167]
	v_cndmask_b32_e32 v159, v156, v159, vcc
	v_cvt_pk_bf16_f32 v112, v124, v125
	v_cvt_pk_bf16_f32 v113, v126, v127
	v_pk_mul_f32 v[114:115], v[124:125], v[124:125]
	v_pk_mul_f32 v[124:125], v[126:127], v[126:127]
	v_pk_mul_f32 v[126:127], v[120:121], v[120:121]
	v_pk_mul_f32 v[164:165], v[122:123], v[122:123]
	v_pk_mul_f32 v[166:167], v[116:117], v[116:117]
	v_pk_mul_f32 v[170:171], v[118:119], v[118:119]
	v_pk_mul_f32 v[172:173], v[160:161], v[160:161]
	v_pk_mul_f32 v[174:175], v[162:163], v[162:163]
	v_lshlrev_b32_e32 v157, 2, v159
	v_add_f32_e32 v159, v174, v175
	v_add_f32_e32 v172, v172, v173
	v_add_f32_e32 v170, v170, v171
	v_add_f32_e32 v166, v166, v167
	v_add_f32_e32 v164, v164, v165
	v_add_f32_e32 v126, v126, v127
	v_add_f32_e32 v124, v124, v125
	v_add_f32_e32 v114, v114, v115
	v_add_f32_e32 v115, v172, v159
	v_add_f32_e32 v125, v166, v170
	v_add_f32_e32 v126, v126, v164
	v_add_f32_e32 v114, v114, v124
	v_add_f32_e32 v115, v125, v115
	v_add_f32_e32 v114, v114, v126
	v_add_f32_e32 v124, v114, v115
	v_mov_b32_e32 v125, v124
	s_nop 1
	v_permlane16_swap_b32_e32 v124, v125
	v_cvt_pk_bf16_f32 v114, v120, v121
	v_cvt_pk_bf16_f32 v115, v122, v123
	global_store_dwordx4 v[168:169], v[112:115], off
	s_waitcnt lgkmcnt(0)
	s_nop 0
	v_add_f32_e32 v112, v124, v125
	v_mov_b32_e32 v113, v112
	s_nop 1
	v_permlane32_swap_b32_e32 v112, v113
	v_cvt_pk_bf16_f32 v114, v116, v117
	v_cvt_pk_bf16_f32 v115, v118, v119
	v_cvt_pk_bf16_f32 v116, v160, v161
	v_cvt_pk_bf16_f32 v117, v162, v163
	global_store_dwordx4 v[168:169], v[114:117], off offset:256
	s_and_saveexec_b64 s[26:27], s[4:5]
	s_cbranch_execz .LBB0_1325
	v_lshlrev_b64 v[114:115], 6, v[150:151]
	v_lshl_add_u64 v[114:115], s[16:17], 0, v[114:115]
	v_lshl_add_u64 v[114:115], s[24:25], 2, v[114:115]
	s_lshl_b32 s10, s40, 2
	v_lshl_add_u64 v[114:115], v[114:115], 0, s[10:11]
	s_waitcnt lgkmcnt(0)
	v_add_f32_e32 v112, v112, v113
	global_store_dword v[114:115], v112, off
.LBB0_1325:
	s_or_b64 exec, exec, s[26:27]
	v_or_b32_e32 v112, 16, v150
	s_waitcnt lgkmcnt(0)
	v_ashrrev_i32_e32 v113, 31, v112
	v_lshlrev_b64 v[114:115], 11, v[112:113]
	v_lshl_add_u64 v[114:115], s[14:15], 0, v[114:115]
	v_lshl_add_u64 v[122:123], v[148:149], 1, v[114:115]
	global_load_dwordx4 v[114:117], v[122:123], off
	global_load_dwordx4 v[118:121], v[122:123], off offset:256
	s_waitcnt vmcnt(1)
	v_lshlrev_b32_e32 v124, 16, v114
	v_and_b32_e32 v125, 0xffff0000, v114
	v_lshlrev_b32_e32 v114, 16, v115
	v_and_b32_e32 v115, 0xffff0000, v115
	v_lshlrev_b32_e32 v126, 16, v116
	v_and_b32_e32 v127, 0xffff0000, v116
	v_lshlrev_b32_e32 v116, 16, v117
	v_and_b32_e32 v117, 0xffff0000, v117
	s_waitcnt vmcnt(0)
	v_lshlrev_b32_e32 v160, 16, v118
	v_and_b32_e32 v161, 0xffff0000, v118
	v_lshlrev_b32_e32 v118, 16, v119
	v_and_b32_e32 v119, 0xffff0000, v119
	v_lshlrev_b32_e32 v162, 16, v120
	v_and_b32_e32 v163, 0xffff0000, v120
	v_lshlrev_b32_e32 v120, 16, v121
	v_and_b32_e32 v121, 0xffff0000, v121
	v_pk_add_f32 v[108:109], v[108:109], v[124:125]
	v_pk_add_f32 v[110:111], v[110:111], v[114:115]
	v_pk_add_f32 v[104:105], v[104:105], v[126:127]
	v_pk_add_f32 v[106:107], v[106:107], v[116:117]
	v_pk_add_f32 v[100:101], v[100:101], v[160:161]
	v_pk_add_f32 v[102:103], v[102:103], v[118:119]
	v_pk_add_f32 v[114:115], v[96:97], v[162:163]
	v_pk_add_f32 v[116:117], v[98:99], v[120:121]
	v_cvt_pk_bf16_f32 v96, v108, v109
	v_cvt_pk_bf16_f32 v97, v110, v111
	v_pk_mul_f32 v[98:99], v[108:109], v[108:109]
	v_pk_mul_f32 v[108:109], v[110:111], v[110:111]
	v_pk_mul_f32 v[110:111], v[104:105], v[104:105]
	v_pk_mul_f32 v[118:119], v[106:107], v[106:107]
	v_pk_mul_f32 v[120:121], v[100:101], v[100:101]
	v_pk_mul_f32 v[124:125], v[102:103], v[102:103]
	v_pk_mul_f32 v[126:127], v[114:115], v[114:115]
	v_pk_mul_f32 v[160:161], v[116:117], v[116:117]
	v_add_f32_e32 v126, v126, v127
	v_add_f32_e32 v151, v160, v161
	v_add_f32_e32 v124, v124, v125
	v_add_f32_e32 v120, v120, v121
	v_add_f32_e32 v118, v118, v119
	v_add_f32_e32 v110, v110, v111
	v_add_f32_e32 v108, v108, v109
	v_add_f32_e32 v98, v98, v99
	v_add_f32_e32 v99, v126, v151
	v_add_f32_e32 v109, v120, v124
	v_add_f32_e32 v110, v110, v118
	v_add_f32_e32 v98, v98, v108
	v_add_f32_e32 v99, v109, v99
	v_add_f32_e32 v98, v98, v110
	v_add_f32_e32 v108, v98, v99
	v_mov_b32_e32 v109, v108
	s_nop 1
	v_permlane16_swap_b32_e32 v108, v109
	v_cvt_pk_bf16_f32 v98, v104, v105
	v_cvt_pk_bf16_f32 v99, v106, v107
	global_store_dwordx4 v[122:123], v[96:99], off
	s_waitcnt lgkmcnt(0)
	s_nop 0
	v_add_f32_e32 v96, v108, v109
	v_mov_b32_e32 v97, v96
	s_nop 1
	v_permlane32_swap_b32_e32 v96, v97
	v_cvt_pk_bf16_f32 v98, v100, v101
	v_cvt_pk_bf16_f32 v99, v102, v103
	v_cvt_pk_bf16_f32 v100, v114, v115
	v_cvt_pk_bf16_f32 v101, v116, v117
	global_store_dwordx4 v[122:123], v[98:101], off offset:256
	s_and_saveexec_b64 s[26:27], s[4:5]
	s_cbranch_execz .LBB0_1327
	v_lshlrev_b64 v[98:99], 6, v[112:113]
	v_lshl_add_u64 v[98:99], s[16:17], 0, v[98:99]
	v_lshl_add_u64 v[98:99], s[24:25], 2, v[98:99]
	s_lshl_b32 s10, s40, 2
	v_lshl_add_u64 v[98:99], v[98:99], 0, s[10:11]
	s_waitcnt lgkmcnt(0)
	v_add_f32_e32 v96, v96, v97
	global_store_dword v[98:99], v96, off
